# gates GEMM: the gate-c column tiles (third round) computed during MIX2 by the attention workgroups into the dead second half of the UC region (ws+212MiB); gates phase keeps 2 rounds; branch GEMM epilo
# speedup vs baseline: 1.0335x; 1.0105x over previous
.LBB0_31:
	s_or_b64 exec, exec, s[2:3]
	s_load_dwordx16 s[36:51], s[0:1], 0x40
	s_ashr_i32 s73, s72, 31
	s_lshr_b32 s0, s73, 29
	s_add_i32 s2, s72, s0
	s_and_b32 s0, s2, -8
	s_waitcnt lgkmcnt(0)
	v_writelane_b32 v248, s36, 24
	s_sub_i32 s0, s72, s0
	s_lshl_b32 s1, s0, 6
	v_writelane_b32 v248, s37, 25
	v_writelane_b32 v248, s38, 26
	s_cmp_lt_i32 s0, 0
	s_mul_i32 s3, s0, 0x41
	v_writelane_b32 v248, s39, 27
	s_cselect_b32 s10, s3, s1
	s_lshl_b32 s1, s0, 8
	v_writelane_b32 v248, s40, 28
	s_cmp_lt_i32 s0, 0
	s_mul_i32 s3, s0, 0x101
	v_writelane_b32 v248, s41, 29
	s_cselect_b32 s11, s3, s1
	s_lshl_b32 s3, s0, 5
	v_writelane_b32 v248, s42, 30
	s_cmp_lt_i32 s0, 0
	s_movk_i32 s1, 0xb1
	v_writelane_b32 v248, s43, 31
	s_cselect_b32 s4, s1, 0xb0
	s_movk_i32 s1, 0x61
	s_mul_i32 s12, s0, 33
	v_writelane_b32 v248, s44, 32
	s_cselect_b32 s1, s1, 0x60
	s_cselect_b32 s13, s12, s3
	s_cmpk_lt_i32 s72, 0x580
	v_writelane_b32 v248, s45, 33
	s_cselect_b64 s[14:15], -1, 0
	s_mul_i32 s3, s4, s0
	s_ashr_i32 s12, s2, 3
	v_writelane_b32 v248, s46, 34
	s_add_i32 s3, s3, s12
	v_writelane_b32 v248, s47, 35
	s_mul_hi_i32 s2, s3, 0x2e8ba2e9
	v_writelane_b32 v248, s48, 36
	s_lshr_b32 s4, s2, 31
	s_ashr_i32 s2, s2, 5
	v_writelane_b32 v248, s49, 37
	s_add_i32 s2, s2, s4
	v_writelane_b32 v248, s50, 38
	s_mul_i32 s4, s2, 0xb0
	v_writelane_b32 v248, s51, 39
	s_sub_i32 s3, s3, s4
	v_writelane_b32 v248, s14, 40
	s_bfe_u32 s4, s3, 0x3001c
	s_lshl_b32 s2, s2, 3
	v_writelane_b32 v248, s15, 41
	s_add_i32 s14, s3, s4
	s_sext_i32_i16 s15, s14
	s_and_b32 s14, s14, 0xfff8
	s_sub_i32 s3, s3, s14
	s_sext_i32_i16 s3, s3
	s_mul_i32 s5, s75, s74
	s_lshr_b32 s4, s15, 3
	s_add_i32 s24, s2, s3
	s_ashr_i32 s2, s15, 3
	s_ashr_i32 s75, s74, 31
	s_add_u32 s78, s6, 0x4200
	s_addc_u32 s79, s7, 0
	s_add_u32 s80, s6, 0x4400
	s_addc_u32 s81, s7, 0
	s_add_u32 s82, s6, 0x4500
	s_addc_u32 s83, s7, 0
	s_add_u32 s84, s6, 0x4600
	s_addc_u32 s85, s7, 0
	s_add_u32 s86, s6, 0x4700
	s_addc_u32 s87, s7, 0
	s_add_u32 s88, s6, 0x4800
	s_addc_u32 s89, s7, 0
	s_add_u32 s90, s6, 0x4900
	s_addc_u32 s91, s7, 0
	s_add_u32 s60, s6, 0x4a00
	s_addc_u32 s61, s7, 0
	s_add_u32 s56, s6, 0x4b00
	s_addc_u32 s57, s7, 0
	s_add_u32 s58, s6, 0x4c00
	s_addc_u32 s59, s7, 0
	v_writelane_b32 v248, s2, 42
	s_add_u32 s2, s6, 0x4d00
	s_addc_u32 s3, s7, 0
	v_writelane_b32 v248, s2, 43
	s_mov_b32 s53, 0
	s_mov_b32 s29, s53
	v_writelane_b32 v248, s3, 44
	s_add_u32 s2, s6, 0x4e00
	s_addc_u32 s3, s7, 0
	v_writelane_b32 v248, s2, 45
	v_lshrrev_b32_e32 v1, 20, v0
	v_lshrrev_b32_e32 v0, 10, v0
	v_writelane_b32 v248, s3, 46
	s_add_u32 s2, s6, 0x4f00
	s_addc_u32 s3, s7, 0
	v_writelane_b32 v248, s2, 47
	v_or_b32_e32 v0, v0, v1
	v_mov_b32_e32 v208, 0x358637bd
	v_writelane_b32 v248, s3, 48
	s_add_u32 s2, s6, 0x5000
	s_addc_u32 s3, s7, 0
	v_writelane_b32 v248, s2, 49
	v_mov_b32_e32 v209, 1
	v_mov_b32_e32 v210, 0x11500000
	v_writelane_b32 v248, s3, 50
	s_add_u32 s2, s6, 0x5100
	s_addc_u32 s3, s7, 0
	v_writelane_b32 v248, s2, 51
	v_mbcnt_hi_u32_b32 v211, -1, v207
	v_mov_b32_e32 v4, 0
	v_writelane_b32 v248, s3, 52
	s_add_u32 s2, s6, 0x5200
	s_addc_u32 s3, s7, 0
	v_writelane_b32 v248, s2, 53
	v_mov_b32_e32 v212, 0x3e38aa3b
	v_mov_b32_e32 v213, 0x41b17218
	v_writelane_b32 v248, s3, 54
	s_add_u32 s2, s6, 0x5300
	s_addc_u32 s3, s7, 0
	v_writelane_b32 v248, s2, 55
	s_cmp_eq_u32 s23, 15
	v_mov_b64_e32 v[152:153], 0x200
	v_writelane_b32 v248, s3, 56
	s_cselect_b64 s[2:3], -1, 0
	v_writelane_b32 v248, s2, 57
	s_cmp_eq_u32 s23, 14
	v_mov_b64_e32 v[154:155], 0x1ff
	v_writelane_b32 v248, s3, 58
	s_cselect_b64 s[2:3], -1, 0
	v_writelane_b32 v248, s2, 59
	s_cmp_eq_u32 s23, 13
	v_mov_b64_e32 v[156:157], 0x100
	v_writelane_b32 v248, s3, 60
	s_cselect_b64 s[2:3], -1, 0
	v_writelane_b32 v248, s2, 61
	s_cmp_eq_u32 s23, 12
	v_mov_b64_e32 v[158:159], 0xff
	v_writelane_b32 v248, s3, 62
	s_cselect_b64 s[2:3], -1, 0
	v_writelane_b32 v248, s2, 63
	s_cmp_eq_u32 s23, 11
	v_readlane_b32 s36, v248, 2
	v_writelane_b32 v249, s3, 0
	s_cselect_b64 s[2:3], -1, 0
	v_writelane_b32 v249, s2, 1
	s_cmp_eq_u32 s23, 10
	v_readlane_b32 s42, v248, 8
	v_writelane_b32 v249, s3, 2
	s_cselect_b64 s[2:3], -1, 0
	v_writelane_b32 v249, s2, 3
	s_cmp_eq_u32 s23, 9
	v_readlane_b32 s43, v248, 9
	v_writelane_b32 v249, s3, 4
	s_cselect_b64 s[2:3], -1, 0
	v_writelane_b32 v249, s2, 5
	s_cmp_eq_u32 s23, 8
	v_readlane_b32 s46, v248, 12
	v_writelane_b32 v249, s3, 6
	s_cselect_b64 s[2:3], -1, 0
	v_writelane_b32 v249, s2, 7
	s_cmp_eq_u32 s23, 7
	v_readlane_b32 s47, v248, 13
	v_writelane_b32 v249, s3, 8
	s_cselect_b64 s[2:3], -1, 0
	v_writelane_b32 v249, s2, 9
	s_cmp_eq_u32 s23, 6
	v_readlane_b32 s48, v248, 14
	v_writelane_b32 v249, s3, 10
	s_cselect_b64 s[2:3], -1, 0
	v_writelane_b32 v249, s2, 11
	s_cmp_eq_u32 s23, 5
	v_readlane_b32 s49, v248, 15
	v_writelane_b32 v249, s3, 12
	s_cselect_b64 s[2:3], -1, 0
	v_writelane_b32 v249, s2, 13
	s_cmp_eq_u32 s23, 4
	v_readlane_b32 s51, v248, 17
	v_writelane_b32 v249, s3, 14
	s_cselect_b64 s[2:3], -1, 0
	v_writelane_b32 v249, s2, 15
	s_cmp_eq_u32 s23, 3
	v_mov_b64_e32 v[166:167], 0x1ff
	v_writelane_b32 v249, s3, 16
	s_cselect_b64 s[2:3], -1, 0
	v_writelane_b32 v249, s2, 17
	s_cmp_eq_u32 s23, 2
	s_mov_b32 s95, 0x10000
	v_writelane_b32 v249, s3, 18
	s_cselect_b64 s[2:3], -1, 0
	v_writelane_b32 v249, s2, 19
	s_cmp_eq_u32 s23, 1
	s_movk_i32 s62, 0x2000
	v_writelane_b32 v249, s3, 20
	s_cselect_b64 s[2:3], -1, 0
	v_writelane_b32 v249, s2, 21
	s_cmp_eq_u32 s23, 0
	s_mov_b32 s51, 0x800000
	v_writelane_b32 v249, s3, 22
	s_cselect_b64 s[2:3], -1, 0
	v_writelane_b32 v249, s2, 23
	s_movk_i32 s93, 0x90
	s_movk_i32 s54, 0x110
	v_writelane_b32 v249, s3, 24
	s_lshl_b32 s2, s23, 8
	s_add_u32 s2, s8, s2
	s_addc_u32 s3, s9, 0
	s_add_u32 s8, s2, 0x1400
	s_addc_u32 s9, s3, 0
	v_writelane_b32 v249, s8, 25
	s_add_u32 s2, s2, 0x2400
	s_addc_u32 s3, s3, 0
	v_writelane_b32 v249, s9, 26
	v_writelane_b32 v249, s2, 27
	s_mul_i32 s9, s1, s0
	s_movk_i32 s55, 0xff00
	v_writelane_b32 v249, s3, 28
	s_add_u32 s2, s6, 0x7400
	s_addc_u32 s3, s7, 0
	v_writelane_b32 v249, s2, 29
	s_mov_b64 s[96:97], 0x80
	s_mov_b64 s[48:49], 0x4000
	v_writelane_b32 v249, s3, 30
	s_add_u32 s2, s6, 0x7500
	s_addc_u32 s3, s7, 0
	v_writelane_b32 v249, s2, 31
	s_cmpk_lt_i32 s72, 0x800
	s_mov_b64 s[46:47], 0x8000
	v_writelane_b32 v249, s3, 32
	s_cselect_b64 s[2:3], -1, 0
	v_writelane_b32 v249, s2, 33
	s_cmp_gt_i32 s72, 63
	v_readlane_b32 s37, v248, 3
	v_writelane_b32 v249, s3, 34
	s_cselect_b64 s[2:3], -1, 0
	s_cmpk_lt_i32 s74, 0x41
	s_cselect_b64 s[6:7], -1, 0
	s_or_b64 s[2:3], s[2:3], s[6:7]
	v_writelane_b32 v249, s2, 35
	s_sub_i32 s8, s72, 64
	s_sub_i32 s0, s74, 64
	v_writelane_b32 v249, s3, 36
	s_cmpk_lt_i32 s72, 0x1040
	v_writelane_b32 v249, s0, 37
	s_cselect_b64 s[0:1], -1, 0
	v_writelane_b32 v249, s0, 38
	s_ashr_i32 s26, s8, 10
	v_readlane_b32 s38, v248, 4
	v_writelane_b32 v249, s1, 39
	s_lshr_b32 s0, s8, 2
	s_and_b32 s0, s0, 64
	s_or_b32 s16, s0, 0x800
	s_or_b32 s17, s0, 0x880
	s_bfe_u32 s0, s8, 0x30006
	s_lshl_b32 s18, s0, 6
	s_or_b32 s19, s18, 0x600
	s_or_b32 s20, s18, 0x200
	s_or_b32 s21, s18, 0x400
	s_cmp_eq_u32 s26, 2
	v_writelane_b32 v249, s0, 40
	s_cselect_b32 s0, 4, 0
	s_cmp_lg_u32 s26, 1
	s_cselect_b32 s1, s0, 2
	s_and_b32 s0, s72, 63
	s_lshr_b32 s14, s0, s1
	s_lshl_b32 s0, -1, s1
	s_andn2_b32 s15, s72, s0
	s_lshl_b32 s0, s72, 7
	v_writelane_b32 v249, s1, 41
	s_and_b32 s1, s0, 0x380
	v_writelane_b32 v249, s1, 42
	v_writelane_b32 v249, s8, 43
	s_bfe_u32 s8, s8, 0x10009
	v_writelane_b32 v249, s8, 44
	s_ashr_i32 s6, s72, 5
	s_lshl_b32 s8, s8, 13
	v_writelane_b32 v249, s14, 45
	s_lshl_b32 s14, s14, 7
	s_lshl_b32 s0, s6, 10
	v_writelane_b32 v249, s14, 46
	s_or_b32 s28, s15, s8
	s_bfe_u32 s8, s72, 0x20003
	s_or_b32 s0, s0, s1
	v_writelane_b32 v249, s15, 47
	s_lshl_b32 s14, s8, 11
	s_ashr_i32 s1, s0, 31
	v_writelane_b32 v249, s14, 48
	s_lshl_b32 s14, s8, 5
	s_or_b32 s2, s0, 1
	v_writelane_b32 v249, s14, 49
	s_lshl_b64 s[14:15], s[0:1], 13
	s_ashr_i32 s3, s2, 31
	v_writelane_b32 v249, s14, 50
	s_ashr_i32 s7, s6, 31
	v_readlane_b32 s39, v248, 5
	v_writelane_b32 v249, s15, 51
	s_lshl_b64 s[14:15], s[2:3], 13
	v_writelane_b32 v249, s14, 52
	v_readlane_b32 s40, v248, 6
	v_readlane_b32 s41, v248, 7
	v_writelane_b32 v249, s15, 53
	s_lshl_b64 s[14:15], s[6:7], 13
	v_writelane_b32 v249, s14, 54
	s_cmpk_lt_i32 s72, 0x300
	v_readlane_b32 s44, v248, 10
	v_writelane_b32 v249, s15, 55
	s_cselect_b64 s[14:15], -1, 0
	v_writelane_b32 v249, s14, 56
	s_add_i32 s9, s9, s12
	v_readlane_b32 s45, v248, 11
	v_writelane_b32 v249, s15, 57
	s_mul_hi_i32 s14, s9, 0x2aaaaaab
	s_lshr_b32 s15, s14, 31
	s_ashr_i32 s14, s14, 4
	s_add_i32 s14, s14, s15
	s_mul_i32 s15, s14, 0x60
	s_sub_i32 s9, s9, s15
	s_bfe_i32 s15, s9, 0x80000
	s_bfe_u32 s15, s15, 0x3000c
	s_add_i32 s15, s9, s15
	s_and_b32 s23, s15, 0xf8
	s_sub_i32 s9, s9, s23
	s_bfe_i32 s15, s15, 0x80000
	s_lshl_b32 s14, s14, 3
	s_sext_i32_i16 s15, s15
	s_sext_i32_i8 s9, s9
	s_add_i32 s30, s14, s9
	s_lshr_b32 s14, s15, 3
	s_ashr_i32 s9, s15, 3
	s_bfe_i64 s[14:15], s[14:15], 0x100000
	v_writelane_b32 v249, s9, 58
	s_lshl_b64 s[14:15], s[14:15], 19
	v_writelane_b32 v249, s14, 59
	s_ashr_i32 s31, s30, 31
	v_readlane_b32 s50, v248, 16
	v_writelane_b32 v249, s15, 60
	s_mov_b32 s14, s30
	v_writelane_b32 v249, s14, 61
	s_nop 1
	v_writelane_b32 v249, s15, 62
	s_lshl_b64 s[14:15], s[30:31], 19
	v_writelane_b32 v249, s14, 63
	s_nop 1
	v_writelane_b32 v250, s15, 0
	s_lshl_b64 s[14:15], s[72:73], 18
	v_writelane_b32 v250, s14, 1
	s_cmpk_lt_i32 s72, 0x100
	s_nop 0
	v_writelane_b32 v250, s15, 2
	s_cselect_b64 s[14:15], -1, 0
	v_writelane_b32 v250, s14, 3
	s_cmpk_lt_i32 s72, 0x200
	s_nop 0
	v_writelane_b32 v250, s15, 4
	s_cselect_b64 s[14:15], -1, 0
	v_writelane_b32 v250, s14, 5
	s_ashr_i32 s25, s24, 31
	s_nop 0
	v_writelane_b32 v250, s15, 6
	s_bfe_i64 s[14:15], s[4:5], 0x100000
	s_lshl_b64 s[14:15], s[14:15], 19
	v_writelane_b32 v250, s14, 7
	s_mov_b32 s4, s24
	s_nop 0
	v_writelane_b32 v250, s15, 8
	v_writelane_b32 v250, s4, 9
	s_lshl_b64 s[14:15], s[24:25], 19
	s_cmp_lt_i32 s26, 3
	v_writelane_b32 v250, s5, 10
	v_writelane_b32 v250, s14, 11
	s_cselect_b32 s9, s20, s16
	s_cselect_b32 s4, s18, s19
	v_writelane_b32 v250, s15, 12
	v_writelane_b32 v250, s26, 13
	v_writelane_b32 v250, s9, 14
	s_cselect_b32 s9, s21, s17
	v_writelane_b32 v250, s9, 15
	s_add_i32 s9, s13, s12
	s_ashr_i32 s13, s9, 31
	s_lshr_b32 s13, s13, 27
	s_add_i32 s13, s9, s13
	s_and_b32 s14, s13, 0xffe0
	s_sub_i32 s9, s9, s14
	s_bfe_i32 s14, s9, 0x80000
	s_bfe_u32 s14, s14, 0x3000c
	s_add_i32 s14, s9, s14
	s_and_b32 s15, s14, 0xf8
	s_add_i32 s11, s11, s12
	s_sub_i32 s9, s9, s15
	s_ashr_i32 s15, s11, 31
	s_lshr_b32 s15, s15, 25
	s_add_i32 s15, s11, s15
	s_and_b32 s16, s15, 0xff80
	s_sub_i32 s11, s11, s16
	s_bfe_i32 s16, s11, 0x80000
	s_bfe_u32 s16, s16, 0x3000c
	s_add_i32 s16, s11, s16
	s_and_b32 s17, s16, 0xf8
	s_add_i32 s10, s10, s12
	s_sub_i32 s17, s11, s17
	s_ashr_i32 s11, s10, 31
	s_lshr_b32 s11, s11, 27
	s_add_i32 s12, s10, s11
	s_and_b32 s11, s12, 0xffe0
	s_sub_i32 s10, s10, s11
	s_bfe_i32 s11, s10, 0x80000
	s_bfe_u32 s11, s11, 0x3000c
	s_add_i32 s18, s10, s11
	s_and_b32 s11, s18, 0xf8
	s_sub_i32 s19, s10, s11
	s_ashr_i32 s10, s13, 5
	s_bfe_i32 s11, s14, 0x80000
	s_lshl_b32 s10, s10, 3
	s_sext_i32_i16 s11, s11
	s_sext_i32_i8 s9, s9
	s_add_i32 s20, s10, s9
	s_lshr_b32 s10, s11, 3
	s_ashr_i32 s9, s11, 3
	s_bfe_i64 s[10:11], s[10:11], 0x100000
	v_writelane_b32 v250, s9, 16
	s_lshl_b64 s[24:25], s[10:11], 18
	v_writelane_b32 v250, s24, 17
	s_lshl_b64 s[10:11], s[10:11], 19
	s_ashr_i32 s9, s15, 7
	v_writelane_b32 v250, s25, 18
	v_writelane_b32 v250, s10, 19
	s_lshl_b32 s9, s9, 3
	s_ashr_i32 s21, s20, 31
	v_writelane_b32 v250, s11, 20
	s_bfe_i32 s10, s16, 0x80000
	s_sext_i32_i16 s10, s10
	s_sext_i32_i8 s11, s17
	s_add_i32 s14, s9, s11
	s_ashr_i32 s9, s10, 3
	s_lshr_b32 s10, s10, 3
	s_bfe_i64 s[10:11], s[10:11], 0x100000
	v_writelane_b32 v250, s9, 21
	s_lshl_b64 s[10:11], s[10:11], 19
	v_writelane_b32 v250, s10, 22
	s_ashr_i32 s9, s12, 5
	s_lshl_b32 s9, s9, 3
	v_writelane_b32 v250, s11, 23
	s_bfe_i32 s10, s18, 0x80000
	s_sext_i32_i16 s10, s10
	s_sext_i32_i8 s11, s19
	s_add_i32 s12, s9, s11
	s_ashr_i32 s9, s10, 3
	s_lshr_b32 s10, s10, 3
	s_bfe_i64 s[10:11], s[10:11], 0x100000
	v_writelane_b32 v250, s9, 24
	s_lshl_b64 s[10:11], s[10:11], 21
	v_writelane_b32 v250, s10, 25
	v_readlane_b32 s9, v248, 20
	s_addk_i32 s9, 0xe970
	v_writelane_b32 v250, s11, 26
	v_writelane_b32 v250, s9, 27
	s_lshl_b32 s9, s74, 8
	v_writelane_b32 v250, s9, 28
	s_lshl_b64 s[10:11], s[20:21], 18
	v_writelane_b32 v250, s10, 29
	s_ashr_i32 s15, s14, 31
	s_ashr_i32 s13, s12, 31
	v_writelane_b32 v250, s11, 30
	s_mov_b32 s10, s20
	v_writelane_b32 v250, s10, 31
	s_nop 1
	v_writelane_b32 v250, s11, 32
	s_lshl_b64 s[10:11], s[20:21], 19
	v_writelane_b32 v250, s10, 33
	s_nop 1
	v_writelane_b32 v250, s11, 34
	s_mov_b32 s10, s14
	v_writelane_b32 v250, s10, 35
	s_nop 1
	v_writelane_b32 v250, s11, 36
	s_lshl_b64 s[10:11], s[14:15], 19
	v_writelane_b32 v250, s10, 37
	s_nop 1
	v_writelane_b32 v250, s11, 38
	s_mov_b32 s10, s12
	v_writelane_b32 v250, s10, 39
	s_nop 1
	v_writelane_b32 v250, s11, 40
	s_lshl_b64 s[10:11], s[12:13], 21
	v_writelane_b32 v250, s10, 41
	s_nop 1
	v_writelane_b32 v250, s11, 42
	s_add_u32 s10, s42, 0x5440
	s_addc_u32 s11, s43, 0
	v_writelane_b32 v250, s10, 43
	s_ashr_i32 s77, s76, 31
	s_lshl_b32 s9, s72, 6
	v_writelane_b32 v250, s11, 44
	s_lshl_b32 s63, s74, 6
	s_lshl_b64 s[24:25], s[76:77], 4
	s_lshl_b64 s[10:11], s[72:73], 2
	s_add_u32 s10, s10, 0x11500000
	v_writelane_b32 v250, s9, 45
	s_addc_u32 s11, s11, 0
	v_writelane_b32 v250, s10, 46
	s_mul_i32 s77, s5, s22
	s_movk_i32 s9, 0x3ff
	v_writelane_b32 v250, s11, 47
	s_lshl_b64 s[10:11], s[74:75], 2
	v_writelane_b32 v250, s10, 48
	v_and_or_b32 v1, v0, s9, v206
	v_mov_b32_e32 v0, 0
	v_writelane_b32 v250, s11, 49
	s_lshl_b64 s[10:11], s[72:73], 13
	s_add_u32 s10, s10, 0x19800000
	s_addc_u32 s11, s11, 0
	v_writelane_b32 v250, s10, 50
	s_and_b32 s5, s72, 7
	s_lshl_b32 s5, s5, 8
	v_writelane_b32 v250, s11, 51
	s_lshl_b32 s8, s8, 6
	v_writelane_b32 v250, s28, 52
	s_or_b32 s5, s5, s8
	s_lshl_b64 s[6:7], s[6:7], 24
	v_writelane_b32 v250, s29, 53
	v_writelane_b32 v250, s5, 54
	s_or_b32 s6, s6, s5
	v_writelane_b32 v250, s6, 55
	s_lshl_b32 s92, s74, 12
	v_mov_b32_e32 v5, v0
	v_writelane_b32 v250, s7, 56
	s_lshl_b64 s[6:7], s[0:1], 14
	v_writelane_b32 v250, s6, 57
	v_mov_b32_e32 v6, v0
	v_mov_b32_e32 v7, v0
	v_writelane_b32 v250, s7, 58
	s_lshl_b64 s[6:7], s[0:1], 2
	v_writelane_b32 v250, s6, 59
	s_lshl_b64 s[0:1], s[0:1], 2
	s_nop 0
	v_writelane_b32 v250, s7, 60
	v_writelane_b32 v250, s0, 61
	s_mov_b32 s6, s53
	s_nop 0
	v_writelane_b32 v250, s1, 62
	s_lshl_b64 s[0:1], s[2:3], 2
	v_writelane_b32 v250, s0, 63
	s_nop 1
	v_writelane_b32 v251, s1, 0
	s_lshl_b32 s0, s72, 12
	v_writelane_b32 v251, s0, 1
	s_add_i32 s0, 0, 0x20c40
	v_writelane_b32 v251, s0, 2
	s_add_i32 s0, 0, 0x20c44
	v_writelane_b32 v251, s0, 3
	s_add_i32 s0, 0, 0x11000
	v_writelane_b32 v251, s0, 4
	s_add_i32 s0, 0, 0x1c400
	v_writelane_b32 v251, s0, 5
	s_add_i32 s0, 0, 0x1cc00
	v_writelane_b32 v251, s0, 6
	s_add_i32 s0, 0, 0x13400
	v_writelane_b32 v251, s0, 7
	s_lshl_b32 s0, s4, 1
	v_writelane_b32 v251, s0, 8
	s_mov_b64 s[4:5], -1
	s_nop 0
	v_writelane_b32 v251, s1, 9
	v_cmp_eq_u32_e64 s[0:1], 0, v1
	s_nop 1
	v_writelane_b32 v251, s0, 10
	s_nop 1
	v_writelane_b32 v251, s1, 11
	s_lshl_b64 s[0:1], s[74:75], 13
	v_writelane_b32 v251, s0, 12
	s_nop 1
	v_writelane_b32 v251, s1, 13
	s_lshl_b64 s[0:1], s[72:73], 14
	v_writelane_b32 v251, s0, 14
	s_nop 1
	v_writelane_b32 v251, s1, 15
	s_lshl_b64 s[0:1], s[74:75], 14
	v_writelane_b32 v251, s0, 16
	s_nop 1
	v_writelane_b32 v251, s1, 17
	v_writelane_b32 v251, s60, 18
	s_nop 1
	v_writelane_b32 v251, s61, 19
	v_writelane_b32 v251, s56, 20
	s_nop 1
	v_writelane_b32 v251, s57, 21
	v_writelane_b32 v251, s58, 22
	s_nop 1
	v_writelane_b32 v251, s59, 23
	v_writelane_b32 v251, s24, 24
	s_nop 1
	v_writelane_b32 v251, s25, 25
	v_writelane_b32 v251, s64, 26
	s_nop 1
	v_writelane_b32 v251, s65, 27
	v_writelane_b32 v251, s66, 28
	v_writelane_b32 v251, s67, 29
	v_writelane_b32 v251, s68, 30
	v_writelane_b32 v251, s69, 31
	v_writelane_b32 v251, s70, 32
	v_writelane_b32 v251, s71, 33
	v_writelane_b32 v251, s74, 34
	s_nop 1
	v_writelane_b32 v251, s75, 35
	v_writelane_b32 v251, s86, 36
	s_nop 1
	v_writelane_b32 v251, s87, 37
	v_writelane_b32 v251, s88, 38
	s_nop 1
	v_writelane_b32 v251, s89, 39
	v_writelane_b32 v251, s90, 40
	s_nop 1
	v_writelane_b32 v251, s91, 41
	v_writelane_b32 v251, s84, 42
	s_nop 1
	v_writelane_b32 v251, s85, 43
	v_writelane_b32 v251, s82, 44
	s_nop 1
	v_writelane_b32 v251, s83, 45
	v_writelane_b32 v251, s80, 46
	s_nop 1
	v_writelane_b32 v251, s81, 47
	v_writelane_b32 v251, s92, 48
	s_branch .LBB0_34

.Lg1t_skip:
	s_sub_u32 s0, s72, 64
	s_sub_u32 s2, s0, 128
	s_lshl_b32 s2, s2, 1
	s_add_u32 s2, s2, 128
	s_cmp_lt_u32 s0, 128
	s_cselect_b32 s1, 1, 2
	s_cselect_b32 s2, s0, s2
	v_readlane_b32 s3, v249, 58
	v_readlane_b32 s4, v249, 59
	v_readlane_b32 s5, v249, 60
	v_readlane_b32 s6, v249, 61
	v_readlane_b32 s7, v249, 63
	v_readlane_b32 s26, v250, 0
	s_nop 3
	v_writelane_b32 v255, s1, 19
	v_writelane_b32 v255, s2, 20
	v_writelane_b32 v255, s3, 21
	v_writelane_b32 v255, s4, 22
	v_writelane_b32 v255, s5, 23
	v_writelane_b32 v255, s6, 24
	v_writelane_b32 v255, s7, 25
	v_writelane_b32 v255, s26, 26
.Lgt_loop:
	v_readlane_b32 s2, v255, 20
	s_nop 3
	s_lshr_b32 s1, s2, 6
	s_add_u32 s1, s1, 8
	s_and_b32 s3, s2, 7
	s_lshl_b32 s3, s3, 3
	s_bfe_u32 s4, s2, 0x30003
	s_add_u32 s3, s3, s4
	s_lshl_b32 s4, s1, 19
	s_lshl_b32 s5, s3, 19
	s_mov_b32 s6, 0
	v_writelane_b32 v249, s1, 58
	v_writelane_b32 v249, s4, 59
	v_writelane_b32 v249, s6, 60
	v_writelane_b32 v249, s3, 61
	v_writelane_b32 v249, s5, 63
	v_writelane_b32 v250, s6, 0
	s_mov_b32 s74, 0x100000
	s_mov_b32 s75, 0
	s_mov_b32 s101, 3
	s_mov_b64 s[0:1], exec
	s_branch .LBB0_762
.Lgt_ret:
	s_mov_b32 s101, 0
	v_readlane_b32 s1, v255, 19
	v_readlane_b32 s2, v255, 20
	s_nop 3
	s_sub_u32 s1, s1, 1
	s_add_u32 s2, s2, 1
	v_writelane_b32 v255, s1, 19
	v_writelane_b32 v255, s2, 20
	s_cmp_lg_u32 s1, 0
	s_cbranch_scc1 .Lgt_loop
	v_readlane_b32 s3, v255, 21
	v_readlane_b32 s4, v255, 22
	v_readlane_b32 s5, v255, 23
	v_readlane_b32 s6, v255, 24
	v_readlane_b32 s7, v255, 25
	v_readlane_b32 s26, v255, 26
	s_nop 3
	v_writelane_b32 v249, s3, 58
	v_writelane_b32 v249, s4, 59
	v_writelane_b32 v249, s5, 60
	v_writelane_b32 v249, s6, 61
	v_writelane_b32 v249, s7, 63
	v_writelane_b32 v250, s26, 0
	v_readlane_b32 s74, v251, 34
	v_readlane_b32 s75, v251, 35
	s_mov_b64 s[0:1], 0
	s_movk_i32 s93, 0x90

.LBB0_774:
	s_lshl_b32 s7, s37, 8
	s_ashr_i32 s9, s33, 2
	s_add_i32 s7, s7, s31
	s_lshl_b32 s14, s9, 10
	s_cmp_eq_u32 s9, 1
	s_mov_b32 s9, 0x1000000
	v_mov_b32_e32 v162, v1
	s_cselect_b32 s9, s9, 0x3400000
	s_cmp_gt_u32 s33, 3
	v_lshl_or_b32 v160, s33, 8, v186
	v_readlane_b32 s16, v251, 63
	v_add_u32_e32 v180, s7, v162
	s_cselect_b32 s7, s9, 0
	v_ashrrev_i32_e32 v161, 31, v160
	v_readlane_b32 s17, v252, 0
	s_lshl_b32 s7, s7, 1
	v_ashrrev_i32_e32 v181, 31, v180
	v_lshl_add_u64 v[28:29], v[160:161], 2, s[16:17]
	v_subrev_u32_e32 v160, s14, v160
	s_add_u32 s14, s29, s7
	s_addc_u32 s15, s30, 0
	v_ashrrev_i32_e32 v161, 31, v160
	v_lshl_add_u64 v[178:179], v[160:161], 1, s[14:15]
	v_lshlrev_b64 v[160:161], 6, v[180:181]
	v_lshl_add_u64 v[160:161], s[2:3], 0, v[160:161]
	global_load_dwordx4 v[40:43], v[28:29], off offset:16
	global_load_dwordx4 v[44:47], v[28:29], off
	global_load_dwordx4 v[24:27], v[28:29], off offset:528
	s_nop 0
	global_load_dwordx4 v[28:31], v[28:29], off offset:512
	s_nop 0
	global_load_dwordx4 v[188:191], v[160:161], off offset:16
	global_load_dwordx4 v[192:195], v[160:161], off offset:48
	global_load_dwordx4 v[196:199], v[160:161], off
	global_load_dwordx4 v[200:203], v[160:161], off offset:32
	s_mov_b64 s[48:49], 0x4000
	s_mov_b64 s[46:47], 0x8000
	s_waitcnt vmcnt(0)
	v_mov_b32_e32 v164, v190
	v_mov_b32_e32 v165, v194
	v_mov_b32_e32 v160, v196
	v_mov_b32_e32 v161, v200
	v_mov_b32_e32 v200, v197
	v_mov_b32_e32 v162, v198
	v_mov_b32_e32 v163, v202
	v_mov_b32_e32 v202, v199
	v_pk_add_f32 v[160:161], v[160:161], v[200:201]
	v_pk_add_f32 v[162:163], v[162:163], v[202:203]
	v_mov_b32_e32 v194, v191
	v_pk_add_f32 v[160:161], v[160:161], v[162:163]
	v_mov_b32_e32 v162, v188
	v_mov_b32_e32 v163, v192
	v_mov_b32_e32 v192, v189
	v_pk_add_f32 v[162:163], v[162:163], v[192:193]
	v_pk_add_f32 v[164:165], v[164:165], v[194:195]
	s_nop 0
	v_pk_add_f32 v[162:163], v[162:163], v[164:165]
	s_nop 0
	v_pk_add_f32 v[160:161], v[160:161], v[162:163]
	s_nop 0
	v_add_f32_e32 v160, v160, v161
	v_fmamk_f32 v160, v160, 0x3a800000, v208
	v_cmp_gt_f32_e32 vcc, s51, v160
	v_mul_f32_e32 v161, 0x4b800000, v160
	s_nop 0
	v_cndmask_b32_e32 v160, v160, v161, vcc
	v_rsq_f32_e32 v160, v160
	s_nop 0
	v_mul_f32_e32 v161, 0x45800000, v160
	v_cndmask_b32_e32 v184, v160, v161, vcc
	v_lshlrev_b64 v[160:161], 11, v[180:181]
	v_lshl_add_u64 v[182:183], v[178:179], 0, v[160:161]
	v_pk_fma_f32 v[160:161], v[148:149], v[184:185], v[44:45] op_sel_hi:[1,0,1]
	v_pk_fma_f32 v[148:149], v[146:147], v[184:185], v[42:43] op_sel_hi:[1,0,1]
	v_pk_fma_f32 v[146:147], v[144:145], v[184:185], v[40:41] op_sel_hi:[1,0,1]
	v_mul_f32_e32 v144, 0xbfb8aa3b, v160
	v_mul_f32_e32 v145, 0xbfb8aa3b, v161
	v_exp_f32_e32 v144, v144
	v_exp_f32_e32 v145, v145
	v_pk_fma_f32 v[150:151], v[150:151], v[184:185], v[46:47] op_sel_hi:[1,0,1]
	v_mul_f32_e32 v146, 0xbfb8aa3b, v146
	v_mul_f32_e32 v147, 0xbfb8aa3b, v147
	v_pk_add_f32 v[144:145], v[144:145], 1.0 op_sel_hi:[1,0]
	v_exp_f32_e32 v146, v146
	s_nop 0
	s_nop 0
	v_exp_f32_e32 v147, v147
	v_pk_fma_f32 v[142:143], v[142:143], v[184:185], v[30:31] op_sel_hi:[1,0,1]
	s_nop 0
	s_nop 0
	s_nop 0
	s_nop 0
	s_nop 0
	s_nop 0
	s_nop 0
	s_nop 0
	v_rcp_f32_e32 v145, v145
	s_nop 0
	s_nop 0
	v_pk_add_f32 v[146:147], v[146:147], 1.0 op_sel_hi:[1,0]
	s_nop 0
	s_nop 0
	s_nop 0
	s_nop 0
	s_nop 0
	s_nop 0
	s_nop 0
	s_nop 0
	v_rcp_f32_e32 v144, v144
	s_nop 0
	v_cvt_pk_bf16_f32 v144, v144, v145
	v_mul_f32_e32 v145, 0xbfb8aa3b, v150
	v_exp_f32_e32 v150, v145
	v_mul_f32_e32 v145, 0xbfb8aa3b, v151
	v_exp_f32_e32 v151, v145
	s_nop 0
	v_pk_add_f32 v[150:151], v[150:151], 1.0 op_sel_hi:[1,0]
	s_nop 0
	s_nop 0
	s_nop 0
	s_nop 0
	s_nop 0
	s_nop 0
	s_nop 0
	s_nop 0
	s_nop 0
	s_nop 0
	s_nop 0
	s_nop 0
	v_rcp_f32_e32 v145, v151
	s_nop 0
	s_nop 0
	s_nop 0
	s_nop 0
	s_nop 0
	s_nop 0
	s_nop 0
	s_nop 0
	s_nop 0
	s_nop 0
	s_nop 0
	v_rcp_f32_e32 v150, v150
	s_nop 0
	v_cvt_pk_bf16_f32 v145, v150, v145
	s_nop 0
	s_nop 0
	s_nop 0
	s_nop 0
	s_nop 0
	s_nop 0
	s_nop 0
	s_nop 0
	s_nop 0
	s_nop 0
	s_nop 0
	v_rcp_f32_e32 v147, v147
	s_nop 0
	s_nop 0
	s_nop 0
	s_nop 0
	s_nop 0
	s_nop 0
	s_nop 0
	s_nop 0
	s_nop 0
	s_nop 0
	s_nop 0
	v_rcp_f32_e32 v146, v146
	s_nop 0
	v_cvt_pk_bf16_f32 v146, v146, v147
	v_mul_f32_e32 v147, 0xbfb8aa3b, v148
	v_exp_f32_e32 v148, v147
	v_mul_f32_e32 v147, 0xbfb8aa3b, v149
	v_exp_f32_e32 v149, v147
	s_nop 0
	v_pk_add_f32 v[148:149], v[148:149], 1.0 op_sel_hi:[1,0]
	s_nop 0
	s_nop 0
	s_nop 0
	s_nop 0
	s_nop 0
	s_nop 0
	s_nop 0
	s_nop 0
	s_nop 0
	s_nop 0
	s_nop 0
	s_nop 0
	v_rcp_f32_e32 v147, v149
	s_nop 0
	s_nop 0
	s_nop 0
	s_nop 0
	s_nop 0
	s_nop 0
	s_nop 0
	s_nop 0
	s_nop 0
	s_nop 0
	s_nop 0
	v_rcp_f32_e32 v148, v148
	s_nop 0
	v_cvt_pk_bf16_f32 v147, v148, v147
	global_store_dwordx4 v[182:183], v[144:147], off
	v_add_u32_e32 v160, 16, v180
	v_ashrrev_i32_e32 v161, 31, v160
	v_pk_fma_f32 v[144:145], v[140:141], v[184:185], v[28:29] op_sel_hi:[1,0,1]
	v_pk_fma_f32 v[140:141], v[138:139], v[184:185], v[26:27] op_sel_hi:[1,0,1]
	v_pk_fma_f32 v[138:139], v[136:137], v[184:185], v[24:25] op_sel_hi:[1,0,1]
	v_mul_f32_e32 v136, 0xbfb8aa3b, v144
	v_mul_f32_e32 v137, 0xbfb8aa3b, v145
	v_exp_f32_e32 v136, v136
	v_exp_f32_e32 v137, v137
	v_mul_f32_e32 v138, 0xbfb8aa3b, v138
	v_mul_f32_e32 v139, 0xbfb8aa3b, v139
	v_exp_f32_e32 v138, v138
	v_pk_add_f32 v[136:137], v[136:137], 1.0 op_sel_hi:[1,0]
	v_exp_f32_e32 v139, v139
	s_nop 0
	s_nop 0
	v_pk_add_f32 v[138:139], v[138:139], 1.0 op_sel_hi:[1,0]
	s_nop 0
	s_nop 0
	s_nop 0
	s_nop 0
	s_nop 0
	s_nop 0
	s_nop 0
	s_nop 0
	v_rcp_f32_e32 v137, v137
	s_nop 0
	s_nop 0
	s_nop 0
	s_nop 0
	s_nop 0
	s_nop 0
	s_nop 0
	s_nop 0
	s_nop 0
	s_nop 0
	s_nop 0
	v_rcp_f32_e32 v136, v136
	s_nop 0
	v_cvt_pk_bf16_f32 v136, v136, v137
	v_mul_f32_e32 v137, 0xbfb8aa3b, v142
	v_exp_f32_e32 v142, v137
	v_mul_f32_e32 v137, 0xbfb8aa3b, v143
	v_exp_f32_e32 v143, v137
	s_nop 0
	v_pk_add_f32 v[142:143], v[142:143], 1.0 op_sel_hi:[1,0]
	s_nop 0
	s_nop 0
	s_nop 0
	s_nop 0
	s_nop 0
	s_nop 0
	s_nop 0
	s_nop 0
	s_nop 0
	s_nop 0
	s_nop 0
	s_nop 0
	v_rcp_f32_e32 v137, v143
	s_nop 0
	s_nop 0
	s_nop 0
	s_nop 0
	s_nop 0
	s_nop 0
	s_nop 0
	s_nop 0
	s_nop 0
	s_nop 0
	s_nop 0
	v_rcp_f32_e32 v142, v142
	s_nop 0
	v_cvt_pk_bf16_f32 v137, v142, v137
	s_nop 0
	s_nop 0
	s_nop 0
	s_nop 0
	s_nop 0
	s_nop 0
	s_nop 0
	s_nop 0
	s_nop 0
	s_nop 0
	s_nop 0
	v_rcp_f32_e32 v139, v139
	s_nop 0
	s_nop 0
	s_nop 0
	s_nop 0
	s_nop 0
	s_nop 0
	s_nop 0
	s_nop 0
	s_nop 0
	s_nop 0
	s_nop 0
	v_rcp_f32_e32 v138, v138
	s_nop 0
	v_cvt_pk_bf16_f32 v138, v138, v139
	v_mul_f32_e32 v139, 0xbfb8aa3b, v140
	v_exp_f32_e32 v140, v139
	v_mul_f32_e32 v139, 0xbfb8aa3b, v141
	v_exp_f32_e32 v141, v139
	s_nop 0
	v_pk_add_f32 v[140:141], v[140:141], 1.0 op_sel_hi:[1,0]
	s_nop 0
	s_nop 0
	s_nop 0
	s_nop 0
	s_nop 0
	s_nop 0
	s_nop 0
	s_nop 0
	s_nop 0
	s_nop 0
	s_nop 0
	s_nop 0
	v_rcp_f32_e32 v139, v141
	s_nop 0
	s_nop 0
	s_nop 0
	s_nop 0
	s_nop 0
	s_nop 0
	s_nop 0
	s_nop 0
	s_nop 0
	s_nop 0
	s_nop 0
	v_rcp_f32_e32 v140, v140
	s_nop 0
	v_cvt_pk_bf16_f32 v139, v140, v139
	global_store_dwordx4 v[182:183], v[136:139], off offset:256
	s_nop 1
	v_lshlrev_b64 v[136:137], 6, v[160:161]
	v_lshl_add_u64 v[148:149], s[2:3], 0, v[136:137]
	global_load_dwordx4 v[136:139], v[148:149], off offset:16
	global_load_dwordx4 v[140:143], v[148:149], off offset:48
	global_load_dwordx4 v[144:147], v[148:149], off
	s_nop 0
	global_load_dwordx4 v[148:151], v[148:149], off offset:32
	s_waitcnt vmcnt(1)
	v_mov_b32_e32 v162, v144
	s_waitcnt vmcnt(0)
	v_mov_b32_e32 v163, v148
	v_mov_b32_e32 v148, v145
	v_pk_add_f32 v[144:145], v[162:163], v[148:149]
	v_mov_b32_e32 v148, v146
	v_mov_b32_e32 v149, v150
	v_mov_b32_e32 v150, v147
	v_pk_add_f32 v[146:147], v[148:149], v[150:151]
	s_nop 0
	v_pk_add_f32 v[144:145], v[144:145], v[146:147]
	v_mov_b32_e32 v146, v136
	v_mov_b32_e32 v147, v140
	v_mov_b32_e32 v140, v137
	v_pk_add_f32 v[136:137], v[146:147], v[140:141]
	v_mov_b32_e32 v140, v138
	v_mov_b32_e32 v141, v142
	v_mov_b32_e32 v142, v139
	v_pk_add_f32 v[138:139], v[140:141], v[142:143]
	s_nop 0
	v_pk_add_f32 v[136:137], v[136:137], v[138:139]
	s_nop 0
	v_pk_add_f32 v[136:137], v[144:145], v[136:137]
	s_nop 0
	v_add_f32_e32 v136, v136, v137
	v_fmamk_f32 v136, v136, 0x3a800000, v208
	v_cmp_gt_f32_e32 vcc, s51, v136
	v_mul_f32_e32 v137, 0x4b800000, v136
	s_nop 0
	v_cndmask_b32_e32 v136, v136, v137, vcc
	v_rsq_f32_e32 v136, v136
	s_nop 0
	v_mul_f32_e32 v137, 0x45800000, v136
	v_cndmask_b32_e32 v138, v136, v137, vcc
	v_pk_fma_f32 v[140:141], v[132:133], v[138:139], v[44:45] op_sel_hi:[1,0,1]
	v_pk_fma_f32 v[132:133], v[130:131], v[138:139], v[42:43] op_sel_hi:[1,0,1]
	v_pk_fma_f32 v[130:131], v[128:129], v[138:139], v[40:41] op_sel_hi:[1,0,1]
	v_mul_f32_e32 v128, 0xbfb8aa3b, v140
	v_mul_f32_e32 v129, 0xbfb8aa3b, v141
	v_exp_f32_e32 v128, v128
	v_exp_f32_e32 v129, v129
	v_pk_fma_f32 v[134:135], v[134:135], v[138:139], v[46:47] op_sel_hi:[1,0,1]
	v_mul_f32_e32 v130, 0xbfb8aa3b, v130
	v_mul_f32_e32 v131, 0xbfb8aa3b, v131
	v_pk_add_f32 v[128:129], v[128:129], 1.0 op_sel_hi:[1,0]
	v_exp_f32_e32 v130, v130
	s_nop 0
	s_nop 0
	v_exp_f32_e32 v131, v131
	v_lshlrev_b64 v[136:137], 11, v[160:161]
	v_lshl_add_u64 v[136:137], v[178:179], 0, v[136:137]
	s_nop 0
	s_nop 0
	s_nop 0
	s_nop 0
	s_nop 0
	s_nop 0
	s_nop 0
	s_nop 0
	v_rcp_f32_e32 v129, v129
	s_nop 0
	s_nop 0
	v_pk_add_f32 v[130:131], v[130:131], 1.0 op_sel_hi:[1,0]
	s_nop 0
	s_nop 0
	s_nop 0
	s_nop 0
	s_nop 0
	s_nop 0
	s_nop 0
	s_nop 0
	v_rcp_f32_e32 v128, v128
	s_nop 0
	v_cvt_pk_bf16_f32 v128, v128, v129
	v_mul_f32_e32 v129, 0xbfb8aa3b, v134
	v_exp_f32_e32 v134, v129
	v_mul_f32_e32 v129, 0xbfb8aa3b, v135
	v_exp_f32_e32 v135, v129
	s_nop 0
	v_pk_add_f32 v[134:135], v[134:135], 1.0 op_sel_hi:[1,0]
	s_nop 0
	s_nop 0
	s_nop 0
	s_nop 0
	s_nop 0
	s_nop 0
	s_nop 0
	s_nop 0
	s_nop 0
	s_nop 0
	s_nop 0
	s_nop 0
	v_rcp_f32_e32 v129, v135
	s_nop 0
	s_nop 0
	s_nop 0
	s_nop 0
	s_nop 0
	s_nop 0
	s_nop 0
	s_nop 0
	s_nop 0
	s_nop 0
	s_nop 0
	v_rcp_f32_e32 v134, v134
	s_nop 0
	v_cvt_pk_bf16_f32 v129, v134, v129
	s_nop 0
	s_nop 0
	s_nop 0
	s_nop 0
	s_nop 0
	s_nop 0
	s_nop 0
	s_nop 0
	s_nop 0
	s_nop 0
	s_nop 0
	v_rcp_f32_e32 v131, v131
	s_nop 0
	s_nop 0
	s_nop 0
	s_nop 0
	s_nop 0
	s_nop 0
	s_nop 0
	s_nop 0
	s_nop 0
	s_nop 0
	s_nop 0
	v_rcp_f32_e32 v130, v130
	s_nop 0
	v_cvt_pk_bf16_f32 v130, v130, v131
	v_mul_f32_e32 v131, 0xbfb8aa3b, v132
	v_exp_f32_e32 v132, v131
	v_mul_f32_e32 v131, 0xbfb8aa3b, v133
	v_exp_f32_e32 v133, v131
	s_nop 0
	v_pk_add_f32 v[132:133], v[132:133], 1.0 op_sel_hi:[1,0]
	s_nop 0
	s_nop 0
	s_nop 0
	s_nop 0
	s_nop 0
	s_nop 0
	s_nop 0
	s_nop 0
	s_nop 0
	s_nop 0
	s_nop 0
	s_nop 0
	v_rcp_f32_e32 v131, v133
	s_nop 0
	s_nop 0
	s_nop 0
	s_nop 0
	s_nop 0
	s_nop 0
	s_nop 0
	s_nop 0
	s_nop 0
	s_nop 0
	s_nop 0
	v_rcp_f32_e32 v132, v132
	s_nop 0
	v_cvt_pk_bf16_f32 v131, v132, v131
	global_store_dwordx4 v[136:137], v[128:131], off
	v_pk_fma_f32 v[126:127], v[126:127], v[138:139], v[30:31] op_sel_hi:[1,0,1]
	s_nop 0
	v_pk_fma_f32 v[128:129], v[124:125], v[138:139], v[28:29] op_sel_hi:[1,0,1]
	v_pk_fma_f32 v[124:125], v[122:123], v[138:139], v[26:27] op_sel_hi:[1,0,1]
	v_pk_fma_f32 v[122:123], v[120:121], v[138:139], v[24:25] op_sel_hi:[1,0,1]
	v_mul_f32_e32 v120, 0xbfb8aa3b, v128
	v_mul_f32_e32 v121, 0xbfb8aa3b, v129
	v_exp_f32_e32 v120, v120
	v_exp_f32_e32 v121, v121
	v_mul_f32_e32 v122, 0xbfb8aa3b, v122
	v_mul_f32_e32 v123, 0xbfb8aa3b, v123
	v_exp_f32_e32 v122, v122
	v_pk_add_f32 v[120:121], v[120:121], 1.0 op_sel_hi:[1,0]
	v_exp_f32_e32 v123, v123
	s_nop 0
	s_nop 0
	v_pk_add_f32 v[122:123], v[122:123], 1.0 op_sel_hi:[1,0]
	s_nop 0
	s_nop 0
	s_nop 0
	s_nop 0
	s_nop 0
	s_nop 0
	s_nop 0
	s_nop 0
	v_rcp_f32_e32 v121, v121
	s_nop 0
	s_nop 0
	s_nop 0
	s_nop 0
	s_nop 0
	s_nop 0
	s_nop 0
	s_nop 0
	s_nop 0
	s_nop 0
	s_nop 0
	v_rcp_f32_e32 v120, v120
	s_nop 0
	v_cvt_pk_bf16_f32 v120, v120, v121
	v_mul_f32_e32 v121, 0xbfb8aa3b, v126
	v_exp_f32_e32 v126, v121
	v_mul_f32_e32 v121, 0xbfb8aa3b, v127
	v_exp_f32_e32 v127, v121
	s_nop 0
	v_pk_add_f32 v[126:127], v[126:127], 1.0 op_sel_hi:[1,0]
	s_nop 0
	s_nop 0
	s_nop 0
	s_nop 0
	s_nop 0
	s_nop 0
	s_nop 0
	s_nop 0
	s_nop 0
	s_nop 0
	s_nop 0
	s_nop 0
	v_rcp_f32_e32 v121, v127
	s_nop 0
	s_nop 0
	s_nop 0
	s_nop 0
	s_nop 0
	s_nop 0
	s_nop 0
	s_nop 0
	s_nop 0
	s_nop 0
	s_nop 0
	v_rcp_f32_e32 v126, v126
	s_nop 0
	v_cvt_pk_bf16_f32 v121, v126, v121
	s_nop 0
	s_nop 0
	s_nop 0
	s_nop 0
	s_nop 0
	s_nop 0
	s_nop 0
	s_nop 0
	s_nop 0
	s_nop 0
	s_nop 0
	v_rcp_f32_e32 v123, v123
	s_nop 0
	s_nop 0
	s_nop 0
	s_nop 0
	s_nop 0
	s_nop 0
	s_nop 0
	s_nop 0
	s_nop 0
	s_nop 0
	s_nop 0
	v_rcp_f32_e32 v122, v122
	s_nop 0
	v_cvt_pk_bf16_f32 v122, v122, v123
	v_mul_f32_e32 v123, 0xbfb8aa3b, v124
	v_exp_f32_e32 v124, v123
	v_mul_f32_e32 v123, 0xbfb8aa3b, v125
	v_exp_f32_e32 v125, v123
	s_nop 0
	v_pk_add_f32 v[124:125], v[124:125], 1.0 op_sel_hi:[1,0]
	s_nop 0
	s_nop 0
	s_nop 0
	s_nop 0
	s_nop 0
	s_nop 0
	s_nop 0
	s_nop 0
	s_nop 0
	s_nop 0
	s_nop 0
	s_nop 0
	v_rcp_f32_e32 v123, v125
	s_nop 0
	s_nop 0
	s_nop 0
	s_nop 0
	s_nop 0
	s_nop 0
	s_nop 0
	s_nop 0
	s_nop 0
	s_nop 0
	s_nop 0
	v_rcp_f32_e32 v124, v124
	s_nop 0
	v_cvt_pk_bf16_f32 v123, v124, v123
	global_store_dwordx4 v[136:137], v[120:123], off offset:256
	v_add_u32_e32 v136, 32, v180
	v_ashrrev_i32_e32 v137, 31, v136
	v_lshlrev_b64 v[120:121], 6, v[136:137]
	v_lshl_add_u64 v[132:133], s[2:3], 0, v[120:121]
	global_load_dwordx4 v[120:123], v[132:133], off offset:16
	global_load_dwordx4 v[124:127], v[132:133], off offset:48
	global_load_dwordx4 v[128:131], v[132:133], off
	s_nop 0
	global_load_dwordx4 v[132:135], v[132:133], off offset:32
	s_waitcnt vmcnt(1)
	v_mov_b32_e32 v138, v128
	s_waitcnt vmcnt(0)
	v_mov_b32_e32 v139, v132
	v_mov_b32_e32 v132, v129
	v_pk_add_f32 v[128:129], v[138:139], v[132:133]
	v_mov_b32_e32 v132, v130
	v_mov_b32_e32 v133, v134
	v_mov_b32_e32 v134, v131
	v_pk_add_f32 v[130:131], v[132:133], v[134:135]
	s_nop 0
	v_pk_add_f32 v[128:129], v[128:129], v[130:131]
	v_mov_b32_e32 v130, v120
	v_mov_b32_e32 v131, v124
	v_mov_b32_e32 v124, v121
	v_pk_add_f32 v[120:121], v[130:131], v[124:125]
	v_mov_b32_e32 v124, v122
	v_mov_b32_e32 v125, v126
	v_mov_b32_e32 v126, v123
	v_pk_add_f32 v[122:123], v[124:125], v[126:127]
	s_nop 0
	v_pk_add_f32 v[120:121], v[120:121], v[122:123]
	s_nop 0
	v_pk_add_f32 v[120:121], v[128:129], v[120:121]
	s_nop 0
	v_add_f32_e32 v120, v120, v121
	v_fmamk_f32 v120, v120, 0x3a800000, v208
	v_cmp_gt_f32_e32 vcc, s51, v120
	v_mul_f32_e32 v121, 0x4b800000, v120
	s_nop 0
	v_cndmask_b32_e32 v120, v120, v121, vcc
	v_rsq_f32_e32 v120, v120
	s_nop 0
	v_mul_f32_e32 v121, 0x45800000, v120
	v_cndmask_b32_e32 v122, v120, v121, vcc
	v_pk_fma_f32 v[124:125], v[116:117], v[122:123], v[44:45] op_sel_hi:[1,0,1]
	v_pk_fma_f32 v[116:117], v[114:115], v[122:123], v[42:43] op_sel_hi:[1,0,1]
	v_pk_fma_f32 v[114:115], v[112:113], v[122:123], v[40:41] op_sel_hi:[1,0,1]
	v_mul_f32_e32 v112, 0xbfb8aa3b, v124
	v_mul_f32_e32 v113, 0xbfb8aa3b, v125
	v_exp_f32_e32 v112, v112
	v_exp_f32_e32 v113, v113
	v_pk_fma_f32 v[118:119], v[118:119], v[122:123], v[46:47] op_sel_hi:[1,0,1]
	v_mul_f32_e32 v114, 0xbfb8aa3b, v114
	v_mul_f32_e32 v115, 0xbfb8aa3b, v115
	v_pk_add_f32 v[112:113], v[112:113], 1.0 op_sel_hi:[1,0]
	v_exp_f32_e32 v114, v114
	s_nop 0
	s_nop 0
	v_exp_f32_e32 v115, v115
	v_lshlrev_b64 v[120:121], 11, v[136:137]
	v_lshl_add_u64 v[120:121], v[178:179], 0, v[120:121]
	s_nop 0
	s_nop 0
	s_nop 0
	s_nop 0
	s_nop 0
	s_nop 0
	s_nop 0
	s_nop 0
	v_rcp_f32_e32 v113, v113
	s_nop 0
	s_nop 0
	v_pk_add_f32 v[114:115], v[114:115], 1.0 op_sel_hi:[1,0]
	s_nop 0
	s_nop 0
	s_nop 0
	s_nop 0
	s_nop 0
	s_nop 0
	s_nop 0
	s_nop 0
	v_rcp_f32_e32 v112, v112
	s_nop 0
	v_cvt_pk_bf16_f32 v112, v112, v113
	v_mul_f32_e32 v113, 0xbfb8aa3b, v118
	v_exp_f32_e32 v118, v113
	v_mul_f32_e32 v113, 0xbfb8aa3b, v119
	v_exp_f32_e32 v119, v113
	s_nop 0
	v_pk_add_f32 v[118:119], v[118:119], 1.0 op_sel_hi:[1,0]
	s_nop 0
	s_nop 0
	s_nop 0
	s_nop 0
	s_nop 0
	s_nop 0
	s_nop 0
	s_nop 0
	s_nop 0
	s_nop 0
	s_nop 0
	s_nop 0
	v_rcp_f32_e32 v113, v119
	s_nop 0
	s_nop 0
	s_nop 0
	s_nop 0
	s_nop 0
	s_nop 0
	s_nop 0
	s_nop 0
	s_nop 0
	s_nop 0
	s_nop 0
	v_rcp_f32_e32 v118, v118
	s_nop 0
	v_cvt_pk_bf16_f32 v113, v118, v113
	s_nop 0
	s_nop 0
	s_nop 0
	s_nop 0
	s_nop 0
	s_nop 0
	s_nop 0
	s_nop 0
	s_nop 0
	s_nop 0
	s_nop 0
	v_rcp_f32_e32 v115, v115
	s_nop 0
	s_nop 0
	s_nop 0
	s_nop 0
	s_nop 0
	s_nop 0
	s_nop 0
	s_nop 0
	s_nop 0
	s_nop 0
	s_nop 0
	v_rcp_f32_e32 v114, v114
	s_nop 0
	v_cvt_pk_bf16_f32 v114, v114, v115
	v_mul_f32_e32 v115, 0xbfb8aa3b, v116
	v_exp_f32_e32 v116, v115
	v_mul_f32_e32 v115, 0xbfb8aa3b, v117
	v_exp_f32_e32 v117, v115
	s_nop 0
	v_pk_add_f32 v[116:117], v[116:117], 1.0 op_sel_hi:[1,0]
	s_nop 0
	s_nop 0
	s_nop 0
	s_nop 0
	s_nop 0
	s_nop 0
	s_nop 0
	s_nop 0
	s_nop 0
	s_nop 0
	s_nop 0
	s_nop 0
	v_rcp_f32_e32 v115, v117
	s_nop 0
	s_nop 0
	s_nop 0
	s_nop 0
	s_nop 0
	s_nop 0
	s_nop 0
	s_nop 0
	s_nop 0
	s_nop 0
	s_nop 0
	v_rcp_f32_e32 v116, v116
	s_nop 0
	v_cvt_pk_bf16_f32 v115, v116, v115
	global_store_dwordx4 v[120:121], v[112:115], off
	v_pk_fma_f32 v[110:111], v[110:111], v[122:123], v[30:31] op_sel_hi:[1,0,1]
	s_nop 0
	v_pk_fma_f32 v[112:113], v[108:109], v[122:123], v[28:29] op_sel_hi:[1,0,1]
	v_pk_fma_f32 v[108:109], v[106:107], v[122:123], v[26:27] op_sel_hi:[1,0,1]
	v_pk_fma_f32 v[106:107], v[104:105], v[122:123], v[24:25] op_sel_hi:[1,0,1]
	v_mul_f32_e32 v104, 0xbfb8aa3b, v112
	v_mul_f32_e32 v105, 0xbfb8aa3b, v113
	v_exp_f32_e32 v104, v104
	v_exp_f32_e32 v105, v105
	v_mul_f32_e32 v106, 0xbfb8aa3b, v106
	v_mul_f32_e32 v107, 0xbfb8aa3b, v107
	v_exp_f32_e32 v106, v106
	v_pk_add_f32 v[104:105], v[104:105], 1.0 op_sel_hi:[1,0]
	v_exp_f32_e32 v107, v107
	s_nop 0
	s_nop 0
	v_pk_add_f32 v[106:107], v[106:107], 1.0 op_sel_hi:[1,0]
	s_nop 0
	s_nop 0
	s_nop 0
	s_nop 0
	s_nop 0
	s_nop 0
	s_nop 0
	s_nop 0
	v_rcp_f32_e32 v105, v105
	s_nop 0
	s_nop 0
	s_nop 0
	s_nop 0
	s_nop 0
	s_nop 0
	s_nop 0
	s_nop 0
	s_nop 0
	s_nop 0
	s_nop 0
	v_rcp_f32_e32 v104, v104
	s_nop 0
	v_cvt_pk_bf16_f32 v104, v104, v105
	v_mul_f32_e32 v105, 0xbfb8aa3b, v110
	v_exp_f32_e32 v110, v105
	v_mul_f32_e32 v105, 0xbfb8aa3b, v111
	v_exp_f32_e32 v111, v105
	s_nop 0
	v_pk_add_f32 v[110:111], v[110:111], 1.0 op_sel_hi:[1,0]
	s_nop 0
	s_nop 0
	s_nop 0
	s_nop 0
	s_nop 0
	s_nop 0
	s_nop 0
	s_nop 0
	s_nop 0
	s_nop 0
	s_nop 0
	s_nop 0
	v_rcp_f32_e32 v105, v111
	s_nop 0
	s_nop 0
	s_nop 0
	s_nop 0
	s_nop 0
	s_nop 0
	s_nop 0
	s_nop 0
	s_nop 0
	s_nop 0
	s_nop 0
	v_rcp_f32_e32 v110, v110
	s_nop 0
	v_cvt_pk_bf16_f32 v105, v110, v105
	s_nop 0
	s_nop 0
	s_nop 0
	s_nop 0
	s_nop 0
	s_nop 0
	s_nop 0
	s_nop 0
	s_nop 0
	s_nop 0
	s_nop 0
	v_rcp_f32_e32 v107, v107
	s_nop 0
	s_nop 0
	s_nop 0
	s_nop 0
	s_nop 0
	s_nop 0
	s_nop 0
	s_nop 0
	s_nop 0
	s_nop 0
	s_nop 0
	v_rcp_f32_e32 v106, v106
	s_nop 0
	v_cvt_pk_bf16_f32 v106, v106, v107
	v_mul_f32_e32 v107, 0xbfb8aa3b, v108
	v_exp_f32_e32 v108, v107
	v_mul_f32_e32 v107, 0xbfb8aa3b, v109
	v_exp_f32_e32 v109, v107
	s_nop 0
	v_pk_add_f32 v[108:109], v[108:109], 1.0 op_sel_hi:[1,0]
	s_nop 0
	s_nop 0
	s_nop 0
	s_nop 0
	s_nop 0
	s_nop 0
	s_nop 0
	s_nop 0
	s_nop 0
	s_nop 0
	s_nop 0
	s_nop 0
	v_rcp_f32_e32 v107, v109
	s_nop 0
	s_nop 0
	s_nop 0
	s_nop 0
	s_nop 0
	s_nop 0
	s_nop 0
	s_nop 0
	s_nop 0
	s_nop 0
	s_nop 0
	v_rcp_f32_e32 v108, v108
	s_nop 0
	v_cvt_pk_bf16_f32 v107, v108, v107
	global_store_dwordx4 v[120:121], v[104:107], off offset:256
	v_add_u32_e32 v120, 48, v180
	v_ashrrev_i32_e32 v121, 31, v120
	v_lshlrev_b64 v[104:105], 6, v[120:121]
	v_lshl_add_u64 v[116:117], s[2:3], 0, v[104:105]
	global_load_dwordx4 v[104:107], v[116:117], off offset:16
	global_load_dwordx4 v[108:111], v[116:117], off offset:48
	global_load_dwordx4 v[112:115], v[116:117], off
	s_nop 0
	global_load_dwordx4 v[116:119], v[116:117], off offset:32
	s_waitcnt vmcnt(1)
	v_mov_b32_e32 v122, v112
	s_waitcnt vmcnt(0)
	v_mov_b32_e32 v123, v116
	v_mov_b32_e32 v116, v113
	v_pk_add_f32 v[112:113], v[122:123], v[116:117]
	v_mov_b32_e32 v116, v114
	v_mov_b32_e32 v117, v118
	v_mov_b32_e32 v118, v115
	v_pk_add_f32 v[114:115], v[116:117], v[118:119]
	s_nop 0
	v_pk_add_f32 v[112:113], v[112:113], v[114:115]
	v_mov_b32_e32 v114, v104
	v_mov_b32_e32 v115, v108
	v_mov_b32_e32 v108, v105
	v_pk_add_f32 v[104:105], v[114:115], v[108:109]
	v_mov_b32_e32 v108, v106
	v_mov_b32_e32 v109, v110
	v_mov_b32_e32 v110, v107
	v_pk_add_f32 v[106:107], v[108:109], v[110:111]
	s_nop 0
	v_pk_add_f32 v[104:105], v[104:105], v[106:107]
	s_nop 0
	v_pk_add_f32 v[104:105], v[112:113], v[104:105]
	s_nop 0
	v_add_f32_e32 v104, v104, v105
	v_fmamk_f32 v104, v104, 0x3a800000, v208
	v_cmp_gt_f32_e32 vcc, s51, v104
	v_mul_f32_e32 v105, 0x4b800000, v104
	s_nop 0
	v_cndmask_b32_e32 v104, v104, v105, vcc
	v_rsq_f32_e32 v104, v104
	s_nop 0
	v_mul_f32_e32 v105, 0x45800000, v104
	v_cndmask_b32_e32 v106, v104, v105, vcc
	v_pk_fma_f32 v[108:109], v[100:101], v[106:107], v[44:45] op_sel_hi:[1,0,1]
	v_pk_fma_f32 v[100:101], v[98:99], v[106:107], v[42:43] op_sel_hi:[1,0,1]
	v_pk_fma_f32 v[98:99], v[96:97], v[106:107], v[40:41] op_sel_hi:[1,0,1]
	v_mul_f32_e32 v96, 0xbfb8aa3b, v108
	v_mul_f32_e32 v97, 0xbfb8aa3b, v109
	v_exp_f32_e32 v96, v96
	v_exp_f32_e32 v97, v97
	v_pk_fma_f32 v[102:103], v[102:103], v[106:107], v[46:47] op_sel_hi:[1,0,1]
	v_mul_f32_e32 v98, 0xbfb8aa3b, v98
	v_mul_f32_e32 v99, 0xbfb8aa3b, v99
	v_pk_add_f32 v[96:97], v[96:97], 1.0 op_sel_hi:[1,0]
	v_exp_f32_e32 v98, v98
	s_nop 0
	s_nop 0
	v_exp_f32_e32 v99, v99
	v_lshlrev_b64 v[104:105], 11, v[120:121]
	v_lshl_add_u64 v[104:105], v[178:179], 0, v[104:105]
	s_nop 0
	s_nop 0
	s_nop 0
	s_nop 0
	s_nop 0
	s_nop 0
	s_nop 0
	s_nop 0
	v_rcp_f32_e32 v97, v97
	s_nop 0
	s_nop 0
	v_pk_add_f32 v[98:99], v[98:99], 1.0 op_sel_hi:[1,0]
	s_nop 0
	s_nop 0
	s_nop 0
	s_nop 0
	s_nop 0
	s_nop 0
	s_nop 0
	s_nop 0
	v_rcp_f32_e32 v96, v96
	s_nop 0
	v_cvt_pk_bf16_f32 v96, v96, v97
	v_mul_f32_e32 v97, 0xbfb8aa3b, v102
	v_exp_f32_e32 v102, v97
	v_mul_f32_e32 v97, 0xbfb8aa3b, v103
	v_exp_f32_e32 v103, v97
	s_nop 0
	v_pk_add_f32 v[102:103], v[102:103], 1.0 op_sel_hi:[1,0]
	s_nop 0
	s_nop 0
	s_nop 0
	s_nop 0
	s_nop 0
	s_nop 0
	s_nop 0
	s_nop 0
	s_nop 0
	s_nop 0
	s_nop 0
	s_nop 0
	v_rcp_f32_e32 v97, v103
	s_nop 0
	s_nop 0
	s_nop 0
	s_nop 0
	s_nop 0
	s_nop 0
	s_nop 0
	s_nop 0
	s_nop 0
	s_nop 0
	s_nop 0
	v_rcp_f32_e32 v102, v102
	s_nop 0
	v_cvt_pk_bf16_f32 v97, v102, v97
	s_nop 0
	s_nop 0
	s_nop 0
	s_nop 0
	s_nop 0
	s_nop 0
	s_nop 0
	s_nop 0
	s_nop 0
	s_nop 0
	s_nop 0
	v_rcp_f32_e32 v99, v99
	s_nop 0
	s_nop 0
	s_nop 0
	s_nop 0
	s_nop 0
	s_nop 0
	s_nop 0
	s_nop 0
	s_nop 0
	s_nop 0
	s_nop 0
	v_rcp_f32_e32 v98, v98
	s_nop 0
	v_cvt_pk_bf16_f32 v98, v98, v99
	v_mul_f32_e32 v99, 0xbfb8aa3b, v100
	v_exp_f32_e32 v100, v99
	v_mul_f32_e32 v99, 0xbfb8aa3b, v101
	v_exp_f32_e32 v101, v99
	s_nop 0
	v_pk_add_f32 v[100:101], v[100:101], 1.0 op_sel_hi:[1,0]
	s_nop 0
	s_nop 0
	s_nop 0
	s_nop 0
	s_nop 0
	s_nop 0
	s_nop 0
	s_nop 0
	s_nop 0
	s_nop 0
	s_nop 0
	s_nop 0
	v_rcp_f32_e32 v99, v101
	s_nop 0
	s_nop 0
	s_nop 0
	s_nop 0
	s_nop 0
	s_nop 0
	s_nop 0
	s_nop 0
	s_nop 0
	s_nop 0
	s_nop 0
	v_rcp_f32_e32 v100, v100
	s_nop 0
	v_cvt_pk_bf16_f32 v99, v100, v99
	global_store_dwordx4 v[104:105], v[96:99], off
	v_pk_fma_f32 v[94:95], v[94:95], v[106:107], v[30:31] op_sel_hi:[1,0,1]
	s_nop 0
	v_pk_fma_f32 v[96:97], v[92:93], v[106:107], v[28:29] op_sel_hi:[1,0,1]
	v_pk_fma_f32 v[92:93], v[90:91], v[106:107], v[26:27] op_sel_hi:[1,0,1]
	v_pk_fma_f32 v[90:91], v[88:89], v[106:107], v[24:25] op_sel_hi:[1,0,1]
	v_mul_f32_e32 v88, 0xbfb8aa3b, v96
	v_mul_f32_e32 v89, 0xbfb8aa3b, v97
	v_exp_f32_e32 v88, v88
	v_exp_f32_e32 v89, v89
	v_mul_f32_e32 v90, 0xbfb8aa3b, v90
	v_mul_f32_e32 v91, 0xbfb8aa3b, v91
	v_exp_f32_e32 v90, v90
	v_pk_add_f32 v[88:89], v[88:89], 1.0 op_sel_hi:[1,0]
	v_exp_f32_e32 v91, v91
	s_nop 0
	s_nop 0
	v_pk_add_f32 v[90:91], v[90:91], 1.0 op_sel_hi:[1,0]
	s_nop 0
	s_nop 0
	s_nop 0
	s_nop 0
	s_nop 0
	s_nop 0
	s_nop 0
	s_nop 0
	v_rcp_f32_e32 v89, v89
	s_nop 0
	s_nop 0
	s_nop 0
	s_nop 0
	s_nop 0
	s_nop 0
	s_nop 0
	s_nop 0
	s_nop 0
	s_nop 0
	s_nop 0
	v_rcp_f32_e32 v88, v88
	s_nop 0
	v_cvt_pk_bf16_f32 v88, v88, v89
	v_mul_f32_e32 v89, 0xbfb8aa3b, v94
	v_exp_f32_e32 v94, v89
	v_mul_f32_e32 v89, 0xbfb8aa3b, v95
	v_exp_f32_e32 v95, v89
	s_nop 0
	v_pk_add_f32 v[94:95], v[94:95], 1.0 op_sel_hi:[1,0]
	s_nop 0
	s_nop 0
	s_nop 0
	s_nop 0
	s_nop 0
	s_nop 0
	s_nop 0
	s_nop 0
	s_nop 0
	s_nop 0
	s_nop 0
	s_nop 0
	v_rcp_f32_e32 v89, v95
	s_nop 0
	s_nop 0
	s_nop 0
	s_nop 0
	s_nop 0
	s_nop 0
	s_nop 0
	s_nop 0
	s_nop 0
	s_nop 0
	s_nop 0
	v_rcp_f32_e32 v94, v94
	s_nop 0
	v_cvt_pk_bf16_f32 v89, v94, v89
	s_nop 0
	s_nop 0
	s_nop 0
	s_nop 0
	s_nop 0
	s_nop 0
	s_nop 0
	s_nop 0
	s_nop 0
	s_nop 0
	s_nop 0
	v_rcp_f32_e32 v91, v91
	s_nop 0
	s_nop 0
	s_nop 0
	s_nop 0
	s_nop 0
	s_nop 0
	s_nop 0
	s_nop 0
	s_nop 0
	s_nop 0
	s_nop 0
	v_rcp_f32_e32 v90, v90
	s_nop 0
	v_cvt_pk_bf16_f32 v90, v90, v91
	v_mul_f32_e32 v91, 0xbfb8aa3b, v92
	v_exp_f32_e32 v92, v91
	v_mul_f32_e32 v91, 0xbfb8aa3b, v93
	v_exp_f32_e32 v93, v91
	s_nop 0
	v_pk_add_f32 v[92:93], v[92:93], 1.0 op_sel_hi:[1,0]
	s_nop 0
	s_nop 0
	s_nop 0
	s_nop 0
	s_nop 0
	s_nop 0
	s_nop 0
	s_nop 0
	s_nop 0
	s_nop 0
	s_nop 0
	s_nop 0
	v_rcp_f32_e32 v91, v93
	s_nop 0
	s_nop 0
	s_nop 0
	s_nop 0
	s_nop 0
	s_nop 0
	s_nop 0
	s_nop 0
	s_nop 0
	s_nop 0
	s_nop 0
	v_rcp_f32_e32 v92, v92
	s_nop 0
	v_cvt_pk_bf16_f32 v91, v92, v91
	global_store_dwordx4 v[104:105], v[88:91], off offset:256
	v_add_u32_e32 v104, 0x80, v180
	v_ashrrev_i32_e32 v105, 31, v104
	v_lshlrev_b64 v[88:89], 6, v[104:105]
	v_lshl_add_u64 v[100:101], s[2:3], 0, v[88:89]
	global_load_dwordx4 v[88:91], v[100:101], off offset:16
	global_load_dwordx4 v[92:95], v[100:101], off offset:48
	global_load_dwordx4 v[96:99], v[100:101], off
	s_nop 0
	global_load_dwordx4 v[100:103], v[100:101], off offset:32
	s_waitcnt vmcnt(1)
	v_mov_b32_e32 v106, v96
	s_waitcnt vmcnt(0)
	v_mov_b32_e32 v107, v100
	v_mov_b32_e32 v100, v97
	v_pk_add_f32 v[96:97], v[106:107], v[100:101]
	v_mov_b32_e32 v100, v98
	v_mov_b32_e32 v101, v102
	v_mov_b32_e32 v102, v99
	v_pk_add_f32 v[98:99], v[100:101], v[102:103]
	s_nop 0
	v_pk_add_f32 v[96:97], v[96:97], v[98:99]
	v_mov_b32_e32 v98, v88
	v_mov_b32_e32 v99, v92
	v_mov_b32_e32 v92, v89
	v_pk_add_f32 v[88:89], v[98:99], v[92:93]
	v_mov_b32_e32 v92, v90
	v_mov_b32_e32 v93, v94
	v_mov_b32_e32 v94, v91
	v_pk_add_f32 v[90:91], v[92:93], v[94:95]
	s_nop 0
	v_pk_add_f32 v[88:89], v[88:89], v[90:91]
	s_nop 0
	v_pk_add_f32 v[88:89], v[96:97], v[88:89]
	s_nop 0
	v_add_f32_e32 v88, v88, v89
	v_fmamk_f32 v88, v88, 0x3a800000, v208
	v_cmp_gt_f32_e32 vcc, s51, v88
	v_mul_f32_e32 v89, 0x4b800000, v88
	s_nop 0
	v_cndmask_b32_e32 v88, v88, v89, vcc
	v_rsq_f32_e32 v88, v88
	s_nop 0
	v_mul_f32_e32 v89, 0x45800000, v88
	v_cndmask_b32_e32 v90, v88, v89, vcc
	v_pk_fma_f32 v[92:93], v[84:85], v[90:91], v[44:45] op_sel_hi:[1,0,1]
	v_pk_fma_f32 v[84:85], v[82:83], v[90:91], v[42:43] op_sel_hi:[1,0,1]
	v_pk_fma_f32 v[82:83], v[80:81], v[90:91], v[40:41] op_sel_hi:[1,0,1]
	v_mul_f32_e32 v80, 0xbfb8aa3b, v92
	v_mul_f32_e32 v81, 0xbfb8aa3b, v93
	v_exp_f32_e32 v80, v80
	v_exp_f32_e32 v81, v81
	v_pk_fma_f32 v[86:87], v[86:87], v[90:91], v[46:47] op_sel_hi:[1,0,1]
	v_mul_f32_e32 v82, 0xbfb8aa3b, v82
	v_mul_f32_e32 v83, 0xbfb8aa3b, v83
	v_pk_add_f32 v[80:81], v[80:81], 1.0 op_sel_hi:[1,0]
	v_exp_f32_e32 v82, v82
	s_nop 0
	s_nop 0
	v_exp_f32_e32 v83, v83
	v_lshlrev_b64 v[88:89], 11, v[104:105]
	v_lshl_add_u64 v[88:89], v[178:179], 0, v[88:89]
	s_nop 0
	s_nop 0
	s_nop 0
	s_nop 0
	s_nop 0
	s_nop 0
	s_nop 0
	s_nop 0
	v_rcp_f32_e32 v81, v81
	s_nop 0
	s_nop 0
	v_pk_add_f32 v[82:83], v[82:83], 1.0 op_sel_hi:[1,0]
	s_nop 0
	s_nop 0
	s_nop 0
	s_nop 0
	s_nop 0
	s_nop 0
	s_nop 0
	s_nop 0
	v_rcp_f32_e32 v80, v80
	s_nop 0
	v_cvt_pk_bf16_f32 v80, v80, v81
	v_mul_f32_e32 v81, 0xbfb8aa3b, v86
	v_exp_f32_e32 v86, v81
	v_mul_f32_e32 v81, 0xbfb8aa3b, v87
	v_exp_f32_e32 v87, v81
	s_nop 0
	v_pk_add_f32 v[86:87], v[86:87], 1.0 op_sel_hi:[1,0]
	s_nop 0
	s_nop 0
	s_nop 0
	s_nop 0
	s_nop 0
	s_nop 0
	s_nop 0
	s_nop 0
	s_nop 0
	s_nop 0
	s_nop 0
	s_nop 0
	v_rcp_f32_e32 v81, v87
	s_nop 0
	s_nop 0
	s_nop 0
	s_nop 0
	s_nop 0
	s_nop 0
	s_nop 0
	s_nop 0
	s_nop 0
	s_nop 0
	s_nop 0
	v_rcp_f32_e32 v86, v86
	s_nop 0
	v_cvt_pk_bf16_f32 v81, v86, v81
	s_nop 0
	s_nop 0
	s_nop 0
	s_nop 0
	s_nop 0
	s_nop 0
	s_nop 0
	s_nop 0
	s_nop 0
	s_nop 0
	s_nop 0
	v_rcp_f32_e32 v83, v83
	s_nop 0
	s_nop 0
	s_nop 0
	s_nop 0
	s_nop 0
	s_nop 0
	s_nop 0
	s_nop 0
	s_nop 0
	s_nop 0
	s_nop 0
	v_rcp_f32_e32 v82, v82
	s_nop 0
	v_cvt_pk_bf16_f32 v82, v82, v83
	v_mul_f32_e32 v83, 0xbfb8aa3b, v84
	v_exp_f32_e32 v84, v83
	v_mul_f32_e32 v83, 0xbfb8aa3b, v85
	v_exp_f32_e32 v85, v83
	s_nop 0
	v_pk_add_f32 v[84:85], v[84:85], 1.0 op_sel_hi:[1,0]
	s_nop 0
	s_nop 0
	s_nop 0
	s_nop 0
	s_nop 0
	s_nop 0
	s_nop 0
	s_nop 0
	s_nop 0
	s_nop 0
	s_nop 0
	s_nop 0
	v_rcp_f32_e32 v83, v85
	s_nop 0
	s_nop 0
	s_nop 0
	s_nop 0
	s_nop 0
	s_nop 0
	s_nop 0
	s_nop 0
	s_nop 0
	s_nop 0
	s_nop 0
	v_rcp_f32_e32 v84, v84
	s_nop 0
	v_cvt_pk_bf16_f32 v83, v84, v83
	global_store_dwordx4 v[88:89], v[80:83], off
	v_pk_fma_f32 v[78:79], v[78:79], v[90:91], v[30:31] op_sel_hi:[1,0,1]
	s_nop 0
	v_pk_fma_f32 v[80:81], v[76:77], v[90:91], v[28:29] op_sel_hi:[1,0,1]
	v_pk_fma_f32 v[76:77], v[74:75], v[90:91], v[26:27] op_sel_hi:[1,0,1]
	v_pk_fma_f32 v[74:75], v[72:73], v[90:91], v[24:25] op_sel_hi:[1,0,1]
	v_mul_f32_e32 v72, 0xbfb8aa3b, v80
	v_mul_f32_e32 v73, 0xbfb8aa3b, v81
	v_exp_f32_e32 v72, v72
	v_exp_f32_e32 v73, v73
	v_mul_f32_e32 v74, 0xbfb8aa3b, v74
	v_mul_f32_e32 v75, 0xbfb8aa3b, v75
	v_exp_f32_e32 v74, v74
	v_pk_add_f32 v[72:73], v[72:73], 1.0 op_sel_hi:[1,0]
	v_exp_f32_e32 v75, v75
	s_nop 0
	s_nop 0
	v_pk_add_f32 v[74:75], v[74:75], 1.0 op_sel_hi:[1,0]
	s_nop 0
	s_nop 0
	s_nop 0
	s_nop 0
	s_nop 0
	s_nop 0
	s_nop 0
	s_nop 0
	v_rcp_f32_e32 v73, v73
	s_nop 0
	s_nop 0
	s_nop 0
	s_nop 0
	s_nop 0
	s_nop 0
	s_nop 0
	s_nop 0
	s_nop 0
	s_nop 0
	s_nop 0
	v_rcp_f32_e32 v72, v72
	s_nop 0
	v_cvt_pk_bf16_f32 v72, v72, v73
	v_mul_f32_e32 v73, 0xbfb8aa3b, v78
	v_exp_f32_e32 v78, v73
	v_mul_f32_e32 v73, 0xbfb8aa3b, v79
	v_exp_f32_e32 v79, v73
	s_nop 0
	v_pk_add_f32 v[78:79], v[78:79], 1.0 op_sel_hi:[1,0]
	s_nop 0
	s_nop 0
	s_nop 0
	s_nop 0
	s_nop 0
	s_nop 0
	s_nop 0
	s_nop 0
	s_nop 0
	s_nop 0
	s_nop 0
	s_nop 0
	v_rcp_f32_e32 v73, v79
	s_nop 0
	s_nop 0
	s_nop 0
	s_nop 0
	s_nop 0
	s_nop 0
	s_nop 0
	s_nop 0
	s_nop 0
	s_nop 0
	s_nop 0
	v_rcp_f32_e32 v78, v78
	s_nop 0
	v_cvt_pk_bf16_f32 v73, v78, v73
	s_nop 0
	s_nop 0
	s_nop 0
	s_nop 0
	s_nop 0
	s_nop 0
	s_nop 0
	s_nop 0
	s_nop 0
	s_nop 0
	s_nop 0
	v_rcp_f32_e32 v75, v75
	s_nop 0
	s_nop 0
	s_nop 0
	s_nop 0
	s_nop 0
	s_nop 0
	s_nop 0
	s_nop 0
	s_nop 0
	s_nop 0
	s_nop 0
	v_rcp_f32_e32 v74, v74
	s_nop 0
	v_cvt_pk_bf16_f32 v74, v74, v75
	v_mul_f32_e32 v75, 0xbfb8aa3b, v76
	v_exp_f32_e32 v76, v75
	v_mul_f32_e32 v75, 0xbfb8aa3b, v77
	v_exp_f32_e32 v77, v75
	s_nop 0
	v_pk_add_f32 v[76:77], v[76:77], 1.0 op_sel_hi:[1,0]
	s_nop 0
	s_nop 0
	s_nop 0
	s_nop 0
	s_nop 0
	s_nop 0
	s_nop 0
	s_nop 0
	s_nop 0
	s_nop 0
	s_nop 0
	s_nop 0
	v_rcp_f32_e32 v75, v77
	s_nop 0
	s_nop 0
	s_nop 0
	s_nop 0
	s_nop 0
	s_nop 0
	s_nop 0
	s_nop 0
	s_nop 0
	s_nop 0
	s_nop 0
	v_rcp_f32_e32 v76, v76
	s_nop 0
	v_cvt_pk_bf16_f32 v75, v76, v75
	global_store_dwordx4 v[88:89], v[72:75], off offset:256
	v_add_u32_e32 v88, 0x90, v180
	v_ashrrev_i32_e32 v89, 31, v88
	v_lshlrev_b64 v[72:73], 6, v[88:89]
	v_lshl_add_u64 v[84:85], s[2:3], 0, v[72:73]
	global_load_dwordx4 v[72:75], v[84:85], off offset:16
	global_load_dwordx4 v[76:79], v[84:85], off offset:48
	global_load_dwordx4 v[80:83], v[84:85], off
	s_nop 0
	global_load_dwordx4 v[84:87], v[84:85], off offset:32
	s_waitcnt vmcnt(1)
	v_mov_b32_e32 v90, v80
	s_waitcnt vmcnt(0)
	v_mov_b32_e32 v91, v84
	v_mov_b32_e32 v84, v81
	v_pk_add_f32 v[80:81], v[90:91], v[84:85]
	v_mov_b32_e32 v84, v82
	v_mov_b32_e32 v85, v86
	v_mov_b32_e32 v86, v83
	v_pk_add_f32 v[82:83], v[84:85], v[86:87]
	s_nop 0
	v_pk_add_f32 v[80:81], v[80:81], v[82:83]
	v_mov_b32_e32 v82, v72
	v_mov_b32_e32 v83, v76
	v_mov_b32_e32 v76, v73
	v_pk_add_f32 v[72:73], v[82:83], v[76:77]
	v_mov_b32_e32 v76, v74
	v_mov_b32_e32 v77, v78
	v_mov_b32_e32 v78, v75
	v_pk_add_f32 v[74:75], v[76:77], v[78:79]
	s_nop 0
	v_pk_add_f32 v[72:73], v[72:73], v[74:75]
	s_nop 0
	v_pk_add_f32 v[72:73], v[80:81], v[72:73]
	s_nop 0
	v_add_f32_e32 v72, v72, v73
	v_fmamk_f32 v72, v72, 0x3a800000, v208
	v_cmp_gt_f32_e32 vcc, s51, v72
	v_mul_f32_e32 v73, 0x4b800000, v72
	s_nop 0
	v_cndmask_b32_e32 v72, v72, v73, vcc
	v_rsq_f32_e32 v72, v72
	s_nop 0
	v_mul_f32_e32 v73, 0x45800000, v72
	v_cndmask_b32_e32 v74, v72, v73, vcc
	v_pk_fma_f32 v[76:77], v[68:69], v[74:75], v[44:45] op_sel_hi:[1,0,1]
	v_pk_fma_f32 v[68:69], v[66:67], v[74:75], v[42:43] op_sel_hi:[1,0,1]
	v_pk_fma_f32 v[66:67], v[64:65], v[74:75], v[40:41] op_sel_hi:[1,0,1]
	v_mul_f32_e32 v64, 0xbfb8aa3b, v76
	v_mul_f32_e32 v65, 0xbfb8aa3b, v77
	v_exp_f32_e32 v64, v64
	v_exp_f32_e32 v65, v65
	v_pk_fma_f32 v[70:71], v[70:71], v[74:75], v[46:47] op_sel_hi:[1,0,1]
	v_mul_f32_e32 v66, 0xbfb8aa3b, v66
	v_mul_f32_e32 v67, 0xbfb8aa3b, v67
	v_pk_add_f32 v[64:65], v[64:65], 1.0 op_sel_hi:[1,0]
	v_exp_f32_e32 v66, v66
	s_nop 0
	s_nop 0
	v_exp_f32_e32 v67, v67
	v_lshlrev_b64 v[72:73], 11, v[88:89]
	v_lshl_add_u64 v[72:73], v[178:179], 0, v[72:73]
	s_nop 0
	s_nop 0
	s_nop 0
	s_nop 0
	s_nop 0
	s_nop 0
	s_nop 0
	s_nop 0
	v_rcp_f32_e32 v65, v65
	s_nop 0
	s_nop 0
	v_pk_add_f32 v[66:67], v[66:67], 1.0 op_sel_hi:[1,0]
	s_nop 0
	s_nop 0
	s_nop 0
	s_nop 0
	s_nop 0
	s_nop 0
	s_nop 0
	s_nop 0
	v_rcp_f32_e32 v64, v64
	s_nop 0
	v_cvt_pk_bf16_f32 v64, v64, v65
	v_mul_f32_e32 v65, 0xbfb8aa3b, v70
	v_exp_f32_e32 v70, v65
	v_mul_f32_e32 v65, 0xbfb8aa3b, v71
	v_exp_f32_e32 v71, v65
	s_nop 0
	v_pk_add_f32 v[70:71], v[70:71], 1.0 op_sel_hi:[1,0]
	s_nop 0
	s_nop 0
	s_nop 0
	s_nop 0
	s_nop 0
	s_nop 0
	s_nop 0
	s_nop 0
	s_nop 0
	s_nop 0
	s_nop 0
	s_nop 0
	v_rcp_f32_e32 v65, v71
	s_nop 0
	s_nop 0
	s_nop 0
	s_nop 0
	s_nop 0
	s_nop 0
	s_nop 0
	s_nop 0
	s_nop 0
	s_nop 0
	s_nop 0
	v_rcp_f32_e32 v70, v70
	s_nop 0
	v_cvt_pk_bf16_f32 v65, v70, v65
	s_nop 0
	s_nop 0
	s_nop 0
	s_nop 0
	s_nop 0
	s_nop 0
	s_nop 0
	s_nop 0
	s_nop 0
	s_nop 0
	s_nop 0
	v_rcp_f32_e32 v67, v67
	s_nop 0
	s_nop 0
	s_nop 0
	s_nop 0
	s_nop 0
	s_nop 0
	s_nop 0
	s_nop 0
	s_nop 0
	s_nop 0
	s_nop 0
	v_rcp_f32_e32 v66, v66
	s_nop 0
	v_cvt_pk_bf16_f32 v66, v66, v67
	v_mul_f32_e32 v67, 0xbfb8aa3b, v68
	v_exp_f32_e32 v68, v67
	v_mul_f32_e32 v67, 0xbfb8aa3b, v69
	v_exp_f32_e32 v69, v67
	s_nop 0
	v_pk_add_f32 v[68:69], v[68:69], 1.0 op_sel_hi:[1,0]
	s_nop 0
	s_nop 0
	s_nop 0
	s_nop 0
	s_nop 0
	s_nop 0
	s_nop 0
	s_nop 0
	s_nop 0
	s_nop 0
	s_nop 0
	s_nop 0
	v_rcp_f32_e32 v67, v69
	s_nop 0
	s_nop 0
	s_nop 0
	s_nop 0
	s_nop 0
	s_nop 0
	s_nop 0
	s_nop 0
	s_nop 0
	s_nop 0
	s_nop 0
	v_rcp_f32_e32 v68, v68
	s_nop 0
	v_cvt_pk_bf16_f32 v67, v68, v67
	global_store_dwordx4 v[72:73], v[64:67], off
	v_pk_fma_f32 v[62:63], v[62:63], v[74:75], v[30:31] op_sel_hi:[1,0,1]
	s_nop 0
	v_pk_fma_f32 v[64:65], v[60:61], v[74:75], v[28:29] op_sel_hi:[1,0,1]
	v_pk_fma_f32 v[60:61], v[58:59], v[74:75], v[26:27] op_sel_hi:[1,0,1]
	v_pk_fma_f32 v[58:59], v[56:57], v[74:75], v[24:25] op_sel_hi:[1,0,1]
	v_mul_f32_e32 v56, 0xbfb8aa3b, v64
	v_mul_f32_e32 v57, 0xbfb8aa3b, v65
	v_exp_f32_e32 v56, v56
	v_exp_f32_e32 v57, v57
	v_mul_f32_e32 v58, 0xbfb8aa3b, v58
	v_mul_f32_e32 v59, 0xbfb8aa3b, v59
	v_exp_f32_e32 v58, v58
	v_pk_add_f32 v[56:57], v[56:57], 1.0 op_sel_hi:[1,0]
	v_exp_f32_e32 v59, v59
	s_nop 0
	s_nop 0
	v_pk_add_f32 v[58:59], v[58:59], 1.0 op_sel_hi:[1,0]
	s_nop 0
	s_nop 0
	s_nop 0
	s_nop 0
	s_nop 0
	s_nop 0
	s_nop 0
	s_nop 0
	v_rcp_f32_e32 v57, v57
	s_nop 0
	s_nop 0
	s_nop 0
	s_nop 0
	s_nop 0
	s_nop 0
	s_nop 0
	s_nop 0
	s_nop 0
	s_nop 0
	s_nop 0
	v_rcp_f32_e32 v56, v56
	s_nop 0
	v_cvt_pk_bf16_f32 v56, v56, v57
	v_mul_f32_e32 v57, 0xbfb8aa3b, v62
	v_exp_f32_e32 v62, v57
	v_mul_f32_e32 v57, 0xbfb8aa3b, v63
	v_exp_f32_e32 v63, v57
	s_nop 0
	v_pk_add_f32 v[62:63], v[62:63], 1.0 op_sel_hi:[1,0]
	s_nop 0
	s_nop 0
	s_nop 0
	s_nop 0
	s_nop 0
	s_nop 0
	s_nop 0
	s_nop 0
	s_nop 0
	s_nop 0
	s_nop 0
	s_nop 0
	v_rcp_f32_e32 v57, v63
	s_nop 0
	s_nop 0
	s_nop 0
	s_nop 0
	s_nop 0
	s_nop 0
	s_nop 0
	s_nop 0
	s_nop 0
	s_nop 0
	s_nop 0
	v_rcp_f32_e32 v62, v62
	s_nop 0
	v_cvt_pk_bf16_f32 v57, v62, v57
	s_nop 0
	s_nop 0
	s_nop 0
	s_nop 0
	s_nop 0
	s_nop 0
	s_nop 0
	s_nop 0
	s_nop 0
	s_nop 0
	s_nop 0
	v_rcp_f32_e32 v59, v59
	s_nop 0
	s_nop 0
	s_nop 0
	s_nop 0
	s_nop 0
	s_nop 0
	s_nop 0
	s_nop 0
	s_nop 0
	s_nop 0
	s_nop 0
	v_rcp_f32_e32 v58, v58
	s_nop 0
	v_cvt_pk_bf16_f32 v58, v58, v59
	v_mul_f32_e32 v59, 0xbfb8aa3b, v60
	v_exp_f32_e32 v60, v59
	v_mul_f32_e32 v59, 0xbfb8aa3b, v61
	v_exp_f32_e32 v61, v59
	s_nop 0
	v_pk_add_f32 v[60:61], v[60:61], 1.0 op_sel_hi:[1,0]
	s_nop 0
	s_nop 0
	s_nop 0
	s_nop 0
	s_nop 0
	s_nop 0
	s_nop 0
	s_nop 0
	s_nop 0
	s_nop 0
	s_nop 0
	s_nop 0
	v_rcp_f32_e32 v59, v61
	s_nop 0
	s_nop 0
	s_nop 0
	s_nop 0
	s_nop 0
	s_nop 0
	s_nop 0
	s_nop 0
	s_nop 0
	s_nop 0
	s_nop 0
	v_rcp_f32_e32 v60, v60
	s_nop 0
	v_cvt_pk_bf16_f32 v59, v60, v59
	global_store_dwordx4 v[72:73], v[56:59], off offset:256
	v_add_u32_e32 v72, 0xa0, v180
	v_ashrrev_i32_e32 v73, 31, v72
	v_lshlrev_b64 v[56:57], 6, v[72:73]
	v_lshl_add_u64 v[68:69], s[2:3], 0, v[56:57]
	global_load_dwordx4 v[56:59], v[68:69], off offset:16
	global_load_dwordx4 v[60:63], v[68:69], off offset:48
	global_load_dwordx4 v[64:67], v[68:69], off
	s_nop 0
	global_load_dwordx4 v[68:71], v[68:69], off offset:32
	s_waitcnt vmcnt(1)
	v_mov_b32_e32 v74, v64
	s_waitcnt vmcnt(0)
	v_mov_b32_e32 v75, v68
	v_mov_b32_e32 v68, v65
	v_pk_add_f32 v[64:65], v[74:75], v[68:69]
	v_mov_b32_e32 v68, v66
	v_mov_b32_e32 v69, v70
	v_mov_b32_e32 v70, v67
	v_pk_add_f32 v[66:67], v[68:69], v[70:71]
	s_nop 0
	v_pk_add_f32 v[64:65], v[64:65], v[66:67]
	v_mov_b32_e32 v66, v56
	v_mov_b32_e32 v67, v60
	v_mov_b32_e32 v60, v57
	v_pk_add_f32 v[56:57], v[66:67], v[60:61]
	v_mov_b32_e32 v60, v58
	v_mov_b32_e32 v61, v62
	v_mov_b32_e32 v62, v59
	v_pk_add_f32 v[58:59], v[60:61], v[62:63]
	s_nop 0
	v_pk_add_f32 v[56:57], v[56:57], v[58:59]
	s_nop 0
	v_pk_add_f32 v[56:57], v[64:65], v[56:57]
	s_nop 0
	v_add_f32_e32 v56, v56, v57
	v_fmamk_f32 v56, v56, 0x3a800000, v208
	v_cmp_gt_f32_e32 vcc, s51, v56
	v_mul_f32_e32 v57, 0x4b800000, v56
	s_nop 0
	v_cndmask_b32_e32 v56, v56, v57, vcc
	v_rsq_f32_e32 v56, v56
	s_nop 0
	v_mul_f32_e32 v57, 0x45800000, v56
	v_cndmask_b32_e32 v58, v56, v57, vcc
	v_pk_fma_f32 v[60:61], v[52:53], v[58:59], v[44:45] op_sel_hi:[1,0,1]
	v_pk_fma_f32 v[52:53], v[50:51], v[58:59], v[42:43] op_sel_hi:[1,0,1]
	v_pk_fma_f32 v[50:51], v[48:49], v[58:59], v[40:41] op_sel_hi:[1,0,1]
	v_mul_f32_e32 v48, 0xbfb8aa3b, v60
	v_mul_f32_e32 v49, 0xbfb8aa3b, v61
	v_exp_f32_e32 v48, v48
	v_exp_f32_e32 v49, v49
	v_pk_fma_f32 v[54:55], v[54:55], v[58:59], v[46:47] op_sel_hi:[1,0,1]
	v_mul_f32_e32 v50, 0xbfb8aa3b, v50
	v_mul_f32_e32 v51, 0xbfb8aa3b, v51
	v_pk_add_f32 v[48:49], v[48:49], 1.0 op_sel_hi:[1,0]
	v_exp_f32_e32 v50, v50
	s_nop 0
	s_nop 0
	v_exp_f32_e32 v51, v51
	v_lshlrev_b64 v[56:57], 11, v[72:73]
	v_lshl_add_u64 v[56:57], v[178:179], 0, v[56:57]
	s_nop 0
	s_nop 0
	s_nop 0
	s_nop 0
	s_nop 0
	s_nop 0
	s_nop 0
	s_nop 0
	v_rcp_f32_e32 v49, v49
	s_nop 0
	s_nop 0
	v_pk_add_f32 v[50:51], v[50:51], 1.0 op_sel_hi:[1,0]
	s_nop 0
	s_nop 0
	s_nop 0
	s_nop 0
	s_nop 0
	s_nop 0
	s_nop 0
	s_nop 0
	v_rcp_f32_e32 v48, v48
	s_nop 0
	v_cvt_pk_bf16_f32 v48, v48, v49
	v_mul_f32_e32 v49, 0xbfb8aa3b, v54
	v_exp_f32_e32 v54, v49
	v_mul_f32_e32 v49, 0xbfb8aa3b, v55
	v_exp_f32_e32 v55, v49
	s_nop 0
	v_pk_add_f32 v[54:55], v[54:55], 1.0 op_sel_hi:[1,0]
	s_nop 0
	s_nop 0
	s_nop 0
	s_nop 0
	s_nop 0
	s_nop 0
	s_nop 0
	s_nop 0
	s_nop 0
	s_nop 0
	s_nop 0
	s_nop 0
	v_rcp_f32_e32 v49, v55
	s_nop 0
	s_nop 0
	s_nop 0
	s_nop 0
	s_nop 0
	s_nop 0
	s_nop 0
	s_nop 0
	s_nop 0
	s_nop 0
	s_nop 0
	v_rcp_f32_e32 v54, v54
	s_nop 0
	v_cvt_pk_bf16_f32 v49, v54, v49
	s_nop 0
	s_nop 0
	s_nop 0
	s_nop 0
	s_nop 0
	s_nop 0
	s_nop 0
	s_nop 0
	s_nop 0
	s_nop 0
	s_nop 0
	v_rcp_f32_e32 v51, v51
	s_nop 0
	s_nop 0
	s_nop 0
	s_nop 0
	s_nop 0
	s_nop 0
	s_nop 0
	s_nop 0
	s_nop 0
	s_nop 0
	s_nop 0
	v_rcp_f32_e32 v50, v50
	s_nop 0
	v_cvt_pk_bf16_f32 v50, v50, v51
	v_mul_f32_e32 v51, 0xbfb8aa3b, v52
	v_exp_f32_e32 v52, v51
	v_mul_f32_e32 v51, 0xbfb8aa3b, v53
	v_exp_f32_e32 v53, v51
	s_nop 0
	v_pk_add_f32 v[52:53], v[52:53], 1.0 op_sel_hi:[1,0]
	s_nop 0
	s_nop 0
	s_nop 0
	s_nop 0
	s_nop 0
	s_nop 0
	s_nop 0
	s_nop 0
	s_nop 0
	s_nop 0
	s_nop 0
	s_nop 0
	v_rcp_f32_e32 v51, v53
	s_nop 0
	s_nop 0
	s_nop 0
	s_nop 0
	s_nop 0
	s_nop 0
	s_nop 0
	s_nop 0
	s_nop 0
	s_nop 0
	s_nop 0
	v_rcp_f32_e32 v52, v52
	s_nop 0
	v_cvt_pk_bf16_f32 v51, v52, v51
	global_store_dwordx4 v[56:57], v[48:51], off
	v_pk_fma_f32 v[38:39], v[38:39], v[58:59], v[30:31] op_sel_hi:[1,0,1]
	s_nop 0
	v_pk_fma_f32 v[48:49], v[36:37], v[58:59], v[28:29] op_sel_hi:[1,0,1]
	v_pk_fma_f32 v[36:37], v[34:35], v[58:59], v[26:27] op_sel_hi:[1,0,1]
	v_pk_fma_f32 v[34:35], v[32:33], v[58:59], v[24:25] op_sel_hi:[1,0,1]
	v_mul_f32_e32 v32, 0xbfb8aa3b, v48
	v_mul_f32_e32 v33, 0xbfb8aa3b, v49
	v_exp_f32_e32 v32, v32
	v_exp_f32_e32 v33, v33
	v_mul_f32_e32 v34, 0xbfb8aa3b, v34
	v_mul_f32_e32 v35, 0xbfb8aa3b, v35
	v_exp_f32_e32 v34, v34
	v_pk_add_f32 v[32:33], v[32:33], 1.0 op_sel_hi:[1,0]
	v_exp_f32_e32 v35, v35
	s_nop 0
	s_nop 0
	v_pk_add_f32 v[34:35], v[34:35], 1.0 op_sel_hi:[1,0]
	s_nop 0
	s_nop 0
	s_nop 0
	s_nop 0
	s_nop 0
	s_nop 0
	s_nop 0
	s_nop 0
	v_rcp_f32_e32 v33, v33
	s_nop 0
	s_nop 0
	s_nop 0
	s_nop 0
	s_nop 0
	s_nop 0
	s_nop 0
	s_nop 0
	s_nop 0
	s_nop 0
	s_nop 0
	v_rcp_f32_e32 v32, v32
	s_nop 0
	v_cvt_pk_bf16_f32 v32, v32, v33
	v_mul_f32_e32 v33, 0xbfb8aa3b, v38
	v_exp_f32_e32 v38, v33
	v_mul_f32_e32 v33, 0xbfb8aa3b, v39
	v_exp_f32_e32 v39, v33
	s_nop 0
	v_pk_add_f32 v[38:39], v[38:39], 1.0 op_sel_hi:[1,0]
	s_nop 0
	s_nop 0
	s_nop 0
	s_nop 0
	s_nop 0
	s_nop 0
	s_nop 0
	s_nop 0
	s_nop 0
	s_nop 0
	s_nop 0
	s_nop 0
	v_rcp_f32_e32 v33, v39
	s_nop 0
	s_nop 0
	s_nop 0
	s_nop 0
	s_nop 0
	s_nop 0
	s_nop 0
	s_nop 0
	s_nop 0
	s_nop 0
	s_nop 0
	v_rcp_f32_e32 v38, v38
	s_nop 0
	v_cvt_pk_bf16_f32 v33, v38, v33
	s_nop 0
	s_nop 0
	s_nop 0
	s_nop 0
	s_nop 0
	s_nop 0
	s_nop 0
	s_nop 0
	s_nop 0
	s_nop 0
	s_nop 0
	v_rcp_f32_e32 v35, v35
	s_nop 0
	s_nop 0
	s_nop 0
	s_nop 0
	s_nop 0
	s_nop 0
	s_nop 0
	s_nop 0
	s_nop 0
	s_nop 0
	s_nop 0
	v_rcp_f32_e32 v34, v34
	s_nop 0
	v_cvt_pk_bf16_f32 v34, v34, v35
	v_mul_f32_e32 v35, 0xbfb8aa3b, v36
	v_exp_f32_e32 v36, v35
	v_mul_f32_e32 v35, 0xbfb8aa3b, v37
	v_exp_f32_e32 v37, v35
	s_nop 0
	v_pk_add_f32 v[36:37], v[36:37], 1.0 op_sel_hi:[1,0]
	s_nop 0
	s_nop 0
	s_nop 0
	s_nop 0
	s_nop 0
	s_nop 0
	s_nop 0
	s_nop 0
	s_nop 0
	s_nop 0
	s_nop 0
	s_nop 0
	v_rcp_f32_e32 v35, v37
	s_nop 0
	s_nop 0
	s_nop 0
	s_nop 0
	s_nop 0
	s_nop 0
	s_nop 0
	s_nop 0
	s_nop 0
	s_nop 0
	s_nop 0
	v_rcp_f32_e32 v36, v36
	s_nop 0
	v_cvt_pk_bf16_f32 v35, v36, v35
	global_store_dwordx4 v[56:57], v[32:35], off offset:256
	v_add_u32_e32 v56, 0xb0, v180
	v_ashrrev_i32_e32 v57, 31, v56
	v_lshlrev_b64 v[32:33], 6, v[56:57]
	v_lshl_add_u64 v[52:53], s[2:3], 0, v[32:33]
	global_load_dwordx4 v[32:35], v[52:53], off offset:16
	global_load_dwordx4 v[36:39], v[52:53], off offset:48
	global_load_dwordx4 v[48:51], v[52:53], off
	s_nop 0
	global_load_dwordx4 v[52:55], v[52:53], off offset:32
	s_waitcnt vmcnt(1)
	v_mov_b32_e32 v58, v48
	s_waitcnt vmcnt(0)
	v_mov_b32_e32 v59, v52
	v_mov_b32_e32 v52, v49
	v_pk_add_f32 v[48:49], v[58:59], v[52:53]
	v_mov_b32_e32 v52, v50
	v_mov_b32_e32 v53, v54
	v_mov_b32_e32 v54, v51
	v_pk_add_f32 v[50:51], v[52:53], v[54:55]
	s_nop 0
	v_pk_add_f32 v[48:49], v[48:49], v[50:51]
	v_mov_b32_e32 v50, v32
	v_mov_b32_e32 v51, v36
	v_mov_b32_e32 v36, v33
	v_pk_add_f32 v[32:33], v[50:51], v[36:37]
	v_mov_b32_e32 v36, v34
	v_mov_b32_e32 v37, v38
	v_mov_b32_e32 v38, v35
	v_pk_add_f32 v[34:35], v[36:37], v[38:39]
	s_nop 0
	v_pk_add_f32 v[32:33], v[32:33], v[34:35]
	s_nop 0
	v_pk_add_f32 v[32:33], v[48:49], v[32:33]
	s_nop 0
	v_add_f32_e32 v32, v32, v33
	v_fmamk_f32 v32, v32, 0x3a800000, v208
	v_cmp_gt_f32_e32 vcc, s51, v32
	v_mul_f32_e32 v33, 0x4b800000, v32
	s_nop 0
	v_cndmask_b32_e32 v32, v32, v33, vcc
	v_rsq_f32_e32 v32, v32
	s_nop 0
	v_mul_f32_e32 v33, 0x45800000, v32
	v_cndmask_b32_e32 v34, v32, v33, vcc
	v_pk_fma_f32 v[36:37], v[20:21], v[34:35], v[44:45] op_sel_hi:[1,0,1]
	v_pk_fma_f32 v[20:21], v[18:19], v[34:35], v[42:43] op_sel_hi:[1,0,1]
	v_pk_fma_f32 v[18:19], v[16:17], v[34:35], v[40:41] op_sel_hi:[1,0,1]
	v_mul_f32_e32 v16, 0xbfb8aa3b, v36
	v_mul_f32_e32 v17, 0xbfb8aa3b, v37
	v_exp_f32_e32 v16, v16
	v_exp_f32_e32 v17, v17
	v_pk_fma_f32 v[22:23], v[22:23], v[34:35], v[46:47] op_sel_hi:[1,0,1]
	v_mul_f32_e32 v18, 0xbfb8aa3b, v18
	v_mul_f32_e32 v19, 0xbfb8aa3b, v19
	v_pk_add_f32 v[16:17], v[16:17], 1.0 op_sel_hi:[1,0]
	v_exp_f32_e32 v18, v18
	s_nop 0
	s_nop 0
	v_exp_f32_e32 v19, v19
	v_lshlrev_b64 v[32:33], 11, v[56:57]
	v_lshl_add_u64 v[32:33], v[178:179], 0, v[32:33]
	s_nop 0
	s_nop 0
	s_nop 0
	s_nop 0
	s_nop 0
	s_nop 0
	s_nop 0
	s_nop 0
	v_rcp_f32_e32 v17, v17
	s_nop 0
	s_nop 0
	v_pk_add_f32 v[18:19], v[18:19], 1.0 op_sel_hi:[1,0]
	s_nop 0
	s_nop 0
	s_nop 0
	s_nop 0
	s_nop 0
	s_nop 0
	s_nop 0
	s_nop 0
	v_rcp_f32_e32 v16, v16
	s_nop 0
	v_cvt_pk_bf16_f32 v16, v16, v17
	v_mul_f32_e32 v17, 0xbfb8aa3b, v22
	v_exp_f32_e32 v22, v17
	v_mul_f32_e32 v17, 0xbfb8aa3b, v23
	v_exp_f32_e32 v23, v17
	s_nop 0
	v_pk_add_f32 v[22:23], v[22:23], 1.0 op_sel_hi:[1,0]
	s_nop 0
	s_nop 0
	s_nop 0
	s_nop 0
	s_nop 0
	s_nop 0
	s_nop 0
	s_nop 0
	s_nop 0
	s_nop 0
	s_nop 0
	s_nop 0
	v_rcp_f32_e32 v17, v23
	s_nop 0
	s_nop 0
	s_nop 0
	s_nop 0
	s_nop 0
	s_nop 0
	s_nop 0
	s_nop 0
	s_nop 0
	s_nop 0
	s_nop 0
	v_rcp_f32_e32 v22, v22
	s_nop 0
	v_cvt_pk_bf16_f32 v17, v22, v17
	s_nop 0
	s_nop 0
	s_nop 0
	s_nop 0
	s_nop 0
	s_nop 0
	s_nop 0
	s_nop 0
	s_nop 0
	s_nop 0
	s_nop 0
	v_rcp_f32_e32 v19, v19
	s_nop 0
	s_nop 0
	s_nop 0
	s_nop 0
	s_nop 0
	s_nop 0
	s_nop 0
	s_nop 0
	s_nop 0
	s_nop 0
	s_nop 0
	v_rcp_f32_e32 v18, v18
	s_nop 0
	v_cvt_pk_bf16_f32 v18, v18, v19
	v_mul_f32_e32 v19, 0xbfb8aa3b, v20
	v_exp_f32_e32 v20, v19
	v_mul_f32_e32 v19, 0xbfb8aa3b, v21
	v_exp_f32_e32 v21, v19
	s_nop 0
	v_pk_add_f32 v[20:21], v[20:21], 1.0 op_sel_hi:[1,0]
	s_nop 0
	s_nop 0
	s_nop 0
	s_nop 0
	s_nop 0
	s_nop 0
	s_nop 0
	s_nop 0
	s_nop 0
	s_nop 0
	s_nop 0
	s_nop 0
	v_rcp_f32_e32 v19, v21
	s_nop 0
	s_nop 0
	s_nop 0
	s_nop 0
	s_nop 0
	s_nop 0
	s_nop 0
	s_nop 0
	s_nop 0
	s_nop 0
	s_nop 0
	v_rcp_f32_e32 v20, v20
	s_nop 0
	v_cvt_pk_bf16_f32 v19, v20, v19
	global_store_dwordx4 v[32:33], v[16:19], off
	v_pk_fma_f32 v[14:15], v[14:15], v[34:35], v[30:31] op_sel_hi:[1,0,1]
	s_nop 0
	v_pk_fma_f32 v[16:17], v[12:13], v[34:35], v[28:29] op_sel_hi:[1,0,1]
	v_pk_fma_f32 v[12:13], v[10:11], v[34:35], v[26:27] op_sel_hi:[1,0,1]
	v_pk_fma_f32 v[10:11], v[8:9], v[34:35], v[24:25] op_sel_hi:[1,0,1]
	v_mul_f32_e32 v8, 0xbfb8aa3b, v16
	v_mul_f32_e32 v9, 0xbfb8aa3b, v17
	v_exp_f32_e32 v8, v8
	v_exp_f32_e32 v9, v9
	v_mul_f32_e32 v10, 0xbfb8aa3b, v10
	v_mul_f32_e32 v11, 0xbfb8aa3b, v11
	v_exp_f32_e32 v10, v10
	v_pk_add_f32 v[8:9], v[8:9], 1.0 op_sel_hi:[1,0]
	v_exp_f32_e32 v11, v11
	s_nop 0
	s_nop 0
	v_pk_add_f32 v[10:11], v[10:11], 1.0 op_sel_hi:[1,0]
	s_nop 0
	s_nop 0
	s_nop 0
	s_nop 0
	s_nop 0
	s_nop 0
	s_nop 0
	s_nop 0
	v_rcp_f32_e32 v9, v9
	s_nop 0
	s_nop 0
	s_nop 0
	s_nop 0
	s_nop 0
	s_nop 0
	s_nop 0
	s_nop 0
	s_nop 0
	s_nop 0
	s_nop 0
	v_rcp_f32_e32 v8, v8
	s_nop 0
	v_cvt_pk_bf16_f32 v8, v8, v9
	v_mul_f32_e32 v9, 0xbfb8aa3b, v14
	v_exp_f32_e32 v14, v9
	v_mul_f32_e32 v9, 0xbfb8aa3b, v15
	v_exp_f32_e32 v15, v9
	s_nop 0
	v_pk_add_f32 v[14:15], v[14:15], 1.0 op_sel_hi:[1,0]
	s_nop 0
	s_nop 0
	s_nop 0
	s_nop 0
	s_nop 0
	s_nop 0
	s_nop 0
	s_nop 0
	s_nop 0
	s_nop 0
	s_nop 0
	s_nop 0
	v_rcp_f32_e32 v9, v15
	s_nop 0
	s_nop 0
	s_nop 0
	s_nop 0
	s_nop 0
	s_nop 0
	s_nop 0
	s_nop 0
	s_nop 0
	s_nop 0
	s_nop 0
	v_rcp_f32_e32 v14, v14
	s_nop 0
	v_cvt_pk_bf16_f32 v9, v14, v9
	s_nop 0
	s_nop 0
	s_nop 0
	s_nop 0
	s_nop 0
	s_nop 0
	s_nop 0
	s_nop 0
	s_nop 0
	s_nop 0
	s_nop 0
	v_rcp_f32_e32 v11, v11
	s_nop 0
	s_nop 0
	s_nop 0
	s_nop 0
	s_nop 0
	s_nop 0
	s_nop 0
	s_nop 0
	s_nop 0
	s_nop 0
	s_nop 0
	v_rcp_f32_e32 v10, v10
	s_nop 0
	v_cvt_pk_bf16_f32 v10, v10, v11
	v_mul_f32_e32 v11, 0xbfb8aa3b, v12
	v_exp_f32_e32 v12, v11
	v_mul_f32_e32 v11, 0xbfb8aa3b, v13
	v_exp_f32_e32 v13, v11
	s_nop 0
	v_pk_add_f32 v[12:13], v[12:13], 1.0 op_sel_hi:[1,0]
	s_nop 0
	s_nop 0
	s_nop 0
	s_nop 0
	s_nop 0
	s_nop 0
	s_nop 0
	s_nop 0
	s_nop 0
	s_nop 0
	s_nop 0
	s_nop 0
	v_rcp_f32_e32 v11, v13
	s_nop 0
	s_nop 0
	s_mov_b64 s[14:15], -1
	s_nop 0
	s_nop 0
	s_nop 0
	s_nop 0
	s_nop 0
	s_nop 0
	s_nop 0
	s_nop 0
	v_rcp_f32_e32 v12, v12
	s_nop 0
	v_cvt_pk_bf16_f32 v11, v12, v11
	global_store_dwordx4 v[32:33], v[8:11], off offset:256
	s_andn2_b64 vcc, exec, s[42:43]
	s_cbranch_vccnz .LBB0_767
	s_andn2_b64 vcc, exec, s[0:1]
	s_cbranch_vccnz .LBB0_766
	s_barrier
	s_branch .LBB0_766

.LBB0_778:
	s_cmp_eq_u32 s101, 3
	s_cbranch_scc1 .Lgt_ret
	s_waitcnt vmcnt(0)
	s_barrier
	s_mov_b64 s[0:1], exec
	v_readlane_b32 s2, v248, 18
	v_readlane_b32 s3, v248, 19
	s_and_b64 s[2:3], s[0:1], s[2:3]
	s_mov_b64 exec, s[2:3]
	s_cbranch_execz .LBB0_830
	v_readlane_b32 s2, v251, 2
	s_waitcnt vmcnt(0) expcnt(0) lgkmcnt(0)
	s_nop 0
	v_mov_b32_e32 v1, s2
	ds_read_b32 v3, v1
	v_readlane_b32 s2, v251, 3
	s_waitcnt lgkmcnt(0)
	v_cmp_ne_u32_e32 vcc, 0, v3
	v_mov_b32_e32 v1, s2
	ds_read_b32 v2, v1
	s_cbranch_vccnz .LBB0_794
	s_mov_b32 s8, 1
	s_branch .LBB0_782

.LBB0_866:
	v_and_b32_e32 v160, 63, v206
	v_lshrrev_b32_e32 v161, 6, v206
	v_and_b32_e32 v162, 15, v160
	v_readfirstlane_b32 s16, v161
	v_lshrrev_b32_e32 v163, 4, v160
	s_nop 3
	s_and_b32 s17, s16, 3
	s_lshl_b32 s17, s17, 5
	s_lshl_b32 s9, s33, 8
	s_add_i32 s17, s17, s9
	v_lshl_add_u32 v164, v163, 3, s17
	s_lshr_b32 s17, s16, 2
	s_lshl_b32 s17, s17, 6
	s_lshl_b32 s9, s37, 8
	s_add_i32 s9, s9, s17
	v_add_u32_e32 v165, s9, v162
	v_lshlrev_b32_e32 v146, 11, v165
	v_lshl_add_u32 v146, v164, 1, v146
	s_add_u32 s46, s70, 0x8c00000
	s_addc_u32 s47, s71, 0
	s_add_u32 s48, s70, 0xd400000
	s_addc_u32 s49, s71, 0
	v_mov_b32_e32 v147, 0x21800000
	v_mov_b32_e32 v172, v146
	v_add_u32_e32 v173, 0x8000, v146
	v_add_u32_e32 v174, 0x10000, v146
	v_add_u32_e32 v175, 0x18000, v146
	v_add_u32_e32 v176, 0x40000, v146
	v_add_u32_e32 v177, 0x48000, v146
	v_add_u32_e32 v178, 0x50000, v146
	v_add_u32_e32 v179, 0x58000, v146
	global_load_dwordx4 v[192:195], v172, s[46:47]
	global_load_dwordx4 v[196:199], v172, s[48:49]
	global_load_dwordx4 v[200:203], v172, s[46:47] offset:256
	global_load_dwordx4 v[216:219], v172, s[48:49] offset:256
	global_load_dwordx4 v[220:223], v173, s[46:47]
	global_load_dwordx4 v[224:227], v173, s[48:49]
	global_load_dwordx4 v[228:231], v173, s[46:47] offset:256
	global_load_dwordx4 v[232:235], v173, s[48:49] offset:256
	global_load_dwordx4 v[236:239], v174, s[46:47]
	global_load_dwordx4 v[240:243], v174, s[48:49]
	s_waitcnt vmcnt(8)
	v_lshlrev_b32_e32 v160, 16, v192
	v_and_b32_e32 v161, 0xffff0000, v192
	v_lshlrev_b32_e32 v162, 16, v193
	v_and_b32_e32 v163, 0xffff0000, v193
	v_lshlrev_b32_e32 v164, 16, v194
	v_and_b32_e32 v165, 0xffff0000, v194
	v_lshlrev_b32_e32 v180, 16, v195
	v_and_b32_e32 v181, 0xffff0000, v195
	v_lshlrev_b32_e32 v183, 16, v196
	v_and_b32_e32 v184, 0xffff0000, v196
	v_lshlrev_b32_e32 v185, 16, v197
	v_and_b32_e32 v186, 0xffff0000, v197
	v_lshlrev_b32_e32 v187, 16, v198
	v_and_b32_e32 v188, 0xffff0000, v198
	v_lshlrev_b32_e32 v189, 16, v199
	v_and_b32_e32 v190, 0xffff0000, v199
	global_load_dwordx4 v[192:195], v174, s[46:47] offset:256
	global_load_dwordx4 v[196:199], v174, s[48:49] offset:256
	v_max_f32_e32 v160, v160, v147
	v_max_f32_e32 v161, v161, v147
	v_max_f32_e32 v162, v162, v147
	v_max_f32_e32 v163, v163, v147
	v_max_f32_e32 v164, v164, v147
	v_max_f32_e32 v165, v165, v147
	v_max_f32_e32 v180, v180, v147
	v_max_f32_e32 v181, v181, v147
	v_max_f32_e32 v183, v183, v147
	v_max_f32_e32 v184, v184, v147
	v_max_f32_e32 v185, v185, v147
	v_max_f32_e32 v186, v186, v147
	v_max_f32_e32 v187, v187, v147
	v_max_f32_e32 v188, v188, v147
	v_max_f32_e32 v189, v189, v147
	v_max_f32_e32 v190, v190, v147
	v_rcp_f32_e32 v183, v183
	v_rcp_f32_e32 v184, v184
	v_rcp_f32_e32 v185, v185
	v_rcp_f32_e32 v186, v186
	v_rcp_f32_e32 v187, v187
	v_rcp_f32_e32 v188, v188
	v_rcp_f32_e32 v189, v189
	v_rcp_f32_e32 v190, v190
	v_mul_f32_e32 v160, v160, v183
	v_mul_f32_e32 v161, v161, v184
	v_mul_f32_e32 v162, v162, v185
	v_mul_f32_e32 v163, v163, v186
	v_mul_f32_e32 v164, v164, v187
	v_mul_f32_e32 v165, v165, v188
	v_mul_f32_e32 v180, v180, v189
	v_mul_f32_e32 v181, v181, v190
	v_mul_f32_e32 v132, v132, v160
	v_mul_f32_e32 v133, v133, v161
	v_mul_f32_e32 v134, v134, v162
	v_mul_f32_e32 v135, v135, v163
	v_mul_f32_e32 v128, v128, v164
	v_mul_f32_e32 v129, v129, v165
	v_mul_f32_e32 v130, v130, v180
	v_mul_f32_e32 v131, v131, v181
	s_waitcnt vmcnt(8)
	v_lshlrev_b32_e32 v160, 16, v200
	v_and_b32_e32 v161, 0xffff0000, v200
	v_lshlrev_b32_e32 v162, 16, v201
	v_and_b32_e32 v163, 0xffff0000, v201
	v_lshlrev_b32_e32 v164, 16, v202
	v_and_b32_e32 v165, 0xffff0000, v202
	v_lshlrev_b32_e32 v180, 16, v203
	v_and_b32_e32 v181, 0xffff0000, v203
	v_lshlrev_b32_e32 v183, 16, v216
	v_and_b32_e32 v184, 0xffff0000, v216
	v_lshlrev_b32_e32 v185, 16, v217
	v_and_b32_e32 v186, 0xffff0000, v217
	v_lshlrev_b32_e32 v187, 16, v218
	v_and_b32_e32 v188, 0xffff0000, v218
	v_lshlrev_b32_e32 v189, 16, v219
	v_and_b32_e32 v190, 0xffff0000, v219
	global_load_dwordx4 v[200:203], v175, s[46:47]
	global_load_dwordx4 v[216:219], v175, s[48:49]
	v_max_f32_e32 v160, v160, v147
	v_max_f32_e32 v161, v161, v147
	v_max_f32_e32 v162, v162, v147
	v_max_f32_e32 v163, v163, v147
	v_max_f32_e32 v164, v164, v147
	v_max_f32_e32 v165, v165, v147
	v_max_f32_e32 v180, v180, v147
	v_max_f32_e32 v181, v181, v147
	v_max_f32_e32 v183, v183, v147
	v_max_f32_e32 v184, v184, v147
	v_max_f32_e32 v185, v185, v147
	v_max_f32_e32 v186, v186, v147
	v_max_f32_e32 v187, v187, v147
	v_max_f32_e32 v188, v188, v147
	v_max_f32_e32 v189, v189, v147
	v_max_f32_e32 v190, v190, v147
	v_rcp_f32_e32 v183, v183
	v_rcp_f32_e32 v184, v184
	v_rcp_f32_e32 v185, v185
	v_rcp_f32_e32 v186, v186
	v_rcp_f32_e32 v187, v187
	v_rcp_f32_e32 v188, v188
	v_rcp_f32_e32 v189, v189
	v_rcp_f32_e32 v190, v190
	v_mul_f32_e32 v160, v160, v183
	v_mul_f32_e32 v161, v161, v184
	v_mul_f32_e32 v162, v162, v185
	v_mul_f32_e32 v163, v163, v186
	v_mul_f32_e32 v164, v164, v187
	v_mul_f32_e32 v165, v165, v188
	v_mul_f32_e32 v180, v180, v189
	v_mul_f32_e32 v181, v181, v190
	v_mul_f32_e32 v124, v124, v160
	v_mul_f32_e32 v125, v125, v161
	v_mul_f32_e32 v126, v126, v162
	v_mul_f32_e32 v127, v127, v163
	v_mul_f32_e32 v120, v120, v164
	v_mul_f32_e32 v121, v121, v165
	v_mul_f32_e32 v122, v122, v180
	v_mul_f32_e32 v123, v123, v181
	s_waitcnt vmcnt(8)
	v_lshlrev_b32_e32 v160, 16, v220
	v_and_b32_e32 v161, 0xffff0000, v220
	v_lshlrev_b32_e32 v162, 16, v221
	v_and_b32_e32 v163, 0xffff0000, v221
	v_lshlrev_b32_e32 v164, 16, v222
	v_and_b32_e32 v165, 0xffff0000, v222
	v_lshlrev_b32_e32 v180, 16, v223
	v_and_b32_e32 v181, 0xffff0000, v223
	v_lshlrev_b32_e32 v183, 16, v224
	v_and_b32_e32 v184, 0xffff0000, v224
	v_lshlrev_b32_e32 v185, 16, v225
	v_and_b32_e32 v186, 0xffff0000, v225
	v_lshlrev_b32_e32 v187, 16, v226
	v_and_b32_e32 v188, 0xffff0000, v226
	v_lshlrev_b32_e32 v189, 16, v227
	v_and_b32_e32 v190, 0xffff0000, v227
	global_load_dwordx4 v[220:223], v175, s[46:47] offset:256
	global_load_dwordx4 v[224:227], v175, s[48:49] offset:256
	v_max_f32_e32 v160, v160, v147
	v_max_f32_e32 v161, v161, v147
	v_max_f32_e32 v162, v162, v147
	v_max_f32_e32 v163, v163, v147
	v_max_f32_e32 v164, v164, v147
	v_max_f32_e32 v165, v165, v147
	v_max_f32_e32 v180, v180, v147
	v_max_f32_e32 v181, v181, v147
	v_max_f32_e32 v183, v183, v147
	v_max_f32_e32 v184, v184, v147
	v_max_f32_e32 v185, v185, v147
	v_max_f32_e32 v186, v186, v147
	v_max_f32_e32 v187, v187, v147
	v_max_f32_e32 v188, v188, v147
	v_max_f32_e32 v189, v189, v147
	v_max_f32_e32 v190, v190, v147
	v_rcp_f32_e32 v183, v183
	v_rcp_f32_e32 v184, v184
	v_rcp_f32_e32 v185, v185
	v_rcp_f32_e32 v186, v186
	v_rcp_f32_e32 v187, v187
	v_rcp_f32_e32 v188, v188
	v_rcp_f32_e32 v189, v189
	v_rcp_f32_e32 v190, v190
	v_mul_f32_e32 v160, v160, v183
	v_mul_f32_e32 v161, v161, v184
	v_mul_f32_e32 v162, v162, v185
	v_mul_f32_e32 v163, v163, v186
	v_mul_f32_e32 v164, v164, v187
	v_mul_f32_e32 v165, v165, v188
	v_mul_f32_e32 v180, v180, v189
	v_mul_f32_e32 v181, v181, v190
	v_mul_f32_e32 v116, v116, v160
	v_mul_f32_e32 v117, v117, v161
	v_mul_f32_e32 v118, v118, v162
	v_mul_f32_e32 v119, v119, v163
	v_mul_f32_e32 v112, v112, v164
	v_mul_f32_e32 v113, v113, v165
	v_mul_f32_e32 v114, v114, v180
	v_mul_f32_e32 v115, v115, v181
	s_waitcnt vmcnt(8)
	v_lshlrev_b32_e32 v160, 16, v228
	v_and_b32_e32 v161, 0xffff0000, v228
	v_lshlrev_b32_e32 v162, 16, v229
	v_and_b32_e32 v163, 0xffff0000, v229
	v_lshlrev_b32_e32 v164, 16, v230
	v_and_b32_e32 v165, 0xffff0000, v230
	v_lshlrev_b32_e32 v180, 16, v231
	v_and_b32_e32 v181, 0xffff0000, v231
	v_lshlrev_b32_e32 v183, 16, v232
	v_and_b32_e32 v184, 0xffff0000, v232
	v_lshlrev_b32_e32 v185, 16, v233
	v_and_b32_e32 v186, 0xffff0000, v233
	v_lshlrev_b32_e32 v187, 16, v234
	v_and_b32_e32 v188, 0xffff0000, v234
	v_lshlrev_b32_e32 v189, 16, v235
	v_and_b32_e32 v190, 0xffff0000, v235
	global_load_dwordx4 v[228:231], v176, s[46:47]
	global_load_dwordx4 v[232:235], v176, s[48:49]
	v_max_f32_e32 v160, v160, v147
	v_max_f32_e32 v161, v161, v147
	v_max_f32_e32 v162, v162, v147
	v_max_f32_e32 v163, v163, v147
	v_max_f32_e32 v164, v164, v147
	v_max_f32_e32 v165, v165, v147
	v_max_f32_e32 v180, v180, v147
	v_max_f32_e32 v181, v181, v147
	v_max_f32_e32 v183, v183, v147
	v_max_f32_e32 v184, v184, v147
	v_max_f32_e32 v185, v185, v147
	v_max_f32_e32 v186, v186, v147
	v_max_f32_e32 v187, v187, v147
	v_max_f32_e32 v188, v188, v147
	v_max_f32_e32 v189, v189, v147
	v_max_f32_e32 v190, v190, v147
	v_rcp_f32_e32 v183, v183
	v_rcp_f32_e32 v184, v184
	v_rcp_f32_e32 v185, v185
	v_rcp_f32_e32 v186, v186
	v_rcp_f32_e32 v187, v187
	v_rcp_f32_e32 v188, v188
	v_rcp_f32_e32 v189, v189
	v_rcp_f32_e32 v190, v190
	v_mul_f32_e32 v160, v160, v183
	v_mul_f32_e32 v161, v161, v184
	v_mul_f32_e32 v162, v162, v185
	v_mul_f32_e32 v163, v163, v186
	v_mul_f32_e32 v164, v164, v187
	v_mul_f32_e32 v165, v165, v188
	v_mul_f32_e32 v180, v180, v189
	v_mul_f32_e32 v181, v181, v190
	v_mul_f32_e32 v108, v108, v160
	v_mul_f32_e32 v109, v109, v161
	v_mul_f32_e32 v110, v110, v162
	v_mul_f32_e32 v111, v111, v163
	v_mul_f32_e32 v104, v104, v164
	v_mul_f32_e32 v105, v105, v165
	v_mul_f32_e32 v106, v106, v180
	v_mul_f32_e32 v107, v107, v181
	s_waitcnt vmcnt(8)
	v_lshlrev_b32_e32 v160, 16, v236
	v_and_b32_e32 v161, 0xffff0000, v236
	v_lshlrev_b32_e32 v162, 16, v237
	v_and_b32_e32 v163, 0xffff0000, v237
	v_lshlrev_b32_e32 v164, 16, v238
	v_and_b32_e32 v165, 0xffff0000, v238
	v_lshlrev_b32_e32 v180, 16, v239
	v_and_b32_e32 v181, 0xffff0000, v239
	v_lshlrev_b32_e32 v183, 16, v240
	v_and_b32_e32 v184, 0xffff0000, v240
	v_lshlrev_b32_e32 v185, 16, v241
	v_and_b32_e32 v186, 0xffff0000, v241
	v_lshlrev_b32_e32 v187, 16, v242
	v_and_b32_e32 v188, 0xffff0000, v242
	v_lshlrev_b32_e32 v189, 16, v243
	v_and_b32_e32 v190, 0xffff0000, v243
	global_load_dwordx4 v[236:239], v176, s[46:47] offset:256
	global_load_dwordx4 v[240:243], v176, s[48:49] offset:256
	v_max_f32_e32 v160, v160, v147
	v_max_f32_e32 v161, v161, v147
	v_max_f32_e32 v162, v162, v147
	v_max_f32_e32 v163, v163, v147
	v_max_f32_e32 v164, v164, v147
	v_max_f32_e32 v165, v165, v147
	v_max_f32_e32 v180, v180, v147
	v_max_f32_e32 v181, v181, v147
	v_max_f32_e32 v183, v183, v147
	v_max_f32_e32 v184, v184, v147
	v_max_f32_e32 v185, v185, v147
	v_max_f32_e32 v186, v186, v147
	v_max_f32_e32 v187, v187, v147
	v_max_f32_e32 v188, v188, v147
	v_max_f32_e32 v189, v189, v147
	v_max_f32_e32 v190, v190, v147
	v_rcp_f32_e32 v183, v183
	v_rcp_f32_e32 v184, v184
	v_rcp_f32_e32 v185, v185
	v_rcp_f32_e32 v186, v186
	v_rcp_f32_e32 v187, v187
	v_rcp_f32_e32 v188, v188
	v_rcp_f32_e32 v189, v189
	v_rcp_f32_e32 v190, v190
	v_mul_f32_e32 v160, v160, v183
	v_mul_f32_e32 v161, v161, v184
	v_mul_f32_e32 v162, v162, v185
	v_mul_f32_e32 v163, v163, v186
	v_mul_f32_e32 v164, v164, v187
	v_mul_f32_e32 v165, v165, v188
	v_mul_f32_e32 v180, v180, v189
	v_mul_f32_e32 v181, v181, v190
	v_mul_f32_e32 v100, v100, v160
	v_mul_f32_e32 v101, v101, v161
	v_mul_f32_e32 v102, v102, v162
	v_mul_f32_e32 v103, v103, v163
	v_mul_f32_e32 v96, v96, v164
	v_mul_f32_e32 v97, v97, v165
	v_mul_f32_e32 v98, v98, v180
	v_mul_f32_e32 v99, v99, v181
	s_waitcnt vmcnt(8)
	v_lshlrev_b32_e32 v160, 16, v192
	v_and_b32_e32 v161, 0xffff0000, v192
	v_lshlrev_b32_e32 v162, 16, v193
	v_and_b32_e32 v163, 0xffff0000, v193
	v_lshlrev_b32_e32 v164, 16, v194
	v_and_b32_e32 v165, 0xffff0000, v194
	v_lshlrev_b32_e32 v180, 16, v195
	v_and_b32_e32 v181, 0xffff0000, v195
	v_lshlrev_b32_e32 v183, 16, v196
	v_and_b32_e32 v184, 0xffff0000, v196
	v_lshlrev_b32_e32 v185, 16, v197
	v_and_b32_e32 v186, 0xffff0000, v197
	v_lshlrev_b32_e32 v187, 16, v198
	v_and_b32_e32 v188, 0xffff0000, v198
	v_lshlrev_b32_e32 v189, 16, v199
	v_and_b32_e32 v190, 0xffff0000, v199
	global_load_dwordx4 v[192:195], v177, s[46:47]
	global_load_dwordx4 v[196:199], v177, s[48:49]
	v_max_f32_e32 v160, v160, v147
	v_max_f32_e32 v161, v161, v147
	v_max_f32_e32 v162, v162, v147
	v_max_f32_e32 v163, v163, v147
	v_max_f32_e32 v164, v164, v147
	v_max_f32_e32 v165, v165, v147
	v_max_f32_e32 v180, v180, v147
	v_max_f32_e32 v181, v181, v147
	v_max_f32_e32 v183, v183, v147
	v_max_f32_e32 v184, v184, v147
	v_max_f32_e32 v185, v185, v147
	v_max_f32_e32 v186, v186, v147
	v_max_f32_e32 v187, v187, v147
	v_max_f32_e32 v188, v188, v147
	v_max_f32_e32 v189, v189, v147
	v_max_f32_e32 v190, v190, v147
	v_rcp_f32_e32 v183, v183
	v_rcp_f32_e32 v184, v184
	v_rcp_f32_e32 v185, v185
	v_rcp_f32_e32 v186, v186
	v_rcp_f32_e32 v187, v187
	v_rcp_f32_e32 v188, v188
	v_rcp_f32_e32 v189, v189
	v_rcp_f32_e32 v190, v190
	v_mul_f32_e32 v160, v160, v183
	v_mul_f32_e32 v161, v161, v184
	v_mul_f32_e32 v162, v162, v185
	v_mul_f32_e32 v163, v163, v186
	v_mul_f32_e32 v164, v164, v187
	v_mul_f32_e32 v165, v165, v188
	v_mul_f32_e32 v180, v180, v189
	v_mul_f32_e32 v181, v181, v190
	v_mul_f32_e32 v92, v92, v160
	v_mul_f32_e32 v93, v93, v161
	v_mul_f32_e32 v94, v94, v162
	v_mul_f32_e32 v95, v95, v163
	v_mul_f32_e32 v88, v88, v164
	v_mul_f32_e32 v89, v89, v165
	v_mul_f32_e32 v90, v90, v180
	v_mul_f32_e32 v91, v91, v181
	s_waitcnt vmcnt(8)
	v_lshlrev_b32_e32 v160, 16, v200
	v_and_b32_e32 v161, 0xffff0000, v200
	v_lshlrev_b32_e32 v162, 16, v201
	v_and_b32_e32 v163, 0xffff0000, v201
	v_lshlrev_b32_e32 v164, 16, v202
	v_and_b32_e32 v165, 0xffff0000, v202
	v_lshlrev_b32_e32 v180, 16, v203
	v_and_b32_e32 v181, 0xffff0000, v203
	v_lshlrev_b32_e32 v183, 16, v216
	v_and_b32_e32 v184, 0xffff0000, v216
	v_lshlrev_b32_e32 v185, 16, v217
	v_and_b32_e32 v186, 0xffff0000, v217
	v_lshlrev_b32_e32 v187, 16, v218
	v_and_b32_e32 v188, 0xffff0000, v218
	v_lshlrev_b32_e32 v189, 16, v219
	v_and_b32_e32 v190, 0xffff0000, v219
	global_load_dwordx4 v[200:203], v177, s[46:47] offset:256
	global_load_dwordx4 v[216:219], v177, s[48:49] offset:256
	v_max_f32_e32 v160, v160, v147
	v_max_f32_e32 v161, v161, v147
	v_max_f32_e32 v162, v162, v147
	v_max_f32_e32 v163, v163, v147
	v_max_f32_e32 v164, v164, v147
	v_max_f32_e32 v165, v165, v147
	v_max_f32_e32 v180, v180, v147
	v_max_f32_e32 v181, v181, v147
	v_max_f32_e32 v183, v183, v147
	v_max_f32_e32 v184, v184, v147
	v_max_f32_e32 v185, v185, v147
	v_max_f32_e32 v186, v186, v147
	v_max_f32_e32 v187, v187, v147
	v_max_f32_e32 v188, v188, v147
	v_max_f32_e32 v189, v189, v147
	v_max_f32_e32 v190, v190, v147
	v_rcp_f32_e32 v183, v183
	v_rcp_f32_e32 v184, v184
	v_rcp_f32_e32 v185, v185
	v_rcp_f32_e32 v186, v186
	v_rcp_f32_e32 v187, v187
	v_rcp_f32_e32 v188, v188
	v_rcp_f32_e32 v189, v189
	v_rcp_f32_e32 v190, v190
	v_mul_f32_e32 v160, v160, v183
	v_mul_f32_e32 v161, v161, v184
	v_mul_f32_e32 v162, v162, v185
	v_mul_f32_e32 v163, v163, v186
	v_mul_f32_e32 v164, v164, v187
	v_mul_f32_e32 v165, v165, v188
	v_mul_f32_e32 v180, v180, v189
	v_mul_f32_e32 v181, v181, v190
	v_mul_f32_e32 v84, v84, v160
	v_mul_f32_e32 v85, v85, v161
	v_mul_f32_e32 v86, v86, v162
	v_mul_f32_e32 v87, v87, v163
	v_mul_f32_e32 v80, v80, v164
	v_mul_f32_e32 v81, v81, v165
	v_mul_f32_e32 v82, v82, v180
	v_mul_f32_e32 v83, v83, v181
	s_waitcnt vmcnt(8)
	v_lshlrev_b32_e32 v160, 16, v220
	v_and_b32_e32 v161, 0xffff0000, v220
	v_lshlrev_b32_e32 v162, 16, v221
	v_and_b32_e32 v163, 0xffff0000, v221
	v_lshlrev_b32_e32 v164, 16, v222
	v_and_b32_e32 v165, 0xffff0000, v222
	v_lshlrev_b32_e32 v180, 16, v223
	v_and_b32_e32 v181, 0xffff0000, v223
	v_lshlrev_b32_e32 v183, 16, v224
	v_and_b32_e32 v184, 0xffff0000, v224
	v_lshlrev_b32_e32 v185, 16, v225
	v_and_b32_e32 v186, 0xffff0000, v225
	v_lshlrev_b32_e32 v187, 16, v226
	v_and_b32_e32 v188, 0xffff0000, v226
	v_lshlrev_b32_e32 v189, 16, v227
	v_and_b32_e32 v190, 0xffff0000, v227
	global_load_dwordx4 v[220:223], v178, s[46:47]
	global_load_dwordx4 v[224:227], v178, s[48:49]
	v_max_f32_e32 v160, v160, v147
	v_max_f32_e32 v161, v161, v147
	v_max_f32_e32 v162, v162, v147
	v_max_f32_e32 v163, v163, v147
	v_max_f32_e32 v164, v164, v147
	v_max_f32_e32 v165, v165, v147
	v_max_f32_e32 v180, v180, v147
	v_max_f32_e32 v181, v181, v147
	v_max_f32_e32 v183, v183, v147
	v_max_f32_e32 v184, v184, v147
	v_max_f32_e32 v185, v185, v147
	v_max_f32_e32 v186, v186, v147
	v_max_f32_e32 v187, v187, v147
	v_max_f32_e32 v188, v188, v147
	v_max_f32_e32 v189, v189, v147
	v_max_f32_e32 v190, v190, v147
	v_rcp_f32_e32 v183, v183
	v_rcp_f32_e32 v184, v184
	v_rcp_f32_e32 v185, v185
	v_rcp_f32_e32 v186, v186
	v_rcp_f32_e32 v187, v187
	v_rcp_f32_e32 v188, v188
	v_rcp_f32_e32 v189, v189
	v_rcp_f32_e32 v190, v190
	v_mul_f32_e32 v160, v160, v183
	v_mul_f32_e32 v161, v161, v184
	v_mul_f32_e32 v162, v162, v185
	v_mul_f32_e32 v163, v163, v186
	v_mul_f32_e32 v164, v164, v187
	v_mul_f32_e32 v165, v165, v188
	v_mul_f32_e32 v180, v180, v189
	v_mul_f32_e32 v181, v181, v190
	v_mul_f32_e32 v76, v76, v160
	v_mul_f32_e32 v77, v77, v161
	v_mul_f32_e32 v78, v78, v162
	v_mul_f32_e32 v79, v79, v163
	v_mul_f32_e32 v72, v72, v164
	v_mul_f32_e32 v73, v73, v165
	v_mul_f32_e32 v74, v74, v180
	v_mul_f32_e32 v75, v75, v181
	s_waitcnt vmcnt(8)
	v_lshlrev_b32_e32 v160, 16, v228
	v_and_b32_e32 v161, 0xffff0000, v228
	v_lshlrev_b32_e32 v162, 16, v229
	v_and_b32_e32 v163, 0xffff0000, v229
	v_lshlrev_b32_e32 v164, 16, v230
	v_and_b32_e32 v165, 0xffff0000, v230
	v_lshlrev_b32_e32 v180, 16, v231
	v_and_b32_e32 v181, 0xffff0000, v231
	v_lshlrev_b32_e32 v183, 16, v232
	v_and_b32_e32 v184, 0xffff0000, v232
	v_lshlrev_b32_e32 v185, 16, v233
	v_and_b32_e32 v186, 0xffff0000, v233
	v_lshlrev_b32_e32 v187, 16, v234
	v_and_b32_e32 v188, 0xffff0000, v234
	v_lshlrev_b32_e32 v189, 16, v235
	v_and_b32_e32 v190, 0xffff0000, v235
	global_load_dwordx4 v[228:231], v178, s[46:47] offset:256
	global_load_dwordx4 v[232:235], v178, s[48:49] offset:256
	v_max_f32_e32 v160, v160, v147
	v_max_f32_e32 v161, v161, v147
	v_max_f32_e32 v162, v162, v147
	v_max_f32_e32 v163, v163, v147
	v_max_f32_e32 v164, v164, v147
	v_max_f32_e32 v165, v165, v147
	v_max_f32_e32 v180, v180, v147
	v_max_f32_e32 v181, v181, v147
	v_max_f32_e32 v183, v183, v147
	v_max_f32_e32 v184, v184, v147
	v_max_f32_e32 v185, v185, v147
	v_max_f32_e32 v186, v186, v147
	v_max_f32_e32 v187, v187, v147
	v_max_f32_e32 v188, v188, v147
	v_max_f32_e32 v189, v189, v147
	v_max_f32_e32 v190, v190, v147
	v_rcp_f32_e32 v183, v183
	v_rcp_f32_e32 v184, v184
	v_rcp_f32_e32 v185, v185
	v_rcp_f32_e32 v186, v186
	v_rcp_f32_e32 v187, v187
	v_rcp_f32_e32 v188, v188
	v_rcp_f32_e32 v189, v189
	v_rcp_f32_e32 v190, v190
	v_mul_f32_e32 v160, v160, v183
	v_mul_f32_e32 v161, v161, v184
	v_mul_f32_e32 v162, v162, v185
	v_mul_f32_e32 v163, v163, v186
	v_mul_f32_e32 v164, v164, v187
	v_mul_f32_e32 v165, v165, v188
	v_mul_f32_e32 v180, v180, v189
	v_mul_f32_e32 v181, v181, v190
	v_mul_f32_e32 v68, v68, v160
	v_mul_f32_e32 v69, v69, v161
	v_mul_f32_e32 v70, v70, v162
	v_mul_f32_e32 v71, v71, v163
	v_mul_f32_e32 v64, v64, v164
	v_mul_f32_e32 v65, v65, v165
	v_mul_f32_e32 v66, v66, v180
	v_mul_f32_e32 v67, v67, v181
	s_waitcnt vmcnt(8)
	v_lshlrev_b32_e32 v160, 16, v236
	v_and_b32_e32 v161, 0xffff0000, v236
	v_lshlrev_b32_e32 v162, 16, v237
	v_and_b32_e32 v163, 0xffff0000, v237
	v_lshlrev_b32_e32 v164, 16, v238
	v_and_b32_e32 v165, 0xffff0000, v238
	v_lshlrev_b32_e32 v180, 16, v239
	v_and_b32_e32 v181, 0xffff0000, v239
	v_lshlrev_b32_e32 v183, 16, v240
	v_and_b32_e32 v184, 0xffff0000, v240
	v_lshlrev_b32_e32 v185, 16, v241
	v_and_b32_e32 v186, 0xffff0000, v241
	v_lshlrev_b32_e32 v187, 16, v242
	v_and_b32_e32 v188, 0xffff0000, v242
	v_lshlrev_b32_e32 v189, 16, v243
	v_and_b32_e32 v190, 0xffff0000, v243
	global_load_dwordx4 v[236:239], v179, s[46:47]
	global_load_dwordx4 v[240:243], v179, s[48:49]
	v_max_f32_e32 v160, v160, v147
	v_max_f32_e32 v161, v161, v147
	v_max_f32_e32 v162, v162, v147
	v_max_f32_e32 v163, v163, v147
	v_max_f32_e32 v164, v164, v147
	v_max_f32_e32 v165, v165, v147
	v_max_f32_e32 v180, v180, v147
	v_max_f32_e32 v181, v181, v147
	v_max_f32_e32 v183, v183, v147
	v_max_f32_e32 v184, v184, v147
	v_max_f32_e32 v185, v185, v147
	v_max_f32_e32 v186, v186, v147
	v_max_f32_e32 v187, v187, v147
	v_max_f32_e32 v188, v188, v147
	v_max_f32_e32 v189, v189, v147
	v_max_f32_e32 v190, v190, v147
	v_rcp_f32_e32 v183, v183
	v_rcp_f32_e32 v184, v184
	v_rcp_f32_e32 v185, v185
	v_rcp_f32_e32 v186, v186
	v_rcp_f32_e32 v187, v187
	v_rcp_f32_e32 v188, v188
	v_rcp_f32_e32 v189, v189
	v_rcp_f32_e32 v190, v190
	v_mul_f32_e32 v160, v160, v183
	v_mul_f32_e32 v161, v161, v184
	v_mul_f32_e32 v162, v162, v185
	v_mul_f32_e32 v163, v163, v186
	v_mul_f32_e32 v164, v164, v187
	v_mul_f32_e32 v165, v165, v188
	v_mul_f32_e32 v180, v180, v189
	v_mul_f32_e32 v181, v181, v190
	v_mul_f32_e32 v60, v60, v160
	v_mul_f32_e32 v61, v61, v161
	v_mul_f32_e32 v62, v62, v162
	v_mul_f32_e32 v63, v63, v163
	v_mul_f32_e32 v56, v56, v164
	v_mul_f32_e32 v57, v57, v165
	v_mul_f32_e32 v58, v58, v180
	v_mul_f32_e32 v59, v59, v181
	s_waitcnt vmcnt(8)
	v_lshlrev_b32_e32 v160, 16, v192
	v_and_b32_e32 v161, 0xffff0000, v192
	v_lshlrev_b32_e32 v162, 16, v193
	v_and_b32_e32 v163, 0xffff0000, v193
	v_lshlrev_b32_e32 v164, 16, v194
	v_and_b32_e32 v165, 0xffff0000, v194
	v_lshlrev_b32_e32 v180, 16, v195
	v_and_b32_e32 v181, 0xffff0000, v195
	v_lshlrev_b32_e32 v183, 16, v196
	v_and_b32_e32 v184, 0xffff0000, v196
	v_lshlrev_b32_e32 v185, 16, v197
	v_and_b32_e32 v186, 0xffff0000, v197
	v_lshlrev_b32_e32 v187, 16, v198
	v_and_b32_e32 v188, 0xffff0000, v198
	v_lshlrev_b32_e32 v189, 16, v199
	v_and_b32_e32 v190, 0xffff0000, v199
	global_load_dwordx4 v[192:195], v179, s[46:47] offset:256
	global_load_dwordx4 v[196:199], v179, s[48:49] offset:256
	v_max_f32_e32 v160, v160, v147
	v_max_f32_e32 v161, v161, v147
	v_max_f32_e32 v162, v162, v147
	v_max_f32_e32 v163, v163, v147
	v_max_f32_e32 v164, v164, v147
	v_max_f32_e32 v165, v165, v147
	v_max_f32_e32 v180, v180, v147
	v_max_f32_e32 v181, v181, v147
	v_max_f32_e32 v183, v183, v147
	v_max_f32_e32 v184, v184, v147
	v_max_f32_e32 v185, v185, v147
	v_max_f32_e32 v186, v186, v147
	v_max_f32_e32 v187, v187, v147
	v_max_f32_e32 v188, v188, v147
	v_max_f32_e32 v189, v189, v147
	v_max_f32_e32 v190, v190, v147
	v_rcp_f32_e32 v183, v183
	v_rcp_f32_e32 v184, v184
	v_rcp_f32_e32 v185, v185
	v_rcp_f32_e32 v186, v186
	v_rcp_f32_e32 v187, v187
	v_rcp_f32_e32 v188, v188
	v_rcp_f32_e32 v189, v189
	v_rcp_f32_e32 v190, v190
	v_mul_f32_e32 v160, v160, v183
	v_mul_f32_e32 v161, v161, v184
	v_mul_f32_e32 v162, v162, v185
	v_mul_f32_e32 v163, v163, v186
	v_mul_f32_e32 v164, v164, v187
	v_mul_f32_e32 v165, v165, v188
	v_mul_f32_e32 v180, v180, v189
	v_mul_f32_e32 v181, v181, v190
	v_mul_f32_e32 v52, v52, v160
	v_mul_f32_e32 v53, v53, v161
	v_mul_f32_e32 v54, v54, v162
	v_mul_f32_e32 v55, v55, v163
	v_mul_f32_e32 v48, v48, v164
	v_mul_f32_e32 v49, v49, v165
	v_mul_f32_e32 v50, v50, v180
	v_mul_f32_e32 v51, v51, v181
	s_waitcnt vmcnt(8)
	v_lshlrev_b32_e32 v160, 16, v200
	v_and_b32_e32 v161, 0xffff0000, v200
	v_lshlrev_b32_e32 v162, 16, v201
	v_and_b32_e32 v163, 0xffff0000, v201
	v_lshlrev_b32_e32 v164, 16, v202
	v_and_b32_e32 v165, 0xffff0000, v202
	v_lshlrev_b32_e32 v180, 16, v203
	v_and_b32_e32 v181, 0xffff0000, v203
	v_lshlrev_b32_e32 v183, 16, v216
	v_and_b32_e32 v184, 0xffff0000, v216
	v_lshlrev_b32_e32 v185, 16, v217
	v_and_b32_e32 v186, 0xffff0000, v217
	v_lshlrev_b32_e32 v187, 16, v218
	v_and_b32_e32 v188, 0xffff0000, v218
	v_lshlrev_b32_e32 v189, 16, v219
	v_and_b32_e32 v190, 0xffff0000, v219
	v_max_f32_e32 v160, v160, v147
	v_max_f32_e32 v161, v161, v147
	v_max_f32_e32 v162, v162, v147
	v_max_f32_e32 v163, v163, v147
	v_max_f32_e32 v164, v164, v147
	v_max_f32_e32 v165, v165, v147
	v_max_f32_e32 v180, v180, v147
	v_max_f32_e32 v181, v181, v147
	v_max_f32_e32 v183, v183, v147
	v_max_f32_e32 v184, v184, v147
	v_max_f32_e32 v185, v185, v147
	v_max_f32_e32 v186, v186, v147
	v_max_f32_e32 v187, v187, v147
	v_max_f32_e32 v188, v188, v147
	v_max_f32_e32 v189, v189, v147
	v_max_f32_e32 v190, v190, v147
	v_rcp_f32_e32 v183, v183
	v_rcp_f32_e32 v184, v184
	v_rcp_f32_e32 v185, v185
	v_rcp_f32_e32 v186, v186
	v_rcp_f32_e32 v187, v187
	v_rcp_f32_e32 v188, v188
	v_rcp_f32_e32 v189, v189
	v_rcp_f32_e32 v190, v190
	v_mul_f32_e32 v160, v160, v183
	v_mul_f32_e32 v161, v161, v184
	v_mul_f32_e32 v162, v162, v185
	v_mul_f32_e32 v163, v163, v186
	v_mul_f32_e32 v164, v164, v187
	v_mul_f32_e32 v165, v165, v188
	v_mul_f32_e32 v180, v180, v189
	v_mul_f32_e32 v181, v181, v190
	v_mul_f32_e32 v44, v44, v160
	v_mul_f32_e32 v45, v45, v161
	v_mul_f32_e32 v46, v46, v162
	v_mul_f32_e32 v47, v47, v163
	v_mul_f32_e32 v40, v40, v164
	v_mul_f32_e32 v41, v41, v165
	v_mul_f32_e32 v42, v42, v180
	v_mul_f32_e32 v43, v43, v181
	s_waitcnt vmcnt(6)
	v_lshlrev_b32_e32 v160, 16, v220
	v_and_b32_e32 v161, 0xffff0000, v220
	v_lshlrev_b32_e32 v162, 16, v221
	v_and_b32_e32 v163, 0xffff0000, v221
	v_lshlrev_b32_e32 v164, 16, v222
	v_and_b32_e32 v165, 0xffff0000, v222
	v_lshlrev_b32_e32 v180, 16, v223
	v_and_b32_e32 v181, 0xffff0000, v223
	v_lshlrev_b32_e32 v183, 16, v224
	v_and_b32_e32 v184, 0xffff0000, v224
	v_lshlrev_b32_e32 v185, 16, v225
	v_and_b32_e32 v186, 0xffff0000, v225
	v_lshlrev_b32_e32 v187, 16, v226
	v_and_b32_e32 v188, 0xffff0000, v226
	v_lshlrev_b32_e32 v189, 16, v227
	v_and_b32_e32 v190, 0xffff0000, v227
	v_max_f32_e32 v160, v160, v147
	v_max_f32_e32 v161, v161, v147
	v_max_f32_e32 v162, v162, v147
	v_max_f32_e32 v163, v163, v147
	v_max_f32_e32 v164, v164, v147
	v_max_f32_e32 v165, v165, v147
	v_max_f32_e32 v180, v180, v147
	v_max_f32_e32 v181, v181, v147
	v_max_f32_e32 v183, v183, v147
	v_max_f32_e32 v184, v184, v147
	v_max_f32_e32 v185, v185, v147
	v_max_f32_e32 v186, v186, v147
	v_max_f32_e32 v187, v187, v147
	v_max_f32_e32 v188, v188, v147
	v_max_f32_e32 v189, v189, v147
	v_max_f32_e32 v190, v190, v147
	v_rcp_f32_e32 v183, v183
	v_rcp_f32_e32 v184, v184
	v_rcp_f32_e32 v185, v185
	v_rcp_f32_e32 v186, v186
	v_rcp_f32_e32 v187, v187
	v_rcp_f32_e32 v188, v188
	v_rcp_f32_e32 v189, v189
	v_rcp_f32_e32 v190, v190
	v_mul_f32_e32 v160, v160, v183
	v_mul_f32_e32 v161, v161, v184
	v_mul_f32_e32 v162, v162, v185
	v_mul_f32_e32 v163, v163, v186
	v_mul_f32_e32 v164, v164, v187
	v_mul_f32_e32 v165, v165, v188
	v_mul_f32_e32 v180, v180, v189
	v_mul_f32_e32 v181, v181, v190
	v_mul_f32_e32 v36, v36, v160
	v_mul_f32_e32 v37, v37, v161
	v_mul_f32_e32 v38, v38, v162
	v_mul_f32_e32 v39, v39, v163
	v_mul_f32_e32 v32, v32, v164
	v_mul_f32_e32 v33, v33, v165
	v_mul_f32_e32 v34, v34, v180
	v_mul_f32_e32 v35, v35, v181
	s_waitcnt vmcnt(4)
	v_lshlrev_b32_e32 v160, 16, v228
	v_and_b32_e32 v161, 0xffff0000, v228
	v_lshlrev_b32_e32 v162, 16, v229
	v_and_b32_e32 v163, 0xffff0000, v229
	v_lshlrev_b32_e32 v164, 16, v230
	v_and_b32_e32 v165, 0xffff0000, v230
	v_lshlrev_b32_e32 v180, 16, v231
	v_and_b32_e32 v181, 0xffff0000, v231
	v_lshlrev_b32_e32 v183, 16, v232
	v_and_b32_e32 v184, 0xffff0000, v232
	v_lshlrev_b32_e32 v185, 16, v233
	v_and_b32_e32 v186, 0xffff0000, v233
	v_lshlrev_b32_e32 v187, 16, v234
	v_and_b32_e32 v188, 0xffff0000, v234
	v_lshlrev_b32_e32 v189, 16, v235
	v_and_b32_e32 v190, 0xffff0000, v235
	v_max_f32_e32 v160, v160, v147
	v_max_f32_e32 v161, v161, v147
	v_max_f32_e32 v162, v162, v147
	v_max_f32_e32 v163, v163, v147
	v_max_f32_e32 v164, v164, v147
	v_max_f32_e32 v165, v165, v147
	v_max_f32_e32 v180, v180, v147
	v_max_f32_e32 v181, v181, v147
	v_max_f32_e32 v183, v183, v147
	v_max_f32_e32 v184, v184, v147
	v_max_f32_e32 v185, v185, v147
	v_max_f32_e32 v186, v186, v147
	v_max_f32_e32 v187, v187, v147
	v_max_f32_e32 v188, v188, v147
	v_max_f32_e32 v189, v189, v147
	v_max_f32_e32 v190, v190, v147
	v_rcp_f32_e32 v183, v183
	v_rcp_f32_e32 v184, v184
	v_rcp_f32_e32 v185, v185
	v_rcp_f32_e32 v186, v186
	v_rcp_f32_e32 v187, v187
	v_rcp_f32_e32 v188, v188
	v_rcp_f32_e32 v189, v189
	v_rcp_f32_e32 v190, v190
	v_mul_f32_e32 v160, v160, v183
	v_mul_f32_e32 v161, v161, v184
	v_mul_f32_e32 v162, v162, v185
	v_mul_f32_e32 v163, v163, v186
	v_mul_f32_e32 v164, v164, v187
	v_mul_f32_e32 v165, v165, v188
	v_mul_f32_e32 v180, v180, v189
	v_mul_f32_e32 v181, v181, v190
	v_mul_f32_e32 v28, v28, v160
	v_mul_f32_e32 v29, v29, v161
	v_mul_f32_e32 v30, v30, v162
	v_mul_f32_e32 v31, v31, v163
	v_mul_f32_e32 v24, v24, v164
	v_mul_f32_e32 v25, v25, v165
	v_mul_f32_e32 v26, v26, v180
	v_mul_f32_e32 v27, v27, v181
	s_waitcnt vmcnt(2)
	v_lshlrev_b32_e32 v160, 16, v236
	v_and_b32_e32 v161, 0xffff0000, v236
	v_lshlrev_b32_e32 v162, 16, v237
	v_and_b32_e32 v163, 0xffff0000, v237
	v_lshlrev_b32_e32 v164, 16, v238
	v_and_b32_e32 v165, 0xffff0000, v238
	v_lshlrev_b32_e32 v180, 16, v239
	v_and_b32_e32 v181, 0xffff0000, v239
	v_lshlrev_b32_e32 v183, 16, v240
	v_and_b32_e32 v184, 0xffff0000, v240
	v_lshlrev_b32_e32 v185, 16, v241
	v_and_b32_e32 v186, 0xffff0000, v241
	v_lshlrev_b32_e32 v187, 16, v242
	v_and_b32_e32 v188, 0xffff0000, v242
	v_lshlrev_b32_e32 v189, 16, v243
	v_and_b32_e32 v190, 0xffff0000, v243
	v_max_f32_e32 v160, v160, v147
	v_max_f32_e32 v161, v161, v147
	v_max_f32_e32 v162, v162, v147
	v_max_f32_e32 v163, v163, v147
	v_max_f32_e32 v164, v164, v147
	v_max_f32_e32 v165, v165, v147
	v_max_f32_e32 v180, v180, v147
	v_max_f32_e32 v181, v181, v147
	v_max_f32_e32 v183, v183, v147
	v_max_f32_e32 v184, v184, v147
	v_max_f32_e32 v185, v185, v147
	v_max_f32_e32 v186, v186, v147
	v_max_f32_e32 v187, v187, v147
	v_max_f32_e32 v188, v188, v147
	v_max_f32_e32 v189, v189, v147
	v_max_f32_e32 v190, v190, v147
	v_rcp_f32_e32 v183, v183
	v_rcp_f32_e32 v184, v184
	v_rcp_f32_e32 v185, v185
	v_rcp_f32_e32 v186, v186
	v_rcp_f32_e32 v187, v187
	v_rcp_f32_e32 v188, v188
	v_rcp_f32_e32 v189, v189
	v_rcp_f32_e32 v190, v190
	v_mul_f32_e32 v160, v160, v183
	v_mul_f32_e32 v161, v161, v184
	v_mul_f32_e32 v162, v162, v185
	v_mul_f32_e32 v163, v163, v186
	v_mul_f32_e32 v164, v164, v187
	v_mul_f32_e32 v165, v165, v188
	v_mul_f32_e32 v180, v180, v189
	v_mul_f32_e32 v181, v181, v190
	v_mul_f32_e32 v20, v20, v160
	v_mul_f32_e32 v21, v21, v161
	v_mul_f32_e32 v22, v22, v162
	v_mul_f32_e32 v23, v23, v163
	v_mul_f32_e32 v16, v16, v164
	v_mul_f32_e32 v17, v17, v165
	v_mul_f32_e32 v18, v18, v180
	v_mul_f32_e32 v19, v19, v181
	s_waitcnt vmcnt(0)
	v_lshlrev_b32_e32 v160, 16, v192
	v_and_b32_e32 v161, 0xffff0000, v192
	v_lshlrev_b32_e32 v162, 16, v193
	v_and_b32_e32 v163, 0xffff0000, v193
	v_lshlrev_b32_e32 v164, 16, v194
	v_and_b32_e32 v165, 0xffff0000, v194
	v_lshlrev_b32_e32 v180, 16, v195
	v_and_b32_e32 v181, 0xffff0000, v195
	v_lshlrev_b32_e32 v183, 16, v196
	v_and_b32_e32 v184, 0xffff0000, v196
	v_lshlrev_b32_e32 v185, 16, v197
	v_and_b32_e32 v186, 0xffff0000, v197
	v_lshlrev_b32_e32 v187, 16, v198
	v_and_b32_e32 v188, 0xffff0000, v198
	v_lshlrev_b32_e32 v189, 16, v199
	v_and_b32_e32 v190, 0xffff0000, v199
	v_max_f32_e32 v160, v160, v147
	v_max_f32_e32 v161, v161, v147
	v_max_f32_e32 v162, v162, v147
	v_max_f32_e32 v163, v163, v147
	v_max_f32_e32 v164, v164, v147
	v_max_f32_e32 v165, v165, v147
	v_max_f32_e32 v180, v180, v147
	v_max_f32_e32 v181, v181, v147
	v_max_f32_e32 v183, v183, v147
	v_max_f32_e32 v184, v184, v147
	v_max_f32_e32 v185, v185, v147
	v_max_f32_e32 v186, v186, v147
	v_max_f32_e32 v187, v187, v147
	v_max_f32_e32 v188, v188, v147
	v_max_f32_e32 v189, v189, v147
	v_max_f32_e32 v190, v190, v147
	v_rcp_f32_e32 v183, v183
	v_rcp_f32_e32 v184, v184
	v_rcp_f32_e32 v185, v185
	v_rcp_f32_e32 v186, v186
	v_rcp_f32_e32 v187, v187
	v_rcp_f32_e32 v188, v188
	v_rcp_f32_e32 v189, v189
	v_rcp_f32_e32 v190, v190
	v_mul_f32_e32 v160, v160, v183
	v_mul_f32_e32 v161, v161, v184
	v_mul_f32_e32 v162, v162, v185
	v_mul_f32_e32 v163, v163, v186
	v_mul_f32_e32 v164, v164, v187
	v_mul_f32_e32 v165, v165, v188
	v_mul_f32_e32 v180, v180, v189
	v_mul_f32_e32 v181, v181, v190
	v_mul_f32_e32 v12, v12, v160
	v_mul_f32_e32 v13, v13, v161
	v_mul_f32_e32 v14, v14, v162
	v_mul_f32_e32 v15, v15, v163
	v_mul_f32_e32 v8, v8, v164
	v_mul_f32_e32 v9, v9, v165
	v_mul_f32_e32 v10, v10, v180
	v_mul_f32_e32 v11, v11, v181
	v_mov_b32_e32 v214, v8
	v_mov_b32_e32 v215, v9
	v_mov_b32_e32 v216, v10
	v_mov_b32_e32 v217, v11
	v_mov_b32_e32 v218, v12
	v_mov_b32_e32 v219, v13
	v_mov_b32_e32 v220, v14
	v_mov_b32_e32 v221, v15
	v_mov_b32_e32 v222, v16
	v_mov_b32_e32 v223, v17
	v_mov_b32_e32 v224, v18
	v_mov_b32_e32 v225, v19
	v_mov_b32_e32 v226, v20
	v_mov_b32_e32 v227, v21
	v_mov_b32_e32 v228, v22
	v_mov_b32_e32 v229, v23
	v_mov_b32_e32 v230, v24
	v_mov_b32_e32 v231, v25
	v_mov_b32_e32 v232, v26
	s_mov_b64 s[48:49], 0x4000
	s_mov_b64 s[46:47], 0x8000
	s_mov_b32 s9, 0x58000
	s_mov_b64 s[16:17], -1
	s_andn2_b64 vcc, exec, s[44:45]
	s_cbranch_vccnz .LBB0_855
	s_andn2_b64 vcc, exec, s[0:1]
	s_cbranch_vccnz .LBB0_854
	s_barrier
	s_branch .LBB0_854

.LBB0_886:
	v_and_b32_e32 v160, 63, v206
	v_lshrrev_b32_e32 v161, 6, v206
	v_and_b32_e32 v162, 15, v160
	v_readfirstlane_b32 s18, v161
	v_lshrrev_b32_e32 v163, 4, v160
	s_nop 3
	s_and_b32 s19, s18, 3
	s_lshl_b32 s19, s19, 5
	s_lshl_b32 s11, s33, 8
	s_add_i32 s19, s19, s11
	v_lshl_add_u32 v164, v163, 3, s19
	s_lshr_b32 s19, s18, 2
	s_lshl_b32 s19, s19, 6
	s_lshl_b32 s11, s38, 8
	s_add_i32 s11, s11, s19
	v_add_u32_e32 v165, s11, v162
	v_lshlrev_b32_e32 v146, 11, v165
	v_lshl_add_u32 v146, v164, 1, v146
	s_add_u32 s46, s70, 0xd400000
	s_addc_u32 s47, s71, 0
	s_add_u32 s48, s70, 0x15800000
	s_addc_u32 s49, s71, 0
	v_mov_b32_e32 v147, 0x21800000
	v_mov_b32_e32 v172, v146
	v_add_u32_e32 v173, 0x8000, v146
	v_add_u32_e32 v174, 0x10000, v146
	v_add_u32_e32 v175, 0x18000, v146
	v_add_u32_e32 v176, 0x40000, v146
	v_add_u32_e32 v177, 0x48000, v146
	v_add_u32_e32 v178, 0x50000, v146
	v_add_u32_e32 v179, 0x58000, v146
	global_load_dwordx4 v[192:195], v172, s[46:47]
	global_load_dwordx4 v[196:199], v172, s[46:47] offset:256
	global_load_dwordx4 v[200:203], v173, s[46:47]
	global_load_dwordx4 v[216:219], v173, s[46:47] offset:256
	global_load_dwordx4 v[220:223], v174, s[46:47]
	global_load_dwordx4 v[224:227], v174, s[46:47] offset:256
	global_load_dwordx4 v[228:231], v175, s[46:47]
	global_load_dwordx4 v[232:235], v175, s[46:47] offset:256
	global_load_dwordx4 v[236:239], v176, s[46:47]
	global_load_dwordx4 v[240:243], v176, s[46:47] offset:256
	global_load_dwordx4 v[244:247], v177, s[46:47]
	s_waitcnt vmcnt(10)
	v_lshlrev_b32_e32 v160, 16, v192
	v_and_b32_e32 v161, 0xffff0000, v192
	v_lshlrev_b32_e32 v162, 16, v193
	v_and_b32_e32 v163, 0xffff0000, v193
	v_lshlrev_b32_e32 v164, 16, v194
	v_and_b32_e32 v165, 0xffff0000, v194
	v_lshlrev_b32_e32 v180, 16, v195
	v_and_b32_e32 v181, 0xffff0000, v195
	global_load_dwordx4 v[192:195], v177, s[46:47] offset:256
	v_max_f32_e32 v160, v160, v147
	v_max_f32_e32 v161, v161, v147
	v_max_f32_e32 v162, v162, v147
	v_max_f32_e32 v163, v163, v147
	v_max_f32_e32 v164, v164, v147
	v_max_f32_e32 v165, v165, v147
	v_max_f32_e32 v180, v180, v147
	v_max_f32_e32 v181, v181, v147
	v_mul_f32_e32 v132, v132, v160
	v_mul_f32_e32 v133, v133, v161
	v_mul_f32_e32 v134, v134, v162
	v_mul_f32_e32 v135, v135, v163
	v_mul_f32_e32 v128, v128, v164
	v_mul_f32_e32 v129, v129, v165
	v_mul_f32_e32 v130, v130, v180
	v_mul_f32_e32 v131, v131, v181
	v_cvt_pk_bf16_f32 v184, v132, v133
	v_cvt_pk_bf16_f32 v185, v134, v135
	v_cvt_pk_bf16_f32 v186, v128, v129
	v_cvt_pk_bf16_f32 v187, v130, v131
	global_store_dwordx4 v172, v[184:187], s[48:49]
	s_waitcnt vmcnt(11)
	v_lshlrev_b32_e32 v160, 16, v196
	v_and_b32_e32 v161, 0xffff0000, v196
	v_lshlrev_b32_e32 v162, 16, v197
	v_and_b32_e32 v163, 0xffff0000, v197
	v_lshlrev_b32_e32 v164, 16, v198
	v_and_b32_e32 v165, 0xffff0000, v198
	v_lshlrev_b32_e32 v180, 16, v199
	v_and_b32_e32 v181, 0xffff0000, v199
	global_load_dwordx4 v[196:199], v178, s[46:47]
	v_max_f32_e32 v160, v160, v147
	v_max_f32_e32 v161, v161, v147
	v_max_f32_e32 v162, v162, v147
	v_max_f32_e32 v163, v163, v147
	v_max_f32_e32 v164, v164, v147
	v_max_f32_e32 v165, v165, v147
	v_max_f32_e32 v180, v180, v147
	v_max_f32_e32 v181, v181, v147
	v_mul_f32_e32 v124, v124, v160
	v_mul_f32_e32 v125, v125, v161
	v_mul_f32_e32 v126, v126, v162
	v_mul_f32_e32 v127, v127, v163
	v_mul_f32_e32 v120, v120, v164
	v_mul_f32_e32 v121, v121, v165
	v_mul_f32_e32 v122, v122, v180
	v_mul_f32_e32 v123, v123, v181
	v_cvt_pk_bf16_f32 v188, v124, v125
	v_cvt_pk_bf16_f32 v189, v126, v127
	v_cvt_pk_bf16_f32 v190, v120, v121
	v_cvt_pk_bf16_f32 v191, v122, v123
	global_store_dwordx4 v172, v[188:191], s[48:49] offset:256
	s_waitcnt vmcnt(12)
	v_lshlrev_b32_e32 v160, 16, v200
	v_and_b32_e32 v161, 0xffff0000, v200
	v_lshlrev_b32_e32 v162, 16, v201
	v_and_b32_e32 v163, 0xffff0000, v201
	v_lshlrev_b32_e32 v164, 16, v202
	v_and_b32_e32 v165, 0xffff0000, v202
	v_lshlrev_b32_e32 v180, 16, v203
	v_and_b32_e32 v181, 0xffff0000, v203
	global_load_dwordx4 v[200:203], v178, s[46:47] offset:256
	v_max_f32_e32 v160, v160, v147
	v_max_f32_e32 v161, v161, v147
	v_max_f32_e32 v162, v162, v147
	v_max_f32_e32 v163, v163, v147
	v_max_f32_e32 v164, v164, v147
	v_max_f32_e32 v165, v165, v147
	v_max_f32_e32 v180, v180, v147
	v_max_f32_e32 v181, v181, v147
	v_mul_f32_e32 v116, v116, v160
	v_mul_f32_e32 v117, v117, v161
	v_mul_f32_e32 v118, v118, v162
	v_mul_f32_e32 v119, v119, v163
	v_mul_f32_e32 v112, v112, v164
	v_mul_f32_e32 v113, v113, v165
	v_mul_f32_e32 v114, v114, v180
	v_mul_f32_e32 v115, v115, v181
	v_cvt_pk_bf16_f32 v184, v116, v117
	v_cvt_pk_bf16_f32 v185, v118, v119
	v_cvt_pk_bf16_f32 v186, v112, v113
	v_cvt_pk_bf16_f32 v187, v114, v115
	global_store_dwordx4 v173, v[184:187], s[48:49]
	s_waitcnt vmcnt(13)
	v_lshlrev_b32_e32 v160, 16, v216
	v_and_b32_e32 v161, 0xffff0000, v216
	v_lshlrev_b32_e32 v162, 16, v217
	v_and_b32_e32 v163, 0xffff0000, v217
	v_lshlrev_b32_e32 v164, 16, v218
	v_and_b32_e32 v165, 0xffff0000, v218
	v_lshlrev_b32_e32 v180, 16, v219
	v_and_b32_e32 v181, 0xffff0000, v219
	global_load_dwordx4 v[216:219], v179, s[46:47]
	v_max_f32_e32 v160, v160, v147
	v_max_f32_e32 v161, v161, v147
	v_max_f32_e32 v162, v162, v147
	v_max_f32_e32 v163, v163, v147
	v_max_f32_e32 v164, v164, v147
	v_max_f32_e32 v165, v165, v147
	v_max_f32_e32 v180, v180, v147
	v_max_f32_e32 v181, v181, v147
	v_mul_f32_e32 v108, v108, v160
	v_mul_f32_e32 v109, v109, v161
	v_mul_f32_e32 v110, v110, v162
	v_mul_f32_e32 v111, v111, v163
	v_mul_f32_e32 v104, v104, v164
	v_mul_f32_e32 v105, v105, v165
	v_mul_f32_e32 v106, v106, v180
	v_mul_f32_e32 v107, v107, v181
	v_cvt_pk_bf16_f32 v188, v108, v109
	v_cvt_pk_bf16_f32 v189, v110, v111
	v_cvt_pk_bf16_f32 v190, v104, v105
	v_cvt_pk_bf16_f32 v191, v106, v107
	global_store_dwordx4 v173, v[188:191], s[48:49] offset:256
	s_waitcnt vmcnt(14)
	v_lshlrev_b32_e32 v160, 16, v220
	v_and_b32_e32 v161, 0xffff0000, v220
	v_lshlrev_b32_e32 v162, 16, v221
	v_and_b32_e32 v163, 0xffff0000, v221
	v_lshlrev_b32_e32 v164, 16, v222
	v_and_b32_e32 v165, 0xffff0000, v222
	v_lshlrev_b32_e32 v180, 16, v223
	v_and_b32_e32 v181, 0xffff0000, v223
	global_load_dwordx4 v[220:223], v179, s[46:47] offset:256
	v_max_f32_e32 v160, v160, v147
	v_max_f32_e32 v161, v161, v147
	v_max_f32_e32 v162, v162, v147
	v_max_f32_e32 v163, v163, v147
	v_max_f32_e32 v164, v164, v147
	v_max_f32_e32 v165, v165, v147
	v_max_f32_e32 v180, v180, v147
	v_max_f32_e32 v181, v181, v147
	v_mul_f32_e32 v100, v100, v160
	v_mul_f32_e32 v101, v101, v161
	v_mul_f32_e32 v102, v102, v162
	v_mul_f32_e32 v103, v103, v163
	v_mul_f32_e32 v96, v96, v164
	v_mul_f32_e32 v97, v97, v165
	v_mul_f32_e32 v98, v98, v180
	v_mul_f32_e32 v99, v99, v181
	v_cvt_pk_bf16_f32 v184, v100, v101
	v_cvt_pk_bf16_f32 v185, v102, v103
	v_cvt_pk_bf16_f32 v186, v96, v97
	v_cvt_pk_bf16_f32 v187, v98, v99
	global_store_dwordx4 v174, v[184:187], s[48:49]
	s_waitcnt vmcnt(15)
	v_lshlrev_b32_e32 v160, 16, v224
	v_and_b32_e32 v161, 0xffff0000, v224
	v_lshlrev_b32_e32 v162, 16, v225
	v_and_b32_e32 v163, 0xffff0000, v225
	v_lshlrev_b32_e32 v164, 16, v226
	v_and_b32_e32 v165, 0xffff0000, v226
	v_lshlrev_b32_e32 v180, 16, v227
	v_and_b32_e32 v181, 0xffff0000, v227
	v_max_f32_e32 v160, v160, v147
	v_max_f32_e32 v161, v161, v147
	v_max_f32_e32 v162, v162, v147
	v_max_f32_e32 v163, v163, v147
	v_max_f32_e32 v164, v164, v147
	v_max_f32_e32 v165, v165, v147
	v_max_f32_e32 v180, v180, v147
	v_max_f32_e32 v181, v181, v147
	v_mul_f32_e32 v92, v92, v160
	v_mul_f32_e32 v93, v93, v161
	v_mul_f32_e32 v94, v94, v162
	v_mul_f32_e32 v95, v95, v163
	v_mul_f32_e32 v88, v88, v164
	v_mul_f32_e32 v89, v89, v165
	v_mul_f32_e32 v90, v90, v180
	v_mul_f32_e32 v91, v91, v181
	v_cvt_pk_bf16_f32 v188, v92, v93
	v_cvt_pk_bf16_f32 v189, v94, v95
	v_cvt_pk_bf16_f32 v190, v88, v89
	v_cvt_pk_bf16_f32 v191, v90, v91
	global_store_dwordx4 v174, v[188:191], s[48:49] offset:256
	s_waitcnt vmcnt(15)
	v_lshlrev_b32_e32 v160, 16, v228
	v_and_b32_e32 v161, 0xffff0000, v228
	v_lshlrev_b32_e32 v162, 16, v229
	v_and_b32_e32 v163, 0xffff0000, v229
	v_lshlrev_b32_e32 v164, 16, v230
	v_and_b32_e32 v165, 0xffff0000, v230
	v_lshlrev_b32_e32 v180, 16, v231
	v_and_b32_e32 v181, 0xffff0000, v231
	v_max_f32_e32 v160, v160, v147
	v_max_f32_e32 v161, v161, v147
	v_max_f32_e32 v162, v162, v147
	v_max_f32_e32 v163, v163, v147
	v_max_f32_e32 v164, v164, v147
	v_max_f32_e32 v165, v165, v147
	v_max_f32_e32 v180, v180, v147
	v_max_f32_e32 v181, v181, v147
	v_mul_f32_e32 v84, v84, v160
	v_mul_f32_e32 v85, v85, v161
	v_mul_f32_e32 v86, v86, v162
	v_mul_f32_e32 v87, v87, v163
	v_mul_f32_e32 v80, v80, v164
	v_mul_f32_e32 v81, v81, v165
	v_mul_f32_e32 v82, v82, v180
	v_mul_f32_e32 v83, v83, v181
	v_cvt_pk_bf16_f32 v184, v84, v85
	v_cvt_pk_bf16_f32 v185, v86, v87
	v_cvt_pk_bf16_f32 v186, v80, v81
	v_cvt_pk_bf16_f32 v187, v82, v83
	global_store_dwordx4 v175, v[184:187], s[48:49]
	s_waitcnt vmcnt(15)
	v_lshlrev_b32_e32 v160, 16, v232
	v_and_b32_e32 v161, 0xffff0000, v232
	v_lshlrev_b32_e32 v162, 16, v233
	v_and_b32_e32 v163, 0xffff0000, v233
	v_lshlrev_b32_e32 v164, 16, v234
	v_and_b32_e32 v165, 0xffff0000, v234
	v_lshlrev_b32_e32 v180, 16, v235
	v_and_b32_e32 v181, 0xffff0000, v235
	v_max_f32_e32 v160, v160, v147
	v_max_f32_e32 v161, v161, v147
	v_max_f32_e32 v162, v162, v147
	v_max_f32_e32 v163, v163, v147
	v_max_f32_e32 v164, v164, v147
	v_max_f32_e32 v165, v165, v147
	v_max_f32_e32 v180, v180, v147
	v_max_f32_e32 v181, v181, v147
	v_mul_f32_e32 v76, v76, v160
	v_mul_f32_e32 v77, v77, v161
	v_mul_f32_e32 v78, v78, v162
	v_mul_f32_e32 v79, v79, v163
	v_mul_f32_e32 v72, v72, v164
	v_mul_f32_e32 v73, v73, v165
	v_mul_f32_e32 v74, v74, v180
	v_mul_f32_e32 v75, v75, v181
	v_cvt_pk_bf16_f32 v188, v76, v77
	v_cvt_pk_bf16_f32 v189, v78, v79
	v_cvt_pk_bf16_f32 v190, v72, v73
	v_cvt_pk_bf16_f32 v191, v74, v75
	global_store_dwordx4 v175, v[188:191], s[48:49] offset:256
	s_waitcnt vmcnt(15)
	v_lshlrev_b32_e32 v160, 16, v236
	v_and_b32_e32 v161, 0xffff0000, v236
	v_lshlrev_b32_e32 v162, 16, v237
	v_and_b32_e32 v163, 0xffff0000, v237
	v_lshlrev_b32_e32 v164, 16, v238
	v_and_b32_e32 v165, 0xffff0000, v238
	v_lshlrev_b32_e32 v180, 16, v239
	v_and_b32_e32 v181, 0xffff0000, v239
	v_max_f32_e32 v160, v160, v147
	v_max_f32_e32 v161, v161, v147
	v_max_f32_e32 v162, v162, v147
	v_max_f32_e32 v163, v163, v147
	v_max_f32_e32 v164, v164, v147
	v_max_f32_e32 v165, v165, v147
	v_max_f32_e32 v180, v180, v147
	v_max_f32_e32 v181, v181, v147
	v_mul_f32_e32 v68, v68, v160
	v_mul_f32_e32 v69, v69, v161
	v_mul_f32_e32 v70, v70, v162
	v_mul_f32_e32 v71, v71, v163
	v_mul_f32_e32 v64, v64, v164
	v_mul_f32_e32 v65, v65, v165
	v_mul_f32_e32 v66, v66, v180
	v_mul_f32_e32 v67, v67, v181
	v_cvt_pk_bf16_f32 v184, v68, v69
	v_cvt_pk_bf16_f32 v185, v70, v71
	v_cvt_pk_bf16_f32 v186, v64, v65
	v_cvt_pk_bf16_f32 v187, v66, v67
	global_store_dwordx4 v176, v[184:187], s[48:49]
	s_waitcnt vmcnt(15)
	v_lshlrev_b32_e32 v160, 16, v240
	v_and_b32_e32 v161, 0xffff0000, v240
	v_lshlrev_b32_e32 v162, 16, v241
	v_and_b32_e32 v163, 0xffff0000, v241
	v_lshlrev_b32_e32 v164, 16, v242
	v_and_b32_e32 v165, 0xffff0000, v242
	v_lshlrev_b32_e32 v180, 16, v243
	v_and_b32_e32 v181, 0xffff0000, v243
	v_max_f32_e32 v160, v160, v147
	v_max_f32_e32 v161, v161, v147
	v_max_f32_e32 v162, v162, v147
	v_max_f32_e32 v163, v163, v147
	v_max_f32_e32 v164, v164, v147
	v_max_f32_e32 v165, v165, v147
	v_max_f32_e32 v180, v180, v147
	v_max_f32_e32 v181, v181, v147
	v_mul_f32_e32 v60, v60, v160
	v_mul_f32_e32 v61, v61, v161
	v_mul_f32_e32 v62, v62, v162
	v_mul_f32_e32 v63, v63, v163
	v_mul_f32_e32 v56, v56, v164
	v_mul_f32_e32 v57, v57, v165
	v_mul_f32_e32 v58, v58, v180
	v_mul_f32_e32 v59, v59, v181
	v_cvt_pk_bf16_f32 v188, v60, v61
	v_cvt_pk_bf16_f32 v189, v62, v63
	v_cvt_pk_bf16_f32 v190, v56, v57
	v_cvt_pk_bf16_f32 v191, v58, v59
	global_store_dwordx4 v176, v[188:191], s[48:49] offset:256
	s_waitcnt vmcnt(15)
	v_lshlrev_b32_e32 v160, 16, v244
	v_and_b32_e32 v161, 0xffff0000, v244
	v_lshlrev_b32_e32 v162, 16, v245
	v_and_b32_e32 v163, 0xffff0000, v245
	v_lshlrev_b32_e32 v164, 16, v246
	v_and_b32_e32 v165, 0xffff0000, v246
	v_lshlrev_b32_e32 v180, 16, v247
	v_and_b32_e32 v181, 0xffff0000, v247
	v_max_f32_e32 v160, v160, v147
	v_max_f32_e32 v161, v161, v147
	v_max_f32_e32 v162, v162, v147
	v_max_f32_e32 v163, v163, v147
	v_max_f32_e32 v164, v164, v147
	v_max_f32_e32 v165, v165, v147
	v_max_f32_e32 v180, v180, v147
	v_max_f32_e32 v181, v181, v147
	v_mul_f32_e32 v52, v52, v160
	v_mul_f32_e32 v53, v53, v161
	v_mul_f32_e32 v54, v54, v162
	v_mul_f32_e32 v55, v55, v163
	v_mul_f32_e32 v48, v48, v164
	v_mul_f32_e32 v49, v49, v165
	v_mul_f32_e32 v50, v50, v180
	v_mul_f32_e32 v51, v51, v181
	v_cvt_pk_bf16_f32 v184, v52, v53
	v_cvt_pk_bf16_f32 v185, v54, v55
	v_cvt_pk_bf16_f32 v186, v48, v49
	v_cvt_pk_bf16_f32 v187, v50, v51
	global_store_dwordx4 v177, v[184:187], s[48:49]
	s_waitcnt vmcnt(15)
	v_lshlrev_b32_e32 v160, 16, v192
	v_and_b32_e32 v161, 0xffff0000, v192
	v_lshlrev_b32_e32 v162, 16, v193
	v_and_b32_e32 v163, 0xffff0000, v193
	v_lshlrev_b32_e32 v164, 16, v194
	v_and_b32_e32 v165, 0xffff0000, v194
	v_lshlrev_b32_e32 v180, 16, v195
	v_and_b32_e32 v181, 0xffff0000, v195
	v_max_f32_e32 v160, v160, v147
	v_max_f32_e32 v161, v161, v147
	v_max_f32_e32 v162, v162, v147
	v_max_f32_e32 v163, v163, v147
	v_max_f32_e32 v164, v164, v147
	v_max_f32_e32 v165, v165, v147
	v_max_f32_e32 v180, v180, v147
	v_max_f32_e32 v181, v181, v147
	v_mul_f32_e32 v44, v44, v160
	v_mul_f32_e32 v45, v45, v161
	v_mul_f32_e32 v46, v46, v162
	v_mul_f32_e32 v47, v47, v163
	v_mul_f32_e32 v40, v40, v164
	v_mul_f32_e32 v41, v41, v165
	v_mul_f32_e32 v42, v42, v180
	v_mul_f32_e32 v43, v43, v181
	v_cvt_pk_bf16_f32 v188, v44, v45
	v_cvt_pk_bf16_f32 v189, v46, v47
	v_cvt_pk_bf16_f32 v190, v40, v41
	v_cvt_pk_bf16_f32 v191, v42, v43
	global_store_dwordx4 v177, v[188:191], s[48:49] offset:256
	s_waitcnt vmcnt(14)
	v_lshlrev_b32_e32 v160, 16, v196
	v_and_b32_e32 v161, 0xffff0000, v196
	v_lshlrev_b32_e32 v162, 16, v197
	v_and_b32_e32 v163, 0xffff0000, v197
	v_lshlrev_b32_e32 v164, 16, v198
	v_and_b32_e32 v165, 0xffff0000, v198
	v_lshlrev_b32_e32 v180, 16, v199
	v_and_b32_e32 v181, 0xffff0000, v199
	v_max_f32_e32 v160, v160, v147
	v_max_f32_e32 v161, v161, v147
	v_max_f32_e32 v162, v162, v147
	v_max_f32_e32 v163, v163, v147
	v_max_f32_e32 v164, v164, v147
	v_max_f32_e32 v165, v165, v147
	v_max_f32_e32 v180, v180, v147
	v_max_f32_e32 v181, v181, v147
	v_mul_f32_e32 v36, v36, v160
	v_mul_f32_e32 v37, v37, v161
	v_mul_f32_e32 v38, v38, v162
	v_mul_f32_e32 v39, v39, v163
	v_mul_f32_e32 v32, v32, v164
	v_mul_f32_e32 v33, v33, v165
	v_mul_f32_e32 v34, v34, v180
	v_mul_f32_e32 v35, v35, v181
	v_cvt_pk_bf16_f32 v184, v36, v37
	v_cvt_pk_bf16_f32 v185, v38, v39
	v_cvt_pk_bf16_f32 v186, v32, v33
	v_cvt_pk_bf16_f32 v187, v34, v35
	global_store_dwordx4 v178, v[184:187], s[48:49]
	s_waitcnt vmcnt(13)
	v_lshlrev_b32_e32 v160, 16, v200
	v_and_b32_e32 v161, 0xffff0000, v200
	v_lshlrev_b32_e32 v162, 16, v201
	v_and_b32_e32 v163, 0xffff0000, v201
	v_lshlrev_b32_e32 v164, 16, v202
	v_and_b32_e32 v165, 0xffff0000, v202
	v_lshlrev_b32_e32 v180, 16, v203
	v_and_b32_e32 v181, 0xffff0000, v203
	v_max_f32_e32 v160, v160, v147
	v_max_f32_e32 v161, v161, v147
	v_max_f32_e32 v162, v162, v147
	v_max_f32_e32 v163, v163, v147
	v_max_f32_e32 v164, v164, v147
	v_max_f32_e32 v165, v165, v147
	v_max_f32_e32 v180, v180, v147
	v_max_f32_e32 v181, v181, v147
	v_mul_f32_e32 v28, v28, v160
	v_mul_f32_e32 v29, v29, v161
	v_mul_f32_e32 v30, v30, v162
	v_mul_f32_e32 v31, v31, v163
	v_mul_f32_e32 v24, v24, v164
	v_mul_f32_e32 v25, v25, v165
	v_mul_f32_e32 v26, v26, v180
	v_mul_f32_e32 v27, v27, v181
	v_cvt_pk_bf16_f32 v188, v28, v29
	v_cvt_pk_bf16_f32 v189, v30, v31
	v_cvt_pk_bf16_f32 v190, v24, v25
	v_cvt_pk_bf16_f32 v191, v26, v27
	global_store_dwordx4 v178, v[188:191], s[48:49] offset:256
	s_waitcnt vmcnt(12)
	v_lshlrev_b32_e32 v160, 16, v216
	v_and_b32_e32 v161, 0xffff0000, v216
	v_lshlrev_b32_e32 v162, 16, v217
	v_and_b32_e32 v163, 0xffff0000, v217
	v_lshlrev_b32_e32 v164, 16, v218
	v_and_b32_e32 v165, 0xffff0000, v218
	v_lshlrev_b32_e32 v180, 16, v219
	v_and_b32_e32 v181, 0xffff0000, v219
	v_max_f32_e32 v160, v160, v147
	v_max_f32_e32 v161, v161, v147
	v_max_f32_e32 v162, v162, v147
	v_max_f32_e32 v163, v163, v147
	v_max_f32_e32 v164, v164, v147
	v_max_f32_e32 v165, v165, v147
	v_max_f32_e32 v180, v180, v147
	v_max_f32_e32 v181, v181, v147
	v_mul_f32_e32 v20, v20, v160
	v_mul_f32_e32 v21, v21, v161
	v_mul_f32_e32 v22, v22, v162
	v_mul_f32_e32 v23, v23, v163
	v_mul_f32_e32 v16, v16, v164
	v_mul_f32_e32 v17, v17, v165
	v_mul_f32_e32 v18, v18, v180
	v_mul_f32_e32 v19, v19, v181
	v_cvt_pk_bf16_f32 v184, v20, v21
	v_cvt_pk_bf16_f32 v185, v22, v23
	v_cvt_pk_bf16_f32 v186, v16, v17
	v_cvt_pk_bf16_f32 v187, v18, v19
	global_store_dwordx4 v179, v[184:187], s[48:49]
	s_waitcnt vmcnt(11)
	v_lshlrev_b32_e32 v160, 16, v220
	v_and_b32_e32 v161, 0xffff0000, v220
	v_lshlrev_b32_e32 v162, 16, v221
	v_and_b32_e32 v163, 0xffff0000, v221
	v_lshlrev_b32_e32 v164, 16, v222
	v_and_b32_e32 v165, 0xffff0000, v222
	v_lshlrev_b32_e32 v180, 16, v223
	v_and_b32_e32 v181, 0xffff0000, v223
	v_max_f32_e32 v160, v160, v147
	v_max_f32_e32 v161, v161, v147
	v_max_f32_e32 v162, v162, v147
	v_max_f32_e32 v163, v163, v147
	v_max_f32_e32 v164, v164, v147
	v_max_f32_e32 v165, v165, v147
	v_max_f32_e32 v180, v180, v147
	v_max_f32_e32 v181, v181, v147
	v_mul_f32_e32 v12, v12, v160
	v_mul_f32_e32 v13, v13, v161
	v_mul_f32_e32 v14, v14, v162
	v_mul_f32_e32 v15, v15, v163
	v_mul_f32_e32 v8, v8, v164
	v_mul_f32_e32 v9, v9, v165
	v_mul_f32_e32 v10, v10, v180
	v_mul_f32_e32 v11, v11, v181
	v_cvt_pk_bf16_f32 v188, v12, v13
	v_cvt_pk_bf16_f32 v189, v14, v15
	v_cvt_pk_bf16_f32 v190, v8, v9
	v_cvt_pk_bf16_f32 v191, v10, v11
	global_store_dwordx4 v179, v[188:191], s[48:49] offset:256
	s_mov_b64 s[48:49], 0x4000
	s_mov_b64 s[46:47], 0x8000
	s_mov_b64 s[18:19], -1
	s_andn2_b64 vcc, exec, s[42:43]
	s_cbranch_vccnz .LBB0_875
	s_andn2_b64 vcc, exec, s[0:1]
	s_cbranch_vccnz .LBB0_874
	s_barrier
	s_branch .LBB0_874
